# MFMA hand-off bubble filled: the first 4 MFMAs of every K-loop MFMA block issue before the block's opening s_barrier (fragments already waited), so the matrix pipe does not idle across the ping-pong b
# speedup vs baseline: 1.0036x; 1.0036x over previous
.LBB0_243:
	s_lshl_b32 s24, s12, 20
	s_and_b32 s24, s24, 0xff00000
	v_readlane_b32 s36, v248, 22
	v_readlane_b32 s37, v248, 23
	s_add_u32 s24, s36, s24
	s_addc_u32 s35, s37, 0
	s_lshr_b32 s36, s12, 13
	s_and_b32 s36, s36, 0x7ff80
	s_add_u32 s54, s24, s36
	s_addc_u32 s55, s35, 0
	s_lshl_b32 s24, s12, 12
	s_and_b32 s24, s24, 0xff00000
	v_readlane_b32 s38, v248, 24
	v_readlane_b32 s39, v248, 25
	s_add_u32 s24, s38, s24
	s_addc_u32 s35, s39, 0
	s_add_u32 s70, s24, s36
	s_addc_u32 s71, s35, 0
	s_cmp_lt_i32 s1, 1
	v_cmp_gt_i64_e64 s[72:73], s[12:13], -1
	s_cbranch_scc1 .LBB0_253
	s_and_b64 s[12:13], s[72:73], exec
	s_cselect_b32 s24, s55, s5
	s_cselect_b32 s35, s54, s4
	s_cselect_b32 s36, s71, s3
	s_cselect_b32 s37, s70, s2
	s_add_i32 s38, s1, -2
	s_add_u32 s4, s4, 0x80080
	s_addc_u32 s5, s5, 0
	s_add_u32 s39, s2, 0x100
	s_addc_u32 s40, s3, 0
	s_mov_b32 s2, 0
	v_add_u32_e32 v138, s29, v183
	ds_read_b128 v[144:147], v138
	ds_read_b128 v[148:151], v138 offset:1024
	ds_read_b128 v[152:155], v138 offset:2048
	ds_read_b128 v[156:159], v138 offset:3072
	v_add_u32_e32 v138, s34, v183
	ds_read_b128 v[160:163], v138
	ds_read_b128 v[164:167], v138 offset:1024
	ds_read_b128 v[186:189], v138 offset:2048
	ds_read_b128 v[190:193], v138 offset:3072
	s_add_i32 s41, s2, 2
	s_add_u32 s3, s4, 0xfff80080
	s_addc_u32 s12, s5, -1
	s_cmp_eq_u32 s38, s2
	s_cselect_b32 s2, s37, s39
	s_cselect_b32 s13, s24, s12
	s_cselect_b32 s12, s35, s3
	s_cselect_b32 s3, s36, s40
	s_add_i32 m0, s17, 0xc000
	ds_read_b128 v[194:197], v185
	ds_read_b128 v[198:201], v185 offset:1024
	ds_read_b128 v[202:205], v185 offset:2048
	ds_read_b128 v[208:211], v185 offset:3072
	ds_read_b128 v[212:215], v185 offset:4096
	ds_read_b128 v[216:219], v185 offset:5120
	ds_read_b128 v[220:223], v185 offset:6144
	ds_read_b128 v[224:227], v185 offset:7168
	global_load_lds_dwordx4 v140, s[4:5]
	s_add_i32 m0, s17, 0xe000
	s_nop 0
	global_load_lds_dwordx4 v142, s[4:5]
	s_waitcnt vmcnt(8)
	s_waitcnt lgkmcnt(0)
	v_mfma_i32_16x16x64_i8 v[126:129], v[144:147], v[194:197], 0
	v_mfma_i32_16x16x64_i8 v[126:129], v[148:151], v[198:201], v[126:129]
	v_mfma_i32_16x16x64_i8 v[122:125], v[152:155], v[194:197], 0
	v_mfma_i32_16x16x64_i8 v[122:125], v[156:159], v[198:201], v[122:125]
	s_barrier
	s_setprio 1
	s_waitcnt lgkmcnt(0)
	v_mfma_i32_16x16x64_i8 v[118:121], v[144:147], v[202:205], 0
	v_mfma_i32_16x16x64_i8 v[118:121], v[148:151], v[208:211], v[118:121]
	v_mfma_i32_16x16x64_i8 v[114:117], v[152:155], v[202:205], 0
	v_mfma_i32_16x16x64_i8 v[114:117], v[156:159], v[208:211], v[114:117]
	v_mfma_i32_16x16x64_i8 v[110:113], v[144:147], v[212:215], 0
	v_mfma_i32_16x16x64_i8 v[110:113], v[148:151], v[216:219], v[110:113]
	v_mfma_i32_16x16x64_i8 v[106:109], v[152:155], v[212:215], 0
	v_mfma_i32_16x16x64_i8 v[106:109], v[156:159], v[216:219], v[106:109]
	v_mfma_i32_16x16x64_i8 v[102:105], v[144:147], v[220:223], 0
	v_mfma_i32_16x16x64_i8 v[102:105], v[148:151], v[224:227], v[102:105]
	v_mfma_i32_16x16x64_i8 v[98:101], v[152:155], v[220:223], 0
	v_mfma_i32_16x16x64_i8 v[98:101], v[156:159], v[224:227], v[98:101]
	s_setprio 0
	s_setprio 1
	v_mfma_i32_16x16x64_i8 v[94:97], v[160:163], v[194:197], 0
	v_mfma_i32_16x16x64_i8 v[94:97], v[164:167], v[198:201], v[94:97]
	v_mfma_i32_16x16x64_i8 v[90:93], v[186:189], v[194:197], 0
	v_mfma_i32_16x16x64_i8 v[90:93], v[190:193], v[198:201], v[90:93]
	v_mfma_i32_16x16x64_i8 v[86:89], v[160:163], v[202:205], 0
	v_mfma_i32_16x16x64_i8 v[86:89], v[164:167], v[208:211], v[86:89]
	v_mfma_i32_16x16x64_i8 v[82:85], v[186:189], v[202:205], 0
	v_mfma_i32_16x16x64_i8 v[82:85], v[190:193], v[208:211], v[82:85]
	v_mfma_i32_16x16x64_i8 v[78:81], v[160:163], v[212:215], 0
	v_mfma_i32_16x16x64_i8 v[78:81], v[164:167], v[216:219], v[78:81]
	v_mfma_i32_16x16x64_i8 v[74:77], v[186:189], v[212:215], 0
	v_mfma_i32_16x16x64_i8 v[74:77], v[190:193], v[216:219], v[74:77]
	v_mfma_i32_16x16x64_i8 v[70:73], v[160:163], v[220:223], 0
	v_mfma_i32_16x16x64_i8 v[70:73], v[164:167], v[224:227], v[70:73]
	v_mfma_i32_16x16x64_i8 v[66:69], v[186:189], v[220:223], 0
	v_mfma_i32_16x16x64_i8 v[66:69], v[190:193], v[224:227], v[66:69]
	s_setprio 0
	s_barrier
	s_add_i32 s42, s29, s16
	s_mov_b32 m0, s42
	ds_read_b128 v[194:197], v185 offset:16384
	ds_read_b128 v[198:201], v185 offset:17408
	ds_read_b128 v[202:205], v185 offset:18432
	ds_read_b128 v[208:211], v185 offset:19456
	ds_read_b128 v[212:215], v185 offset:20480
	ds_read_b128 v[216:219], v185 offset:21504
	ds_read_b128 v[220:223], v185 offset:22528
	ds_read_b128 v[224:227], v185 offset:23552
	global_load_lds_dwordx4 v132, s[2:3]
	s_add_i32 m0, s42, 0x2000
	s_add_u32 s42, s2, 0x80000
	s_addc_u32 s43, s3, 0
	s_add_i32 s44, s34, s16
	global_load_lds_dwordx4 v136, s[2:3]
	s_mov_b32 m0, s44
	v_lshl_add_u64 v[234:235], s[12:13], 0, v[134:135]
	global_load_lds_dwordx4 v132, s[42:43]
	s_add_i32 m0, s44, 0x2000
	s_nop 0
	global_load_lds_dwordx4 v136, s[42:43]
	v_lshl_add_u64 v[232:233], s[12:13], 0, v[130:131]
	s_mov_b32 m0, s17
	s_nop 0
	global_load_lds_dwordx4 v130, s[12:13]
	s_mov_b32 m0, s18
	s_nop 0
	global_load_lds_dwordx4 v134, s[12:13]
	s_waitcnt vmcnt(8)
	s_waitcnt lgkmcnt(0)
	v_mfma_i32_16x16x64_i8 v[62:65], v[144:147], v[194:197], 0
	v_mfma_i32_16x16x64_i8 v[62:65], v[148:151], v[198:201], v[62:65]
	v_mfma_i32_16x16x64_i8 v[58:61], v[152:155], v[194:197], 0
	v_mfma_i32_16x16x64_i8 v[58:61], v[156:159], v[198:201], v[58:61]
	s_barrier
	s_setprio 1
	s_waitcnt lgkmcnt(0)
	v_mfma_i32_16x16x64_i8 v[54:57], v[144:147], v[202:205], 0
	v_mfma_i32_16x16x64_i8 v[54:57], v[148:151], v[208:211], v[54:57]
	v_mfma_i32_16x16x64_i8 v[50:53], v[152:155], v[202:205], 0
	v_mfma_i32_16x16x64_i8 v[50:53], v[156:159], v[208:211], v[50:53]
	v_mfma_i32_16x16x64_i8 v[46:49], v[144:147], v[212:215], 0
	v_mfma_i32_16x16x64_i8 v[46:49], v[148:151], v[216:219], v[46:49]
	v_mfma_i32_16x16x64_i8 v[42:45], v[152:155], v[212:215], 0
	v_mfma_i32_16x16x64_i8 v[42:45], v[156:159], v[216:219], v[42:45]
	v_mfma_i32_16x16x64_i8 v[38:41], v[144:147], v[220:223], 0
	v_mfma_i32_16x16x64_i8 v[38:41], v[148:151], v[224:227], v[38:41]
	v_mfma_i32_16x16x64_i8 v[34:37], v[152:155], v[220:223], 0
	v_mfma_i32_16x16x64_i8 v[34:37], v[156:159], v[224:227], v[34:37]
	s_setprio 0
	s_setprio 1
	v_mfma_i32_16x16x64_i8 v[30:33], v[160:163], v[194:197], 0
	v_mfma_i32_16x16x64_i8 v[30:33], v[164:167], v[198:201], v[30:33]
	v_mfma_i32_16x16x64_i8 v[26:29], v[186:189], v[194:197], 0
	v_mfma_i32_16x16x64_i8 v[26:29], v[190:193], v[198:201], v[26:29]
	v_mfma_i32_16x16x64_i8 v[22:25], v[160:163], v[202:205], 0
	v_mfma_i32_16x16x64_i8 v[22:25], v[164:167], v[208:211], v[22:25]
	v_mfma_i32_16x16x64_i8 v[18:21], v[186:189], v[202:205], 0
	v_mfma_i32_16x16x64_i8 v[18:21], v[190:193], v[208:211], v[18:21]
	v_mfma_i32_16x16x64_i8 v[14:17], v[160:163], v[212:215], 0
	v_mfma_i32_16x16x64_i8 v[14:17], v[164:167], v[216:219], v[14:17]
	v_mfma_i32_16x16x64_i8 v[10:13], v[186:189], v[212:215], 0
	v_mfma_i32_16x16x64_i8 v[10:13], v[190:193], v[216:219], v[10:13]
	v_mfma_i32_16x16x64_i8 v[6:9], v[160:163], v[220:223], 0
	v_mfma_i32_16x16x64_i8 v[6:9], v[164:167], v[224:227], v[6:9]
	v_mfma_i32_16x16x64_i8 v[2:5], v[186:189], v[220:223], 0
	v_mfma_i32_16x16x64_i8 v[2:5], v[190:193], v[224:227], v[2:5]
	s_setprio 0
	s_barrier
	s_add_i32 s42, 0, 0x18000
	v_add_u32_e32 v138, s42, v183
	s_add_i32 s43, 0, 0x1c000
	ds_read_b128 v[144:147], v138
	ds_read_b128 v[148:151], v138 offset:1024
	ds_read_b128 v[152:155], v138 offset:2048
	ds_read_b128 v[156:159], v138 offset:3072
	v_add_u32_e32 v138, s43, v183
	ds_read_b128 v[160:163], v138
	ds_read_b128 v[164:167], v138 offset:1024
	ds_read_b128 v[186:189], v138 offset:2048
	ds_read_b128 v[190:193], v138 offset:3072
	s_add_u32 s12, s12, 0x80000
	s_addc_u32 s13, s13, 0
	s_mov_b32 m0, s19
	ds_read_b128 v[194:197], v185 offset:32768
	ds_read_b128 v[198:201], v185 offset:33792
	ds_read_b128 v[202:205], v185 offset:34816
	ds_read_b128 v[208:211], v185 offset:35840
	ds_read_b128 v[212:215], v185 offset:36864
	ds_read_b128 v[216:219], v185 offset:37888
	ds_read_b128 v[220:223], v185 offset:38912
	ds_read_b128 v[224:227], v185 offset:39936
	global_load_lds_dwordx4 v130, s[12:13]
	s_mov_b32 m0, s20
	s_nop 0
	global_load_lds_dwordx4 v134, s[12:13]
	s_waitcnt vmcnt(8)
	s_waitcnt lgkmcnt(0)
	v_mfma_i32_16x16x64_i8 v[126:129], v[144:147], v[194:197], v[126:129]
	v_mfma_i32_16x16x64_i8 v[126:129], v[148:151], v[198:201], v[126:129]
	v_mfma_i32_16x16x64_i8 v[122:125], v[152:155], v[194:197], v[122:125]
	v_mfma_i32_16x16x64_i8 v[122:125], v[156:159], v[198:201], v[122:125]
	s_barrier
	s_setprio 1
	s_waitcnt lgkmcnt(0)
	v_mfma_i32_16x16x64_i8 v[118:121], v[144:147], v[202:205], v[118:121]
	v_mfma_i32_16x16x64_i8 v[118:121], v[148:151], v[208:211], v[118:121]
	v_mfma_i32_16x16x64_i8 v[114:117], v[152:155], v[202:205], v[114:117]
	v_mfma_i32_16x16x64_i8 v[114:117], v[156:159], v[208:211], v[114:117]
	v_mfma_i32_16x16x64_i8 v[110:113], v[144:147], v[212:215], v[110:113]
	v_mfma_i32_16x16x64_i8 v[110:113], v[148:151], v[216:219], v[110:113]
	v_mfma_i32_16x16x64_i8 v[106:109], v[152:155], v[212:215], v[106:109]
	v_mfma_i32_16x16x64_i8 v[106:109], v[156:159], v[216:219], v[106:109]
	v_mfma_i32_16x16x64_i8 v[102:105], v[144:147], v[220:223], v[102:105]
	v_mfma_i32_16x16x64_i8 v[102:105], v[148:151], v[224:227], v[102:105]
	v_mfma_i32_16x16x64_i8 v[98:101], v[152:155], v[220:223], v[98:101]
	v_mfma_i32_16x16x64_i8 v[98:101], v[156:159], v[224:227], v[98:101]
	s_setprio 0
	s_setprio 1
	v_mfma_i32_16x16x64_i8 v[94:97], v[160:163], v[194:197], v[94:97]
	v_mfma_i32_16x16x64_i8 v[94:97], v[164:167], v[198:201], v[94:97]
	v_mfma_i32_16x16x64_i8 v[90:93], v[186:189], v[194:197], v[90:93]
	v_mfma_i32_16x16x64_i8 v[90:93], v[190:193], v[198:201], v[90:93]
	v_mfma_i32_16x16x64_i8 v[86:89], v[160:163], v[202:205], v[86:89]
	v_mfma_i32_16x16x64_i8 v[86:89], v[164:167], v[208:211], v[86:89]
	v_mfma_i32_16x16x64_i8 v[82:85], v[186:189], v[202:205], v[82:85]
	v_mfma_i32_16x16x64_i8 v[82:85], v[190:193], v[208:211], v[82:85]
	v_mfma_i32_16x16x64_i8 v[78:81], v[160:163], v[212:215], v[78:81]
	v_mfma_i32_16x16x64_i8 v[78:81], v[164:167], v[216:219], v[78:81]
	v_mfma_i32_16x16x64_i8 v[74:77], v[186:189], v[212:215], v[74:77]
	v_mfma_i32_16x16x64_i8 v[74:77], v[190:193], v[216:219], v[74:77]
	v_mfma_i32_16x16x64_i8 v[70:73], v[160:163], v[220:223], v[70:73]
	v_mfma_i32_16x16x64_i8 v[70:73], v[164:167], v[224:227], v[70:73]
	v_mfma_i32_16x16x64_i8 v[66:69], v[186:189], v[220:223], v[66:69]
	v_mfma_i32_16x16x64_i8 v[66:69], v[190:193], v[224:227], v[66:69]
	s_setprio 0
	s_barrier
	s_add_i32 s12, s42, s16
	s_add_u32 s98, s2, s10
	s_addc_u32 s99, s3, s11
	s_mov_b32 m0, s12
	ds_read_b128 v[194:197], v185 offset:49152
	ds_read_b128 v[198:201], v185 offset:50176
	ds_read_b128 v[202:205], v185 offset:51200
	ds_read_b128 v[208:211], v185 offset:52224
	ds_read_b128 v[212:215], v185 offset:53248
	ds_read_b128 v[216:219], v185 offset:54272
	ds_read_b128 v[220:223], v185 offset:55296
	ds_read_b128 v[224:227], v185 offset:56320
	global_load_lds_dwordx4 v132, s[98:99]
	s_add_i32 m0, s12, 0x2000
	s_add_u32 s2, s2, 0x80080
	s_addc_u32 s3, s3, 0
	s_add_i32 s12, s43, s16
	global_load_lds_dwordx4 v136, s[98:99]
	s_mov_b32 m0, s12
	s_nop 0
	global_load_lds_dwordx4 v132, s[2:3]
	s_add_i32 m0, s12, 0x2000
	s_nop 0
	global_load_lds_dwordx4 v136, s[2:3]
	v_lshl_add_u64 v[228:229], v[232:233], 0, s[10:11]
	s_mov_b32 m0, s22
	s_nop 0
	global_load_lds_dwordx4 v[228:229], off
	v_lshl_add_u64 v[228:229], v[234:235], 0, s[10:11]
	s_mov_b32 m0, s23
	s_nop 0
	global_load_lds_dwordx4 v[228:229], off
	s_waitcnt vmcnt(8)
	s_waitcnt lgkmcnt(0)
	v_mfma_i32_16x16x64_i8 v[62:65], v[144:147], v[194:197], v[62:65]
	v_mfma_i32_16x16x64_i8 v[62:65], v[148:151], v[198:201], v[62:65]
	v_mfma_i32_16x16x64_i8 v[58:61], v[152:155], v[194:197], v[58:61]
	v_mfma_i32_16x16x64_i8 v[58:61], v[156:159], v[198:201], v[58:61]
	s_barrier
	s_setprio 1
	s_waitcnt lgkmcnt(0)
	v_mfma_i32_16x16x64_i8 v[54:57], v[144:147], v[202:205], v[54:57]
	v_mfma_i32_16x16x64_i8 v[54:57], v[148:151], v[208:211], v[54:57]
	v_mfma_i32_16x16x64_i8 v[50:53], v[152:155], v[202:205], v[50:53]
	v_mfma_i32_16x16x64_i8 v[50:53], v[156:159], v[208:211], v[50:53]
	v_mfma_i32_16x16x64_i8 v[46:49], v[144:147], v[212:215], v[46:49]
	v_mfma_i32_16x16x64_i8 v[46:49], v[148:151], v[216:219], v[46:49]
	v_mfma_i32_16x16x64_i8 v[42:45], v[152:155], v[212:215], v[42:45]
	v_mfma_i32_16x16x64_i8 v[42:45], v[156:159], v[216:219], v[42:45]
	v_mfma_i32_16x16x64_i8 v[38:41], v[144:147], v[220:223], v[38:41]
	v_mfma_i32_16x16x64_i8 v[38:41], v[148:151], v[224:227], v[38:41]
	v_mfma_i32_16x16x64_i8 v[34:37], v[152:155], v[220:223], v[34:37]
	v_mfma_i32_16x16x64_i8 v[34:37], v[156:159], v[224:227], v[34:37]
	s_setprio 0
	s_setprio 1
	v_mfma_i32_16x16x64_i8 v[30:33], v[160:163], v[194:197], v[30:33]
	v_mfma_i32_16x16x64_i8 v[30:33], v[164:167], v[198:201], v[30:33]
	v_mfma_i32_16x16x64_i8 v[26:29], v[186:189], v[194:197], v[26:29]
	v_mfma_i32_16x16x64_i8 v[26:29], v[190:193], v[198:201], v[26:29]
	v_mfma_i32_16x16x64_i8 v[22:25], v[160:163], v[202:205], v[22:25]
	v_mfma_i32_16x16x64_i8 v[22:25], v[164:167], v[208:211], v[22:25]
	v_mfma_i32_16x16x64_i8 v[18:21], v[186:189], v[202:205], v[18:21]
	v_mfma_i32_16x16x64_i8 v[18:21], v[190:193], v[208:211], v[18:21]
	v_mfma_i32_16x16x64_i8 v[14:17], v[160:163], v[212:215], v[14:17]
	v_mfma_i32_16x16x64_i8 v[14:17], v[164:167], v[216:219], v[14:17]
	v_mfma_i32_16x16x64_i8 v[10:13], v[186:189], v[212:215], v[10:13]
	v_mfma_i32_16x16x64_i8 v[10:13], v[190:193], v[216:219], v[10:13]
	v_mfma_i32_16x16x64_i8 v[6:9], v[160:163], v[220:223], v[6:9]
	v_mfma_i32_16x16x64_i8 v[6:9], v[164:167], v[224:227], v[6:9]
	v_mfma_i32_16x16x64_i8 v[2:5], v[186:189], v[220:223], v[2:5]
	v_mfma_i32_16x16x64_i8 v[2:5], v[190:193], v[224:227], v[2:5]
	s_setprio 0
	s_barrier
	s_add_u32 s4, s4, 0x100
	s_addc_u32 s5, s5, 0
	s_add_u32 s39, s39, 0x100
	s_addc_u32 s40, s40, 0
	s_cmp_ge_i32 s41, s1
	s_mov_b32 s2, s41
	s_cbranch_scc1 .Lkpeel_exit_0
.LBB0_245:
	v_add_u32_e32 v138, s29, v183
	ds_read_b128 v[144:147], v138
	ds_read_b128 v[148:151], v138 offset:1024
	ds_read_b128 v[152:155], v138 offset:2048
	ds_read_b128 v[156:159], v138 offset:3072
	v_add_u32_e32 v138, s34, v183
	ds_read_b128 v[160:163], v138
	ds_read_b128 v[164:167], v138 offset:1024
	ds_read_b128 v[186:189], v138 offset:2048
	ds_read_b128 v[190:193], v138 offset:3072
	s_add_i32 s41, s2, 2
	s_add_u32 s3, s4, 0xfff80080
	s_addc_u32 s12, s5, -1
	s_cmp_eq_u32 s38, s2
	s_cselect_b32 s2, s37, s39
	s_cselect_b32 s13, s24, s12
	s_cselect_b32 s12, s35, s3
	s_cselect_b32 s3, s36, s40
	s_add_i32 m0, s17, 0xc000
	ds_read_b128 v[194:197], v185
	ds_read_b128 v[198:201], v185 offset:1024
	ds_read_b128 v[202:205], v185 offset:2048
	ds_read_b128 v[208:211], v185 offset:3072
	ds_read_b128 v[212:215], v185 offset:4096
	ds_read_b128 v[216:219], v185 offset:5120
	ds_read_b128 v[220:223], v185 offset:6144
	ds_read_b128 v[224:227], v185 offset:7168
	global_load_lds_dwordx4 v140, s[4:5]
	s_add_i32 m0, s17, 0xe000
	s_nop 0
	global_load_lds_dwordx4 v142, s[4:5]
	s_waitcnt vmcnt(8)
	s_waitcnt lgkmcnt(0)
	v_mfma_i32_16x16x64_i8 v[126:129], v[144:147], v[194:197], v[126:129]
	v_mfma_i32_16x16x64_i8 v[126:129], v[148:151], v[198:201], v[126:129]
	v_mfma_i32_16x16x64_i8 v[122:125], v[152:155], v[194:197], v[122:125]
	v_mfma_i32_16x16x64_i8 v[122:125], v[156:159], v[198:201], v[122:125]
	s_barrier
	s_setprio 1
	s_waitcnt lgkmcnt(0)
	v_mfma_i32_16x16x64_i8 v[118:121], v[144:147], v[202:205], v[118:121]
	v_mfma_i32_16x16x64_i8 v[118:121], v[148:151], v[208:211], v[118:121]
	v_mfma_i32_16x16x64_i8 v[114:117], v[152:155], v[202:205], v[114:117]
	v_mfma_i32_16x16x64_i8 v[114:117], v[156:159], v[208:211], v[114:117]
	v_mfma_i32_16x16x64_i8 v[110:113], v[144:147], v[212:215], v[110:113]
	v_mfma_i32_16x16x64_i8 v[110:113], v[148:151], v[216:219], v[110:113]
	v_mfma_i32_16x16x64_i8 v[106:109], v[152:155], v[212:215], v[106:109]
	v_mfma_i32_16x16x64_i8 v[106:109], v[156:159], v[216:219], v[106:109]
	v_mfma_i32_16x16x64_i8 v[102:105], v[144:147], v[220:223], v[102:105]
	v_mfma_i32_16x16x64_i8 v[102:105], v[148:151], v[224:227], v[102:105]
	v_mfma_i32_16x16x64_i8 v[98:101], v[152:155], v[220:223], v[98:101]
	v_mfma_i32_16x16x64_i8 v[98:101], v[156:159], v[224:227], v[98:101]
	s_setprio 0
	s_setprio 1
	v_mfma_i32_16x16x64_i8 v[94:97], v[160:163], v[194:197], v[94:97]
	v_mfma_i32_16x16x64_i8 v[94:97], v[164:167], v[198:201], v[94:97]
	v_mfma_i32_16x16x64_i8 v[90:93], v[186:189], v[194:197], v[90:93]
	v_mfma_i32_16x16x64_i8 v[90:93], v[190:193], v[198:201], v[90:93]
	v_mfma_i32_16x16x64_i8 v[86:89], v[160:163], v[202:205], v[86:89]
	v_mfma_i32_16x16x64_i8 v[86:89], v[164:167], v[208:211], v[86:89]
	v_mfma_i32_16x16x64_i8 v[82:85], v[186:189], v[202:205], v[82:85]
	v_mfma_i32_16x16x64_i8 v[82:85], v[190:193], v[208:211], v[82:85]
	v_mfma_i32_16x16x64_i8 v[78:81], v[160:163], v[212:215], v[78:81]
	v_mfma_i32_16x16x64_i8 v[78:81], v[164:167], v[216:219], v[78:81]
	v_mfma_i32_16x16x64_i8 v[74:77], v[186:189], v[212:215], v[74:77]
	v_mfma_i32_16x16x64_i8 v[74:77], v[190:193], v[216:219], v[74:77]
	v_mfma_i32_16x16x64_i8 v[70:73], v[160:163], v[220:223], v[70:73]
	v_mfma_i32_16x16x64_i8 v[70:73], v[164:167], v[224:227], v[70:73]
	v_mfma_i32_16x16x64_i8 v[66:69], v[186:189], v[220:223], v[66:69]
	v_mfma_i32_16x16x64_i8 v[66:69], v[190:193], v[224:227], v[66:69]
	s_setprio 0
	s_barrier
	s_add_i32 s42, s29, s16
	s_mov_b32 m0, s42
	ds_read_b128 v[194:197], v185 offset:16384
	ds_read_b128 v[198:201], v185 offset:17408
	ds_read_b128 v[202:205], v185 offset:18432
	ds_read_b128 v[208:211], v185 offset:19456
	ds_read_b128 v[212:215], v185 offset:20480
	ds_read_b128 v[216:219], v185 offset:21504
	ds_read_b128 v[220:223], v185 offset:22528
	ds_read_b128 v[224:227], v185 offset:23552
	global_load_lds_dwordx4 v132, s[2:3]
	s_add_i32 m0, s42, 0x2000
	s_add_u32 s42, s2, 0x80000
	s_addc_u32 s43, s3, 0
	s_add_i32 s44, s34, s16
	global_load_lds_dwordx4 v136, s[2:3]
	s_mov_b32 m0, s44
	v_lshl_add_u64 v[234:235], s[12:13], 0, v[134:135]
	global_load_lds_dwordx4 v132, s[42:43]
	s_add_i32 m0, s44, 0x2000
	s_nop 0
	global_load_lds_dwordx4 v136, s[42:43]
	v_lshl_add_u64 v[232:233], s[12:13], 0, v[130:131]
	s_mov_b32 m0, s17
	s_nop 0
	global_load_lds_dwordx4 v130, s[12:13]
	s_mov_b32 m0, s18
	s_nop 0
	global_load_lds_dwordx4 v134, s[12:13]
	s_waitcnt vmcnt(8)
	s_waitcnt lgkmcnt(0)
	v_mfma_i32_16x16x64_i8 v[62:65], v[144:147], v[194:197], v[62:65]
	v_mfma_i32_16x16x64_i8 v[62:65], v[148:151], v[198:201], v[62:65]
	v_mfma_i32_16x16x64_i8 v[58:61], v[152:155], v[194:197], v[58:61]
	v_mfma_i32_16x16x64_i8 v[58:61], v[156:159], v[198:201], v[58:61]
	s_barrier
	s_setprio 1
	s_waitcnt lgkmcnt(0)
	v_mfma_i32_16x16x64_i8 v[54:57], v[144:147], v[202:205], v[54:57]
	v_mfma_i32_16x16x64_i8 v[54:57], v[148:151], v[208:211], v[54:57]
	v_mfma_i32_16x16x64_i8 v[50:53], v[152:155], v[202:205], v[50:53]
	v_mfma_i32_16x16x64_i8 v[50:53], v[156:159], v[208:211], v[50:53]
	v_mfma_i32_16x16x64_i8 v[46:49], v[144:147], v[212:215], v[46:49]
	v_mfma_i32_16x16x64_i8 v[46:49], v[148:151], v[216:219], v[46:49]
	v_mfma_i32_16x16x64_i8 v[42:45], v[152:155], v[212:215], v[42:45]
	v_mfma_i32_16x16x64_i8 v[42:45], v[156:159], v[216:219], v[42:45]
	v_mfma_i32_16x16x64_i8 v[38:41], v[144:147], v[220:223], v[38:41]
	v_mfma_i32_16x16x64_i8 v[38:41], v[148:151], v[224:227], v[38:41]
	v_mfma_i32_16x16x64_i8 v[34:37], v[152:155], v[220:223], v[34:37]
	v_mfma_i32_16x16x64_i8 v[34:37], v[156:159], v[224:227], v[34:37]
	s_setprio 0
	s_setprio 1
	v_mfma_i32_16x16x64_i8 v[30:33], v[160:163], v[194:197], v[30:33]
	v_mfma_i32_16x16x64_i8 v[30:33], v[164:167], v[198:201], v[30:33]
	v_mfma_i32_16x16x64_i8 v[26:29], v[186:189], v[194:197], v[26:29]
	v_mfma_i32_16x16x64_i8 v[26:29], v[190:193], v[198:201], v[26:29]
	v_mfma_i32_16x16x64_i8 v[22:25], v[160:163], v[202:205], v[22:25]
	v_mfma_i32_16x16x64_i8 v[22:25], v[164:167], v[208:211], v[22:25]
	v_mfma_i32_16x16x64_i8 v[18:21], v[186:189], v[202:205], v[18:21]
	v_mfma_i32_16x16x64_i8 v[18:21], v[190:193], v[208:211], v[18:21]
	v_mfma_i32_16x16x64_i8 v[14:17], v[160:163], v[212:215], v[14:17]
	v_mfma_i32_16x16x64_i8 v[14:17], v[164:167], v[216:219], v[14:17]
	v_mfma_i32_16x16x64_i8 v[10:13], v[186:189], v[212:215], v[10:13]
	v_mfma_i32_16x16x64_i8 v[10:13], v[190:193], v[216:219], v[10:13]
	v_mfma_i32_16x16x64_i8 v[6:9], v[160:163], v[220:223], v[6:9]
	v_mfma_i32_16x16x64_i8 v[6:9], v[164:167], v[224:227], v[6:9]
	v_mfma_i32_16x16x64_i8 v[2:5], v[186:189], v[220:223], v[2:5]
	v_mfma_i32_16x16x64_i8 v[2:5], v[190:193], v[224:227], v[2:5]
	s_setprio 0
	s_barrier
	s_add_i32 s42, 0, 0x18000
	v_add_u32_e32 v138, s42, v183
	s_add_i32 s43, 0, 0x1c000
	ds_read_b128 v[144:147], v138
	ds_read_b128 v[148:151], v138 offset:1024
	ds_read_b128 v[152:155], v138 offset:2048
	ds_read_b128 v[156:159], v138 offset:3072
	v_add_u32_e32 v138, s43, v183
	ds_read_b128 v[160:163], v138
	ds_read_b128 v[164:167], v138 offset:1024
	ds_read_b128 v[186:189], v138 offset:2048
	ds_read_b128 v[190:193], v138 offset:3072
	s_add_u32 s12, s12, 0x80000
	s_addc_u32 s13, s13, 0
	s_mov_b32 m0, s19
	ds_read_b128 v[194:197], v185 offset:32768
	ds_read_b128 v[198:201], v185 offset:33792
	ds_read_b128 v[202:205], v185 offset:34816
	ds_read_b128 v[208:211], v185 offset:35840
	ds_read_b128 v[212:215], v185 offset:36864
	ds_read_b128 v[216:219], v185 offset:37888
	ds_read_b128 v[220:223], v185 offset:38912
	ds_read_b128 v[224:227], v185 offset:39936
	global_load_lds_dwordx4 v130, s[12:13]
	s_mov_b32 m0, s20
	s_nop 0
	global_load_lds_dwordx4 v134, s[12:13]
	s_waitcnt vmcnt(8)
	s_waitcnt lgkmcnt(0)
	v_mfma_i32_16x16x64_i8 v[126:129], v[144:147], v[194:197], v[126:129]
	v_mfma_i32_16x16x64_i8 v[126:129], v[148:151], v[198:201], v[126:129]
	v_mfma_i32_16x16x64_i8 v[122:125], v[152:155], v[194:197], v[122:125]
	v_mfma_i32_16x16x64_i8 v[122:125], v[156:159], v[198:201], v[122:125]
	s_barrier
	s_setprio 1
	s_waitcnt lgkmcnt(0)
	v_mfma_i32_16x16x64_i8 v[118:121], v[144:147], v[202:205], v[118:121]
	v_mfma_i32_16x16x64_i8 v[118:121], v[148:151], v[208:211], v[118:121]
	v_mfma_i32_16x16x64_i8 v[114:117], v[152:155], v[202:205], v[114:117]
	v_mfma_i32_16x16x64_i8 v[114:117], v[156:159], v[208:211], v[114:117]
	v_mfma_i32_16x16x64_i8 v[110:113], v[144:147], v[212:215], v[110:113]
	v_mfma_i32_16x16x64_i8 v[110:113], v[148:151], v[216:219], v[110:113]
	v_mfma_i32_16x16x64_i8 v[106:109], v[152:155], v[212:215], v[106:109]
	v_mfma_i32_16x16x64_i8 v[106:109], v[156:159], v[216:219], v[106:109]
	v_mfma_i32_16x16x64_i8 v[102:105], v[144:147], v[220:223], v[102:105]
	v_mfma_i32_16x16x64_i8 v[102:105], v[148:151], v[224:227], v[102:105]
	v_mfma_i32_16x16x64_i8 v[98:101], v[152:155], v[220:223], v[98:101]
	v_mfma_i32_16x16x64_i8 v[98:101], v[156:159], v[224:227], v[98:101]
	s_setprio 0
	s_setprio 1
	v_mfma_i32_16x16x64_i8 v[94:97], v[160:163], v[194:197], v[94:97]
	v_mfma_i32_16x16x64_i8 v[94:97], v[164:167], v[198:201], v[94:97]
	v_mfma_i32_16x16x64_i8 v[90:93], v[186:189], v[194:197], v[90:93]
	v_mfma_i32_16x16x64_i8 v[90:93], v[190:193], v[198:201], v[90:93]
	v_mfma_i32_16x16x64_i8 v[86:89], v[160:163], v[202:205], v[86:89]
	v_mfma_i32_16x16x64_i8 v[86:89], v[164:167], v[208:211], v[86:89]
	v_mfma_i32_16x16x64_i8 v[82:85], v[186:189], v[202:205], v[82:85]
	v_mfma_i32_16x16x64_i8 v[82:85], v[190:193], v[208:211], v[82:85]
	v_mfma_i32_16x16x64_i8 v[78:81], v[160:163], v[212:215], v[78:81]
	v_mfma_i32_16x16x64_i8 v[78:81], v[164:167], v[216:219], v[78:81]
	v_mfma_i32_16x16x64_i8 v[74:77], v[186:189], v[212:215], v[74:77]
	v_mfma_i32_16x16x64_i8 v[74:77], v[190:193], v[216:219], v[74:77]
	v_mfma_i32_16x16x64_i8 v[70:73], v[160:163], v[220:223], v[70:73]
	v_mfma_i32_16x16x64_i8 v[70:73], v[164:167], v[224:227], v[70:73]
	v_mfma_i32_16x16x64_i8 v[66:69], v[186:189], v[220:223], v[66:69]
	v_mfma_i32_16x16x64_i8 v[66:69], v[190:193], v[224:227], v[66:69]
	s_setprio 0
	s_barrier
	s_add_i32 s12, s42, s16
	s_add_u32 s98, s2, s10
	s_addc_u32 s99, s3, s11
	s_mov_b32 m0, s12
	ds_read_b128 v[194:197], v185 offset:49152
	ds_read_b128 v[198:201], v185 offset:50176
	ds_read_b128 v[202:205], v185 offset:51200
	ds_read_b128 v[208:211], v185 offset:52224
	ds_read_b128 v[212:215], v185 offset:53248
	ds_read_b128 v[216:219], v185 offset:54272
	ds_read_b128 v[220:223], v185 offset:55296
	ds_read_b128 v[224:227], v185 offset:56320
	global_load_lds_dwordx4 v132, s[98:99]
	s_add_i32 m0, s12, 0x2000
	s_add_u32 s2, s2, 0x80080
	s_addc_u32 s3, s3, 0
	s_add_i32 s12, s43, s16
	global_load_lds_dwordx4 v136, s[98:99]
	s_mov_b32 m0, s12
	s_nop 0
	global_load_lds_dwordx4 v132, s[2:3]
	s_add_i32 m0, s12, 0x2000
	s_nop 0
	global_load_lds_dwordx4 v136, s[2:3]
	v_lshl_add_u64 v[228:229], v[232:233], 0, s[10:11]
	s_mov_b32 m0, s22
	s_nop 0
	global_load_lds_dwordx4 v[228:229], off
	v_lshl_add_u64 v[228:229], v[234:235], 0, s[10:11]
	s_mov_b32 m0, s23
	s_nop 0
	global_load_lds_dwordx4 v[228:229], off
	s_waitcnt vmcnt(8)
	s_waitcnt lgkmcnt(0)
	v_mfma_i32_16x16x64_i8 v[62:65], v[144:147], v[194:197], v[62:65]
	v_mfma_i32_16x16x64_i8 v[62:65], v[148:151], v[198:201], v[62:65]
	v_mfma_i32_16x16x64_i8 v[58:61], v[152:155], v[194:197], v[58:61]
	v_mfma_i32_16x16x64_i8 v[58:61], v[156:159], v[198:201], v[58:61]
	s_barrier
	s_setprio 1
	s_waitcnt lgkmcnt(0)
	v_mfma_i32_16x16x64_i8 v[54:57], v[144:147], v[202:205], v[54:57]
	v_mfma_i32_16x16x64_i8 v[54:57], v[148:151], v[208:211], v[54:57]
	v_mfma_i32_16x16x64_i8 v[50:53], v[152:155], v[202:205], v[50:53]
	v_mfma_i32_16x16x64_i8 v[50:53], v[156:159], v[208:211], v[50:53]
	v_mfma_i32_16x16x64_i8 v[46:49], v[144:147], v[212:215], v[46:49]
	v_mfma_i32_16x16x64_i8 v[46:49], v[148:151], v[216:219], v[46:49]
	v_mfma_i32_16x16x64_i8 v[42:45], v[152:155], v[212:215], v[42:45]
	v_mfma_i32_16x16x64_i8 v[42:45], v[156:159], v[216:219], v[42:45]
	v_mfma_i32_16x16x64_i8 v[38:41], v[144:147], v[220:223], v[38:41]
	v_mfma_i32_16x16x64_i8 v[38:41], v[148:151], v[224:227], v[38:41]
	v_mfma_i32_16x16x64_i8 v[34:37], v[152:155], v[220:223], v[34:37]
	v_mfma_i32_16x16x64_i8 v[34:37], v[156:159], v[224:227], v[34:37]
	s_setprio 0
	s_setprio 1
	v_mfma_i32_16x16x64_i8 v[30:33], v[160:163], v[194:197], v[30:33]
	v_mfma_i32_16x16x64_i8 v[30:33], v[164:167], v[198:201], v[30:33]
	v_mfma_i32_16x16x64_i8 v[26:29], v[186:189], v[194:197], v[26:29]
	v_mfma_i32_16x16x64_i8 v[26:29], v[190:193], v[198:201], v[26:29]
	v_mfma_i32_16x16x64_i8 v[22:25], v[160:163], v[202:205], v[22:25]
	v_mfma_i32_16x16x64_i8 v[22:25], v[164:167], v[208:211], v[22:25]
	v_mfma_i32_16x16x64_i8 v[18:21], v[186:189], v[202:205], v[18:21]
	v_mfma_i32_16x16x64_i8 v[18:21], v[190:193], v[208:211], v[18:21]
	v_mfma_i32_16x16x64_i8 v[14:17], v[160:163], v[212:215], v[14:17]
	v_mfma_i32_16x16x64_i8 v[14:17], v[164:167], v[216:219], v[14:17]
	v_mfma_i32_16x16x64_i8 v[10:13], v[186:189], v[212:215], v[10:13]
	v_mfma_i32_16x16x64_i8 v[10:13], v[190:193], v[216:219], v[10:13]
	v_mfma_i32_16x16x64_i8 v[6:9], v[160:163], v[220:223], v[6:9]
	v_mfma_i32_16x16x64_i8 v[6:9], v[164:167], v[224:227], v[6:9]
	v_mfma_i32_16x16x64_i8 v[2:5], v[186:189], v[220:223], v[2:5]
	v_mfma_i32_16x16x64_i8 v[2:5], v[190:193], v[224:227], v[2:5]
	s_setprio 0
	s_barrier
	s_add_u32 s4, s4, 0x100
	s_addc_u32 s5, s5, 0
	s_add_u32 s39, s39, 0x100
	s_addc_u32 s40, s40, 0
	s_cmp_ge_i32 s41, s1
	s_mov_b32 s2, s41
	s_cbranch_scc0 .LBB0_245

.LBB0_265:
	s_lshl_b32 s10, s8, 21
	s_and_b32 s10, s10, 0x1fe00000
	v_readlane_b32 s40, v248, 20
	v_readlane_b32 s41, v248, 21
	s_add_u32 s10, s40, s10
	s_addc_u32 s33, s41, 0
	s_lshr_b32 s39, s8, 13
	s_and_b32 s39, s39, 0x7ff80
	s_add_u32 s70, s10, s39
	s_addc_u32 s71, s33, 0
	s_lshl_b32 s10, s8, 13
	s_and_b32 s10, s10, 0x1fe00000
	v_readlane_b32 s40, v248, 18
	v_readlane_b32 s41, v248, 19
	s_add_u32 s10, s40, s10
	s_addc_u32 s33, s41, 0
	s_add_u32 s72, s10, s39
	s_addc_u32 s73, s33, 0
	s_cmp_lt_i32 s1, 1
	v_cmp_gt_i64_e64 s[74:75], s[8:9], -1
	s_cbranch_scc1 .LBB0_324
	s_and_b64 s[8:9], s[74:75], exec
	s_cselect_b32 s10, s71, s5
	s_cselect_b32 s33, s70, s4
	s_cselect_b32 s39, s73, s3
	s_cselect_b32 s40, s72, s2
	s_add_i32 s41, s1, -2
	s_add_u32 s4, s4, 0x100080
	s_addc_u32 s5, s5, 0
	s_add_u32 s42, s2, 0x100
	s_addc_u32 s43, s3, 0
	s_mov_b32 s2, 0
	ds_read_b128 v[148:151], v145
	ds_read_b128 v[152:155], v145 offset:1024
	ds_read_b128 v[156:159], v145 offset:2048
	ds_read_b128 v[160:163], v145 offset:3072
	ds_read_b128 v[164:167], v146
	ds_read_b128 v[168:171], v146 offset:1024
	ds_read_b128 v[172:175], v146 offset:2048
	ds_read_b128 v[176:179], v146 offset:3072
	s_add_i32 s44, s2, 2
	s_add_u32 s3, s4, 0xfff00080
	s_addc_u32 s8, s5, -1
	s_cmp_eq_u32 s41, s2
	s_cselect_b32 s2, s40, s42
	s_cselect_b32 s9, s10, s8
	s_cselect_b32 s8, s33, s3
	s_cselect_b32 s3, s39, s43
	s_add_i32 m0, s16, 0xc000
	ds_read_b128 v[180:183], v147
	ds_read_b128 v[184:187], v147 offset:1024
	ds_read_b128 v[188:191], v147 offset:2048
	ds_read_b128 v[192:195], v147 offset:3072
	ds_read_b128 v[196:199], v147 offset:4096
	ds_read_b128 v[200:203], v147 offset:5120
	ds_read_b128 v[208:211], v147 offset:6144
	ds_read_b128 v[212:215], v147 offset:7168
	global_load_lds_dwordx4 v138, s[4:5]
	s_add_i32 m0, s16, 0xe000
	s_nop 0
	global_load_lds_dwordx4 v140, s[4:5]
	s_waitcnt vmcnt(8)
	s_waitcnt lgkmcnt(0)
	v_mfma_f32_16x16x32_bf16 v[122:125], v[148:151], v[180:183], 0
	v_mfma_f32_16x16x32_bf16 v[122:125], v[152:155], v[184:187], v[122:125]
	v_mfma_f32_16x16x32_bf16 v[118:121], v[156:159], v[180:183], 0
	v_mfma_f32_16x16x32_bf16 v[118:121], v[160:163], v[184:187], v[118:121]
	s_barrier
	s_setprio 1
	s_waitcnt lgkmcnt(0)
	v_mfma_f32_16x16x32_bf16 v[110:113], v[148:151], v[188:191], 0
	v_mfma_f32_16x16x32_bf16 v[110:113], v[152:155], v[192:195], v[110:113]
	v_mfma_f32_16x16x32_bf16 v[102:105], v[156:159], v[188:191], 0
	v_mfma_f32_16x16x32_bf16 v[102:105], v[160:163], v[192:195], v[102:105]
	v_mfma_f32_16x16x32_bf16 v[94:97], v[148:151], v[196:199], 0
	v_mfma_f32_16x16x32_bf16 v[94:97], v[152:155], v[200:203], v[94:97]
	v_mfma_f32_16x16x32_bf16 v[86:89], v[156:159], v[196:199], 0
	v_mfma_f32_16x16x32_bf16 v[86:89], v[160:163], v[200:203], v[86:89]
	v_mfma_f32_16x16x32_bf16 v[78:81], v[148:151], v[208:211], 0
	v_mfma_f32_16x16x32_bf16 v[78:81], v[152:155], v[212:215], v[78:81]
	v_mfma_f32_16x16x32_bf16 v[70:73], v[156:159], v[208:211], 0
	v_mfma_f32_16x16x32_bf16 v[70:73], v[160:163], v[212:215], v[70:73]
	s_setprio 0
	s_setprio 1
	v_mfma_f32_16x16x32_bf16 v[126:129], v[164:167], v[180:183], 0
	v_mfma_f32_16x16x32_bf16 v[126:129], v[168:171], v[184:187], v[126:129]
	v_mfma_f32_16x16x32_bf16 v[114:117], v[172:175], v[180:183], 0
	v_mfma_f32_16x16x32_bf16 v[114:117], v[176:179], v[184:187], v[114:117]
	v_mfma_f32_16x16x32_bf16 v[106:109], v[164:167], v[188:191], 0
	v_mfma_f32_16x16x32_bf16 v[106:109], v[168:171], v[192:195], v[106:109]
	v_mfma_f32_16x16x32_bf16 v[98:101], v[172:175], v[188:191], 0
	v_mfma_f32_16x16x32_bf16 v[98:101], v[176:179], v[192:195], v[98:101]
	v_mfma_f32_16x16x32_bf16 v[90:93], v[164:167], v[196:199], 0
	v_mfma_f32_16x16x32_bf16 v[90:93], v[168:171], v[200:203], v[90:93]
	v_mfma_f32_16x16x32_bf16 v[82:85], v[172:175], v[196:199], 0
	v_mfma_f32_16x16x32_bf16 v[82:85], v[176:179], v[200:203], v[82:85]
	v_mfma_f32_16x16x32_bf16 v[74:77], v[164:167], v[208:211], 0
	v_mfma_f32_16x16x32_bf16 v[74:77], v[168:171], v[212:215], v[74:77]
	v_mfma_f32_16x16x32_bf16 v[66:69], v[172:175], v[208:211], 0
	v_mfma_f32_16x16x32_bf16 v[66:69], v[176:179], v[212:215], v[66:69]
	s_setprio 0
	s_barrier
	s_add_i32 s45, s36, s13
	s_mov_b32 m0, s45
	ds_read_b128 v[180:183], v147 offset:16384
	ds_read_b128 v[184:187], v147 offset:17408
	ds_read_b128 v[188:191], v147 offset:18432
	ds_read_b128 v[192:195], v147 offset:19456
	ds_read_b128 v[196:199], v147 offset:20480
	ds_read_b128 v[200:203], v147 offset:21504
	ds_read_b128 v[208:211], v147 offset:22528
	ds_read_b128 v[212:215], v147 offset:23552
	global_load_lds_dwordx4 v132, s[2:3]
	s_add_i32 m0, s45, 0x2000
	s_add_u32 s46, s2, 0x100000
	s_addc_u32 s47, s3, 0
	s_add_i32 s45, s37, s13
	global_load_lds_dwordx4 v136, s[2:3]
	s_mov_b32 m0, s45
	v_lshl_add_u64 v[220:221], s[8:9], 0, v[134:135]
	global_load_lds_dwordx4 v132, s[46:47]
	s_add_i32 m0, s45, 0x2000
	s_nop 0
	global_load_lds_dwordx4 v136, s[46:47]
	v_lshl_add_u64 v[218:219], s[8:9], 0, v[130:131]
	s_mov_b32 m0, s16
	s_nop 0
	global_load_lds_dwordx4 v130, s[8:9]
	s_mov_b32 m0, s17
	s_nop 0
	global_load_lds_dwordx4 v134, s[8:9]
	s_waitcnt vmcnt(8)
	s_waitcnt lgkmcnt(0)
	v_mfma_f32_16x16x32_bf16 v[62:65], v[148:151], v[180:183], 0
	v_mfma_f32_16x16x32_bf16 v[62:65], v[152:155], v[184:187], v[62:65]
	v_mfma_f32_16x16x32_bf16 v[54:57], v[156:159], v[180:183], 0
	v_mfma_f32_16x16x32_bf16 v[54:57], v[160:163], v[184:187], v[54:57]
	s_barrier
	s_setprio 1
	s_waitcnt lgkmcnt(0)
	v_mfma_f32_16x16x32_bf16 v[46:49], v[148:151], v[188:191], 0
	v_mfma_f32_16x16x32_bf16 v[46:49], v[152:155], v[192:195], v[46:49]
	v_mfma_f32_16x16x32_bf16 v[38:41], v[156:159], v[188:191], 0
	v_mfma_f32_16x16x32_bf16 v[38:41], v[160:163], v[192:195], v[38:41]
	v_mfma_f32_16x16x32_bf16 v[30:33], v[148:151], v[196:199], 0
	v_mfma_f32_16x16x32_bf16 v[30:33], v[152:155], v[200:203], v[30:33]
	v_mfma_f32_16x16x32_bf16 v[22:25], v[156:159], v[196:199], 0
	v_mfma_f32_16x16x32_bf16 v[22:25], v[160:163], v[200:203], v[22:25]
	v_mfma_f32_16x16x32_bf16 v[14:17], v[148:151], v[208:211], 0
	v_mfma_f32_16x16x32_bf16 v[14:17], v[152:155], v[212:215], v[14:17]
	v_mfma_f32_16x16x32_bf16 v[6:9], v[156:159], v[208:211], 0
	v_mfma_f32_16x16x32_bf16 v[6:9], v[160:163], v[212:215], v[6:9]
	s_setprio 0
	s_setprio 1
	v_mfma_f32_16x16x32_bf16 v[58:61], v[164:167], v[180:183], 0
	v_mfma_f32_16x16x32_bf16 v[58:61], v[168:171], v[184:187], v[58:61]
	v_mfma_f32_16x16x32_bf16 v[50:53], v[172:175], v[180:183], 0
	v_mfma_f32_16x16x32_bf16 v[50:53], v[176:179], v[184:187], v[50:53]
	v_mfma_f32_16x16x32_bf16 v[42:45], v[164:167], v[188:191], 0
	v_mfma_f32_16x16x32_bf16 v[42:45], v[168:171], v[192:195], v[42:45]
	v_mfma_f32_16x16x32_bf16 v[34:37], v[172:175], v[188:191], 0
	v_mfma_f32_16x16x32_bf16 v[34:37], v[176:179], v[192:195], v[34:37]
	v_mfma_f32_16x16x32_bf16 v[26:29], v[164:167], v[196:199], 0
	v_mfma_f32_16x16x32_bf16 v[26:29], v[168:171], v[200:203], v[26:29]
	v_mfma_f32_16x16x32_bf16 v[18:21], v[172:175], v[196:199], 0
	v_mfma_f32_16x16x32_bf16 v[18:21], v[176:179], v[200:203], v[18:21]
	v_mfma_f32_16x16x32_bf16 v[10:13], v[164:167], v[208:211], 0
	v_mfma_f32_16x16x32_bf16 v[10:13], v[168:171], v[212:215], v[10:13]
	v_mfma_f32_16x16x32_bf16 v[2:5], v[172:175], v[208:211], 0
	v_mfma_f32_16x16x32_bf16 v[2:5], v[176:179], v[212:215], v[2:5]
	s_setprio 0
	s_barrier
	s_add_i32 s45, 0, 0x18000
	s_add_i32 s46, 0, 0x1c000
	v_add_u32_e32 v160, s45, v1
	v_add_u32_e32 v176, s46, v1
	ds_read_b128 v[148:151], v160
	ds_read_b128 v[152:155], v160 offset:1024
	ds_read_b128 v[156:159], v160 offset:2048
	ds_read_b128 v[160:163], v160 offset:3072
	ds_read_b128 v[164:167], v176
	ds_read_b128 v[168:171], v176 offset:1024
	ds_read_b128 v[172:175], v176 offset:2048
	ds_read_b128 v[176:179], v176 offset:3072
	s_add_u32 s8, s8, 0x100000
	s_addc_u32 s9, s9, 0
	s_mov_b32 m0, s18
	ds_read_b128 v[180:183], v147 offset:32768
	ds_read_b128 v[184:187], v147 offset:33792
	ds_read_b128 v[188:191], v147 offset:34816
	ds_read_b128 v[192:195], v147 offset:35840
	ds_read_b128 v[196:199], v147 offset:36864
	ds_read_b128 v[200:203], v147 offset:37888
	ds_read_b128 v[208:211], v147 offset:38912
	ds_read_b128 v[212:215], v147 offset:39936
	global_load_lds_dwordx4 v130, s[8:9]
	s_mov_b32 m0, s19
	s_nop 0
	global_load_lds_dwordx4 v134, s[8:9]
	s_waitcnt vmcnt(8)
	s_waitcnt lgkmcnt(0)
	v_mfma_f32_16x16x32_bf16 v[122:125], v[148:151], v[180:183], v[122:125]
	v_mfma_f32_16x16x32_bf16 v[122:125], v[152:155], v[184:187], v[122:125]
	v_mfma_f32_16x16x32_bf16 v[118:121], v[156:159], v[180:183], v[118:121]
	v_mfma_f32_16x16x32_bf16 v[118:121], v[160:163], v[184:187], v[118:121]
	s_barrier
	s_setprio 1
	s_waitcnt lgkmcnt(0)
	v_mfma_f32_16x16x32_bf16 v[110:113], v[148:151], v[188:191], v[110:113]
	v_mfma_f32_16x16x32_bf16 v[110:113], v[152:155], v[192:195], v[110:113]
	v_mfma_f32_16x16x32_bf16 v[102:105], v[156:159], v[188:191], v[102:105]
	v_mfma_f32_16x16x32_bf16 v[102:105], v[160:163], v[192:195], v[102:105]
	v_mfma_f32_16x16x32_bf16 v[94:97], v[148:151], v[196:199], v[94:97]
	v_mfma_f32_16x16x32_bf16 v[94:97], v[152:155], v[200:203], v[94:97]
	v_mfma_f32_16x16x32_bf16 v[86:89], v[156:159], v[196:199], v[86:89]
	v_mfma_f32_16x16x32_bf16 v[86:89], v[160:163], v[200:203], v[86:89]
	v_mfma_f32_16x16x32_bf16 v[78:81], v[148:151], v[208:211], v[78:81]
	v_mfma_f32_16x16x32_bf16 v[78:81], v[152:155], v[212:215], v[78:81]
	v_mfma_f32_16x16x32_bf16 v[70:73], v[156:159], v[208:211], v[70:73]
	v_mfma_f32_16x16x32_bf16 v[70:73], v[160:163], v[212:215], v[70:73]
	s_setprio 0
	s_setprio 1
	v_mfma_f32_16x16x32_bf16 v[126:129], v[164:167], v[180:183], v[126:129]
	v_mfma_f32_16x16x32_bf16 v[126:129], v[168:171], v[184:187], v[126:129]
	v_mfma_f32_16x16x32_bf16 v[114:117], v[172:175], v[180:183], v[114:117]
	v_mfma_f32_16x16x32_bf16 v[114:117], v[176:179], v[184:187], v[114:117]
	v_mfma_f32_16x16x32_bf16 v[106:109], v[164:167], v[188:191], v[106:109]
	v_mfma_f32_16x16x32_bf16 v[106:109], v[168:171], v[192:195], v[106:109]
	v_mfma_f32_16x16x32_bf16 v[98:101], v[172:175], v[188:191], v[98:101]
	v_mfma_f32_16x16x32_bf16 v[98:101], v[176:179], v[192:195], v[98:101]
	v_mfma_f32_16x16x32_bf16 v[90:93], v[164:167], v[196:199], v[90:93]
	v_mfma_f32_16x16x32_bf16 v[90:93], v[168:171], v[200:203], v[90:93]
	v_mfma_f32_16x16x32_bf16 v[82:85], v[172:175], v[196:199], v[82:85]
	v_mfma_f32_16x16x32_bf16 v[82:85], v[176:179], v[200:203], v[82:85]
	v_mfma_f32_16x16x32_bf16 v[74:77], v[164:167], v[208:211], v[74:77]
	v_mfma_f32_16x16x32_bf16 v[74:77], v[168:171], v[212:215], v[74:77]
	v_mfma_f32_16x16x32_bf16 v[66:69], v[172:175], v[208:211], v[66:69]
	v_mfma_f32_16x16x32_bf16 v[66:69], v[176:179], v[212:215], v[66:69]
	s_setprio 0
	s_barrier
	s_add_i32 s8, s45, s13
	s_add_u32 s98, s2, s24
	s_addc_u32 s99, s3, s25
	s_mov_b32 m0, s8
	ds_read_b128 v[180:183], v147 offset:49152
	ds_read_b128 v[184:187], v147 offset:50176
	ds_read_b128 v[188:191], v147 offset:51200
	ds_read_b128 v[192:195], v147 offset:52224
	ds_read_b128 v[196:199], v147 offset:53248
	ds_read_b128 v[200:203], v147 offset:54272
	ds_read_b128 v[208:211], v147 offset:55296
	ds_read_b128 v[212:215], v147 offset:56320
	global_load_lds_dwordx4 v132, s[98:99]
	s_add_i32 m0, s8, 0x2000
	s_add_u32 s2, s2, 0x100080
	s_addc_u32 s3, s3, 0
	s_add_i32 s8, s46, s13
	global_load_lds_dwordx4 v136, s[98:99]
	s_mov_b32 m0, s8
	s_nop 0
	global_load_lds_dwordx4 v132, s[2:3]
	s_add_i32 m0, s8, 0x2000
	s_nop 0
	global_load_lds_dwordx4 v136, s[2:3]
	v_lshl_add_u64 v[204:205], v[218:219], 0, s[24:25]
	s_mov_b32 m0, s29
	s_nop 0
	global_load_lds_dwordx4 v[204:205], off
	v_lshl_add_u64 v[204:205], v[220:221], 0, s[24:25]
	s_mov_b32 m0, s34
	s_nop 0
	global_load_lds_dwordx4 v[204:205], off
	s_waitcnt vmcnt(8)
	s_waitcnt lgkmcnt(0)
	v_mfma_f32_16x16x32_bf16 v[62:65], v[148:151], v[180:183], v[62:65]
	v_mfma_f32_16x16x32_bf16 v[62:65], v[152:155], v[184:187], v[62:65]
	v_mfma_f32_16x16x32_bf16 v[54:57], v[156:159], v[180:183], v[54:57]
	v_mfma_f32_16x16x32_bf16 v[54:57], v[160:163], v[184:187], v[54:57]
	s_barrier
	s_setprio 1
	s_waitcnt lgkmcnt(0)
	v_mfma_f32_16x16x32_bf16 v[46:49], v[148:151], v[188:191], v[46:49]
	v_mfma_f32_16x16x32_bf16 v[46:49], v[152:155], v[192:195], v[46:49]
	v_mfma_f32_16x16x32_bf16 v[38:41], v[156:159], v[188:191], v[38:41]
	v_mfma_f32_16x16x32_bf16 v[38:41], v[160:163], v[192:195], v[38:41]
	v_mfma_f32_16x16x32_bf16 v[30:33], v[148:151], v[196:199], v[30:33]
	v_mfma_f32_16x16x32_bf16 v[30:33], v[152:155], v[200:203], v[30:33]
	v_mfma_f32_16x16x32_bf16 v[22:25], v[156:159], v[196:199], v[22:25]
	v_mfma_f32_16x16x32_bf16 v[22:25], v[160:163], v[200:203], v[22:25]
	v_mfma_f32_16x16x32_bf16 v[14:17], v[148:151], v[208:211], v[14:17]
	v_mfma_f32_16x16x32_bf16 v[14:17], v[152:155], v[212:215], v[14:17]
	v_mfma_f32_16x16x32_bf16 v[6:9], v[156:159], v[208:211], v[6:9]
	v_mfma_f32_16x16x32_bf16 v[6:9], v[160:163], v[212:215], v[6:9]
	s_setprio 0
	s_setprio 1
	v_mfma_f32_16x16x32_bf16 v[58:61], v[164:167], v[180:183], v[58:61]
	v_mfma_f32_16x16x32_bf16 v[58:61], v[168:171], v[184:187], v[58:61]
	v_mfma_f32_16x16x32_bf16 v[50:53], v[172:175], v[180:183], v[50:53]
	v_mfma_f32_16x16x32_bf16 v[50:53], v[176:179], v[184:187], v[50:53]
	v_mfma_f32_16x16x32_bf16 v[42:45], v[164:167], v[188:191], v[42:45]
	v_mfma_f32_16x16x32_bf16 v[42:45], v[168:171], v[192:195], v[42:45]
	v_mfma_f32_16x16x32_bf16 v[34:37], v[172:175], v[188:191], v[34:37]
	v_mfma_f32_16x16x32_bf16 v[34:37], v[176:179], v[192:195], v[34:37]
	v_mfma_f32_16x16x32_bf16 v[26:29], v[164:167], v[196:199], v[26:29]
	v_mfma_f32_16x16x32_bf16 v[26:29], v[168:171], v[200:203], v[26:29]
	v_mfma_f32_16x16x32_bf16 v[18:21], v[172:175], v[196:199], v[18:21]
	v_mfma_f32_16x16x32_bf16 v[18:21], v[176:179], v[200:203], v[18:21]
	v_mfma_f32_16x16x32_bf16 v[10:13], v[164:167], v[208:211], v[10:13]
	v_mfma_f32_16x16x32_bf16 v[10:13], v[168:171], v[212:215], v[10:13]
	v_mfma_f32_16x16x32_bf16 v[2:5], v[172:175], v[208:211], v[2:5]
	v_mfma_f32_16x16x32_bf16 v[2:5], v[176:179], v[212:215], v[2:5]
	s_setprio 0
	s_barrier
	s_add_u32 s4, s4, 0x100
	s_addc_u32 s5, s5, 0
	s_add_u32 s42, s42, 0x100
	s_addc_u32 s43, s43, 0
	s_cmp_ge_i32 s44, s1
	s_mov_b32 s2, s44
	s_cbranch_scc1 .Lkpeel_exit_1
.LBB0_267:
	ds_read_b128 v[148:151], v145
	ds_read_b128 v[152:155], v145 offset:1024
	ds_read_b128 v[156:159], v145 offset:2048
	ds_read_b128 v[160:163], v145 offset:3072
	ds_read_b128 v[164:167], v146
	ds_read_b128 v[168:171], v146 offset:1024
	ds_read_b128 v[172:175], v146 offset:2048
	ds_read_b128 v[176:179], v146 offset:3072
	s_add_i32 s44, s2, 2
	s_add_u32 s3, s4, 0xfff00080
	s_addc_u32 s8, s5, -1
	s_cmp_eq_u32 s41, s2
	s_cselect_b32 s2, s40, s42
	s_cselect_b32 s9, s10, s8
	s_cselect_b32 s8, s33, s3
	s_cselect_b32 s3, s39, s43
	s_add_i32 m0, s16, 0xc000
	ds_read_b128 v[180:183], v147
	ds_read_b128 v[184:187], v147 offset:1024
	ds_read_b128 v[188:191], v147 offset:2048
	ds_read_b128 v[192:195], v147 offset:3072
	ds_read_b128 v[196:199], v147 offset:4096
	ds_read_b128 v[200:203], v147 offset:5120
	ds_read_b128 v[208:211], v147 offset:6144
	ds_read_b128 v[212:215], v147 offset:7168
	global_load_lds_dwordx4 v138, s[4:5]
	s_add_i32 m0, s16, 0xe000
	s_nop 0
	global_load_lds_dwordx4 v140, s[4:5]
	s_waitcnt vmcnt(8)
	s_waitcnt lgkmcnt(0)
	v_mfma_f32_16x16x32_bf16 v[122:125], v[148:151], v[180:183], v[122:125]
	v_mfma_f32_16x16x32_bf16 v[122:125], v[152:155], v[184:187], v[122:125]
	v_mfma_f32_16x16x32_bf16 v[118:121], v[156:159], v[180:183], v[118:121]
	v_mfma_f32_16x16x32_bf16 v[118:121], v[160:163], v[184:187], v[118:121]
	s_barrier
	s_setprio 1
	s_waitcnt lgkmcnt(0)
	v_mfma_f32_16x16x32_bf16 v[110:113], v[148:151], v[188:191], v[110:113]
	v_mfma_f32_16x16x32_bf16 v[110:113], v[152:155], v[192:195], v[110:113]
	v_mfma_f32_16x16x32_bf16 v[102:105], v[156:159], v[188:191], v[102:105]
	v_mfma_f32_16x16x32_bf16 v[102:105], v[160:163], v[192:195], v[102:105]
	v_mfma_f32_16x16x32_bf16 v[94:97], v[148:151], v[196:199], v[94:97]
	v_mfma_f32_16x16x32_bf16 v[94:97], v[152:155], v[200:203], v[94:97]
	v_mfma_f32_16x16x32_bf16 v[86:89], v[156:159], v[196:199], v[86:89]
	v_mfma_f32_16x16x32_bf16 v[86:89], v[160:163], v[200:203], v[86:89]
	v_mfma_f32_16x16x32_bf16 v[78:81], v[148:151], v[208:211], v[78:81]
	v_mfma_f32_16x16x32_bf16 v[78:81], v[152:155], v[212:215], v[78:81]
	v_mfma_f32_16x16x32_bf16 v[70:73], v[156:159], v[208:211], v[70:73]
	v_mfma_f32_16x16x32_bf16 v[70:73], v[160:163], v[212:215], v[70:73]
	s_setprio 0
	s_setprio 1
	v_mfma_f32_16x16x32_bf16 v[126:129], v[164:167], v[180:183], v[126:129]
	v_mfma_f32_16x16x32_bf16 v[126:129], v[168:171], v[184:187], v[126:129]
	v_mfma_f32_16x16x32_bf16 v[114:117], v[172:175], v[180:183], v[114:117]
	v_mfma_f32_16x16x32_bf16 v[114:117], v[176:179], v[184:187], v[114:117]
	v_mfma_f32_16x16x32_bf16 v[106:109], v[164:167], v[188:191], v[106:109]
	v_mfma_f32_16x16x32_bf16 v[106:109], v[168:171], v[192:195], v[106:109]
	v_mfma_f32_16x16x32_bf16 v[98:101], v[172:175], v[188:191], v[98:101]
	v_mfma_f32_16x16x32_bf16 v[98:101], v[176:179], v[192:195], v[98:101]
	v_mfma_f32_16x16x32_bf16 v[90:93], v[164:167], v[196:199], v[90:93]
	v_mfma_f32_16x16x32_bf16 v[90:93], v[168:171], v[200:203], v[90:93]
	v_mfma_f32_16x16x32_bf16 v[82:85], v[172:175], v[196:199], v[82:85]
	v_mfma_f32_16x16x32_bf16 v[82:85], v[176:179], v[200:203], v[82:85]
	v_mfma_f32_16x16x32_bf16 v[74:77], v[164:167], v[208:211], v[74:77]
	v_mfma_f32_16x16x32_bf16 v[74:77], v[168:171], v[212:215], v[74:77]
	v_mfma_f32_16x16x32_bf16 v[66:69], v[172:175], v[208:211], v[66:69]
	v_mfma_f32_16x16x32_bf16 v[66:69], v[176:179], v[212:215], v[66:69]
	s_setprio 0
	s_barrier
	s_add_i32 s45, s36, s13
	s_mov_b32 m0, s45
	ds_read_b128 v[180:183], v147 offset:16384
	ds_read_b128 v[184:187], v147 offset:17408
	ds_read_b128 v[188:191], v147 offset:18432
	ds_read_b128 v[192:195], v147 offset:19456
	ds_read_b128 v[196:199], v147 offset:20480
	ds_read_b128 v[200:203], v147 offset:21504
	ds_read_b128 v[208:211], v147 offset:22528
	ds_read_b128 v[212:215], v147 offset:23552
	global_load_lds_dwordx4 v132, s[2:3]
	s_add_i32 m0, s45, 0x2000
	s_add_u32 s46, s2, 0x100000
	s_addc_u32 s47, s3, 0
	s_add_i32 s45, s37, s13
	global_load_lds_dwordx4 v136, s[2:3]
	s_mov_b32 m0, s45
	v_lshl_add_u64 v[220:221], s[8:9], 0, v[134:135]
	global_load_lds_dwordx4 v132, s[46:47]
	s_add_i32 m0, s45, 0x2000
	s_nop 0
	global_load_lds_dwordx4 v136, s[46:47]
	v_lshl_add_u64 v[218:219], s[8:9], 0, v[130:131]
	s_mov_b32 m0, s16
	s_nop 0
	global_load_lds_dwordx4 v130, s[8:9]
	s_mov_b32 m0, s17
	s_nop 0
	global_load_lds_dwordx4 v134, s[8:9]
	s_waitcnt vmcnt(8)
	s_waitcnt lgkmcnt(0)
	v_mfma_f32_16x16x32_bf16 v[62:65], v[148:151], v[180:183], v[62:65]
	v_mfma_f32_16x16x32_bf16 v[62:65], v[152:155], v[184:187], v[62:65]
	v_mfma_f32_16x16x32_bf16 v[54:57], v[156:159], v[180:183], v[54:57]
	v_mfma_f32_16x16x32_bf16 v[54:57], v[160:163], v[184:187], v[54:57]
	s_barrier
	s_setprio 1
	s_waitcnt lgkmcnt(0)
	v_mfma_f32_16x16x32_bf16 v[46:49], v[148:151], v[188:191], v[46:49]
	v_mfma_f32_16x16x32_bf16 v[46:49], v[152:155], v[192:195], v[46:49]
	v_mfma_f32_16x16x32_bf16 v[38:41], v[156:159], v[188:191], v[38:41]
	v_mfma_f32_16x16x32_bf16 v[38:41], v[160:163], v[192:195], v[38:41]
	v_mfma_f32_16x16x32_bf16 v[30:33], v[148:151], v[196:199], v[30:33]
	v_mfma_f32_16x16x32_bf16 v[30:33], v[152:155], v[200:203], v[30:33]
	v_mfma_f32_16x16x32_bf16 v[22:25], v[156:159], v[196:199], v[22:25]
	v_mfma_f32_16x16x32_bf16 v[22:25], v[160:163], v[200:203], v[22:25]
	v_mfma_f32_16x16x32_bf16 v[14:17], v[148:151], v[208:211], v[14:17]
	v_mfma_f32_16x16x32_bf16 v[14:17], v[152:155], v[212:215], v[14:17]
	v_mfma_f32_16x16x32_bf16 v[6:9], v[156:159], v[208:211], v[6:9]
	v_mfma_f32_16x16x32_bf16 v[6:9], v[160:163], v[212:215], v[6:9]
	s_setprio 0
	s_setprio 1
	v_mfma_f32_16x16x32_bf16 v[58:61], v[164:167], v[180:183], v[58:61]
	v_mfma_f32_16x16x32_bf16 v[58:61], v[168:171], v[184:187], v[58:61]
	v_mfma_f32_16x16x32_bf16 v[50:53], v[172:175], v[180:183], v[50:53]
	v_mfma_f32_16x16x32_bf16 v[50:53], v[176:179], v[184:187], v[50:53]
	v_mfma_f32_16x16x32_bf16 v[42:45], v[164:167], v[188:191], v[42:45]
	v_mfma_f32_16x16x32_bf16 v[42:45], v[168:171], v[192:195], v[42:45]
	v_mfma_f32_16x16x32_bf16 v[34:37], v[172:175], v[188:191], v[34:37]
	v_mfma_f32_16x16x32_bf16 v[34:37], v[176:179], v[192:195], v[34:37]
	v_mfma_f32_16x16x32_bf16 v[26:29], v[164:167], v[196:199], v[26:29]
	v_mfma_f32_16x16x32_bf16 v[26:29], v[168:171], v[200:203], v[26:29]
	v_mfma_f32_16x16x32_bf16 v[18:21], v[172:175], v[196:199], v[18:21]
	v_mfma_f32_16x16x32_bf16 v[18:21], v[176:179], v[200:203], v[18:21]
	v_mfma_f32_16x16x32_bf16 v[10:13], v[164:167], v[208:211], v[10:13]
	v_mfma_f32_16x16x32_bf16 v[10:13], v[168:171], v[212:215], v[10:13]
	v_mfma_f32_16x16x32_bf16 v[2:5], v[172:175], v[208:211], v[2:5]
	v_mfma_f32_16x16x32_bf16 v[2:5], v[176:179], v[212:215], v[2:5]
	s_setprio 0
	s_barrier
	s_add_i32 s45, 0, 0x18000
	s_add_i32 s46, 0, 0x1c000
	v_add_u32_e32 v160, s45, v1
	v_add_u32_e32 v176, s46, v1
	ds_read_b128 v[148:151], v160
	ds_read_b128 v[152:155], v160 offset:1024
	ds_read_b128 v[156:159], v160 offset:2048
	ds_read_b128 v[160:163], v160 offset:3072
	ds_read_b128 v[164:167], v176
	ds_read_b128 v[168:171], v176 offset:1024
	ds_read_b128 v[172:175], v176 offset:2048
	ds_read_b128 v[176:179], v176 offset:3072
	s_add_u32 s8, s8, 0x100000
	s_addc_u32 s9, s9, 0
	s_mov_b32 m0, s18
	ds_read_b128 v[180:183], v147 offset:32768
	ds_read_b128 v[184:187], v147 offset:33792
	ds_read_b128 v[188:191], v147 offset:34816
	ds_read_b128 v[192:195], v147 offset:35840
	ds_read_b128 v[196:199], v147 offset:36864
	ds_read_b128 v[200:203], v147 offset:37888
	ds_read_b128 v[208:211], v147 offset:38912
	ds_read_b128 v[212:215], v147 offset:39936
	global_load_lds_dwordx4 v130, s[8:9]
	s_mov_b32 m0, s19
	s_nop 0
	global_load_lds_dwordx4 v134, s[8:9]
	s_waitcnt vmcnt(8)
	s_waitcnt lgkmcnt(0)
	v_mfma_f32_16x16x32_bf16 v[122:125], v[148:151], v[180:183], v[122:125]
	v_mfma_f32_16x16x32_bf16 v[122:125], v[152:155], v[184:187], v[122:125]
	v_mfma_f32_16x16x32_bf16 v[118:121], v[156:159], v[180:183], v[118:121]
	v_mfma_f32_16x16x32_bf16 v[118:121], v[160:163], v[184:187], v[118:121]
	s_barrier
	s_setprio 1
	s_waitcnt lgkmcnt(0)
	v_mfma_f32_16x16x32_bf16 v[110:113], v[148:151], v[188:191], v[110:113]
	v_mfma_f32_16x16x32_bf16 v[110:113], v[152:155], v[192:195], v[110:113]
	v_mfma_f32_16x16x32_bf16 v[102:105], v[156:159], v[188:191], v[102:105]
	v_mfma_f32_16x16x32_bf16 v[102:105], v[160:163], v[192:195], v[102:105]
	v_mfma_f32_16x16x32_bf16 v[94:97], v[148:151], v[196:199], v[94:97]
	v_mfma_f32_16x16x32_bf16 v[94:97], v[152:155], v[200:203], v[94:97]
	v_mfma_f32_16x16x32_bf16 v[86:89], v[156:159], v[196:199], v[86:89]
	v_mfma_f32_16x16x32_bf16 v[86:89], v[160:163], v[200:203], v[86:89]
	v_mfma_f32_16x16x32_bf16 v[78:81], v[148:151], v[208:211], v[78:81]
	v_mfma_f32_16x16x32_bf16 v[78:81], v[152:155], v[212:215], v[78:81]
	v_mfma_f32_16x16x32_bf16 v[70:73], v[156:159], v[208:211], v[70:73]
	v_mfma_f32_16x16x32_bf16 v[70:73], v[160:163], v[212:215], v[70:73]
	s_setprio 0
	s_setprio 1
	v_mfma_f32_16x16x32_bf16 v[126:129], v[164:167], v[180:183], v[126:129]
	v_mfma_f32_16x16x32_bf16 v[126:129], v[168:171], v[184:187], v[126:129]
	v_mfma_f32_16x16x32_bf16 v[114:117], v[172:175], v[180:183], v[114:117]
	v_mfma_f32_16x16x32_bf16 v[114:117], v[176:179], v[184:187], v[114:117]
	v_mfma_f32_16x16x32_bf16 v[106:109], v[164:167], v[188:191], v[106:109]
	v_mfma_f32_16x16x32_bf16 v[106:109], v[168:171], v[192:195], v[106:109]
	v_mfma_f32_16x16x32_bf16 v[98:101], v[172:175], v[188:191], v[98:101]
	v_mfma_f32_16x16x32_bf16 v[98:101], v[176:179], v[192:195], v[98:101]
	v_mfma_f32_16x16x32_bf16 v[90:93], v[164:167], v[196:199], v[90:93]
	v_mfma_f32_16x16x32_bf16 v[90:93], v[168:171], v[200:203], v[90:93]
	v_mfma_f32_16x16x32_bf16 v[82:85], v[172:175], v[196:199], v[82:85]
	v_mfma_f32_16x16x32_bf16 v[82:85], v[176:179], v[200:203], v[82:85]
	v_mfma_f32_16x16x32_bf16 v[74:77], v[164:167], v[208:211], v[74:77]
	v_mfma_f32_16x16x32_bf16 v[74:77], v[168:171], v[212:215], v[74:77]
	v_mfma_f32_16x16x32_bf16 v[66:69], v[172:175], v[208:211], v[66:69]
	v_mfma_f32_16x16x32_bf16 v[66:69], v[176:179], v[212:215], v[66:69]
	s_setprio 0
	s_barrier
	s_add_i32 s8, s45, s13
	s_add_u32 s98, s2, s24
	s_addc_u32 s99, s3, s25
	s_mov_b32 m0, s8
	ds_read_b128 v[180:183], v147 offset:49152
	ds_read_b128 v[184:187], v147 offset:50176
	ds_read_b128 v[188:191], v147 offset:51200
	ds_read_b128 v[192:195], v147 offset:52224
	ds_read_b128 v[196:199], v147 offset:53248
	ds_read_b128 v[200:203], v147 offset:54272
	ds_read_b128 v[208:211], v147 offset:55296
	ds_read_b128 v[212:215], v147 offset:56320
	global_load_lds_dwordx4 v132, s[98:99]
	s_add_i32 m0, s8, 0x2000
	s_add_u32 s2, s2, 0x100080
	s_addc_u32 s3, s3, 0
	s_add_i32 s8, s46, s13
	global_load_lds_dwordx4 v136, s[98:99]
	s_mov_b32 m0, s8
	s_nop 0
	global_load_lds_dwordx4 v132, s[2:3]
	s_add_i32 m0, s8, 0x2000
	s_nop 0
	global_load_lds_dwordx4 v136, s[2:3]
	v_lshl_add_u64 v[204:205], v[218:219], 0, s[24:25]
	s_mov_b32 m0, s29
	s_nop 0
	global_load_lds_dwordx4 v[204:205], off
	v_lshl_add_u64 v[204:205], v[220:221], 0, s[24:25]
	s_mov_b32 m0, s34
	s_nop 0
	global_load_lds_dwordx4 v[204:205], off
	s_waitcnt vmcnt(8)
	s_waitcnt lgkmcnt(0)
	v_mfma_f32_16x16x32_bf16 v[62:65], v[148:151], v[180:183], v[62:65]
	v_mfma_f32_16x16x32_bf16 v[62:65], v[152:155], v[184:187], v[62:65]
	v_mfma_f32_16x16x32_bf16 v[54:57], v[156:159], v[180:183], v[54:57]
	v_mfma_f32_16x16x32_bf16 v[54:57], v[160:163], v[184:187], v[54:57]
	s_barrier
	s_setprio 1
	s_waitcnt lgkmcnt(0)
	v_mfma_f32_16x16x32_bf16 v[46:49], v[148:151], v[188:191], v[46:49]
	v_mfma_f32_16x16x32_bf16 v[46:49], v[152:155], v[192:195], v[46:49]
	v_mfma_f32_16x16x32_bf16 v[38:41], v[156:159], v[188:191], v[38:41]
	v_mfma_f32_16x16x32_bf16 v[38:41], v[160:163], v[192:195], v[38:41]
	v_mfma_f32_16x16x32_bf16 v[30:33], v[148:151], v[196:199], v[30:33]
	v_mfma_f32_16x16x32_bf16 v[30:33], v[152:155], v[200:203], v[30:33]
	v_mfma_f32_16x16x32_bf16 v[22:25], v[156:159], v[196:199], v[22:25]
	v_mfma_f32_16x16x32_bf16 v[22:25], v[160:163], v[200:203], v[22:25]
	v_mfma_f32_16x16x32_bf16 v[14:17], v[148:151], v[208:211], v[14:17]
	v_mfma_f32_16x16x32_bf16 v[14:17], v[152:155], v[212:215], v[14:17]
	v_mfma_f32_16x16x32_bf16 v[6:9], v[156:159], v[208:211], v[6:9]
	v_mfma_f32_16x16x32_bf16 v[6:9], v[160:163], v[212:215], v[6:9]
	s_setprio 0
	s_setprio 1
	v_mfma_f32_16x16x32_bf16 v[58:61], v[164:167], v[180:183], v[58:61]
	v_mfma_f32_16x16x32_bf16 v[58:61], v[168:171], v[184:187], v[58:61]
	v_mfma_f32_16x16x32_bf16 v[50:53], v[172:175], v[180:183], v[50:53]
	v_mfma_f32_16x16x32_bf16 v[50:53], v[176:179], v[184:187], v[50:53]
	v_mfma_f32_16x16x32_bf16 v[42:45], v[164:167], v[188:191], v[42:45]
	v_mfma_f32_16x16x32_bf16 v[42:45], v[168:171], v[192:195], v[42:45]
	v_mfma_f32_16x16x32_bf16 v[34:37], v[172:175], v[188:191], v[34:37]
	v_mfma_f32_16x16x32_bf16 v[34:37], v[176:179], v[192:195], v[34:37]
	v_mfma_f32_16x16x32_bf16 v[26:29], v[164:167], v[196:199], v[26:29]
	v_mfma_f32_16x16x32_bf16 v[26:29], v[168:171], v[200:203], v[26:29]
	v_mfma_f32_16x16x32_bf16 v[18:21], v[172:175], v[196:199], v[18:21]
	v_mfma_f32_16x16x32_bf16 v[18:21], v[176:179], v[200:203], v[18:21]
	v_mfma_f32_16x16x32_bf16 v[10:13], v[164:167], v[208:211], v[10:13]
	v_mfma_f32_16x16x32_bf16 v[10:13], v[168:171], v[212:215], v[10:13]
	v_mfma_f32_16x16x32_bf16 v[2:5], v[172:175], v[208:211], v[2:5]
	v_mfma_f32_16x16x32_bf16 v[2:5], v[176:179], v[212:215], v[2:5]
	s_setprio 0
	s_barrier
	s_add_u32 s4, s4, 0x100
	s_addc_u32 s5, s5, 0
	s_add_u32 s42, s42, 0x100
	s_addc_u32 s43, s43, 0
	s_cmp_ge_i32 s44, s1
	s_mov_b32 s2, s44
	s_cbranch_scc0 .LBB0_267

.LBB0_524:
	s_lshl_b32 s0, s26, 20
	s_and_b32 s0, s0, 0xff00000
	s_add_u32 s0, s70, s0
	s_addc_u32 s23, s71, 0
	s_lshr_b32 s22, s26, 13
	s_and_b32 s24, s22, 0x7ff80
	s_add_u32 s22, s0, s24
	s_addc_u32 s23, s23, 0
	s_lshl_b32 s0, s26, 12
	s_and_b32 s0, s0, 0xff00000
	s_add_u32 s0, s30, s0
	s_addc_u32 s25, s31, 0
	s_add_u32 s24, s0, s24
	s_addc_u32 s25, s25, 0
	s_cmp_lt_i32 s37, 1
	v_cmp_gt_i64_e64 s[26:27], s[26:27], -1
	s_cbranch_scc1 .LBB0_546
	s_and_b64 s[40:41], s[26:27], exec
	s_cselect_b32 s0, s23, s39
	s_cselect_b32 s36, s22, s38
	s_cselect_b32 s65, s25, s3
	s_cselect_b32 s66, s24, s2
	s_add_i32 s67, s37, -2
	s_add_u32 s38, s38, 0x80080
	s_addc_u32 s39, s39, 0
	s_add_u32 s68, s2, 0x100
	s_addc_u32 s69, s3, 0
	s_mov_b32 s2, 0
	ds_read_b128 v[148:151], v144
	ds_read_b128 v[152:155], v144 offset:1024
	ds_read_b128 v[156:159], v144 offset:2048
	ds_read_b128 v[160:163], v144 offset:3072
	ds_read_b128 v[164:167], v145
	ds_read_b128 v[168:171], v145 offset:1024
	ds_read_b128 v[172:175], v145 offset:2048
	ds_read_b128 v[176:179], v145 offset:3072
	s_waitcnt lgkmcnt(0)
	s_add_i32 s72, s2, 2
	s_add_u32 s3, s38, 0xfff80080
	s_addc_u32 s40, s39, -1
	s_cmp_eq_u32 s67, s2
	s_cselect_b32 s2, s66, s68
	s_cselect_b32 s41, s0, s40
	s_cselect_b32 s40, s36, s3
	s_cselect_b32 s3, s65, s69
	s_add_i32 m0, s29, 0xc000
	ds_read_b128 v[180:183], v146
	ds_read_b128 v[184:187], v146 offset:1024
	ds_read_b128 v[188:191], v146 offset:2048
	ds_read_b128 v[192:195], v146 offset:3072
	ds_read_b128 v[196:199], v146 offset:4096
	ds_read_b128 v[200:203], v146 offset:5120
	ds_read_b128 v[208:211], v146 offset:6144
	ds_read_b128 v[212:215], v146 offset:7168
	global_load_lds_dwordx4 v138, s[38:39]
	s_add_i32 m0, s29, 0xe000
	s_nop 0
	global_load_lds_dwordx4 v140, s[38:39]
	s_waitcnt vmcnt(8)
	s_waitcnt lgkmcnt(0)
	v_mfma_f32_16x16x32_bf16 v[126:129], v[148:151], v[180:183], 0
	v_mfma_f32_16x16x32_bf16 v[126:129], v[152:155], v[184:187], v[126:129]
	v_mfma_f32_16x16x32_bf16 v[122:125], v[156:159], v[180:183], 0
	v_mfma_f32_16x16x32_bf16 v[122:125], v[160:163], v[184:187], v[122:125]
	s_barrier
	s_setprio 1
	s_waitcnt lgkmcnt(0)
	v_mfma_f32_16x16x32_bf16 v[110:113], v[148:151], v[188:191], 0
	v_mfma_f32_16x16x32_bf16 v[110:113], v[152:155], v[192:195], v[110:113]
	v_mfma_f32_16x16x32_bf16 v[102:105], v[156:159], v[188:191], 0
	v_mfma_f32_16x16x32_bf16 v[102:105], v[160:163], v[192:195], v[102:105]
	v_mfma_f32_16x16x32_bf16 v[94:97], v[148:151], v[196:199], 0
	v_mfma_f32_16x16x32_bf16 v[94:97], v[152:155], v[200:203], v[94:97]
	v_mfma_f32_16x16x32_bf16 v[86:89], v[156:159], v[196:199], 0
	v_mfma_f32_16x16x32_bf16 v[86:89], v[160:163], v[200:203], v[86:89]
	v_mfma_f32_16x16x32_bf16 v[78:81], v[148:151], v[208:211], 0
	v_mfma_f32_16x16x32_bf16 v[78:81], v[152:155], v[212:215], v[78:81]
	v_mfma_f32_16x16x32_bf16 v[70:73], v[156:159], v[208:211], 0
	v_mfma_f32_16x16x32_bf16 v[70:73], v[160:163], v[212:215], v[70:73]
	s_setprio 0
	s_setprio 1
	v_mfma_f32_16x16x32_bf16 v[118:121], v[164:167], v[180:183], 0
	v_mfma_f32_16x16x32_bf16 v[118:121], v[168:171], v[184:187], v[118:121]
	v_mfma_f32_16x16x32_bf16 v[114:117], v[172:175], v[180:183], 0
	v_mfma_f32_16x16x32_bf16 v[114:117], v[176:179], v[184:187], v[114:117]
	v_mfma_f32_16x16x32_bf16 v[106:109], v[164:167], v[188:191], 0
	v_mfma_f32_16x16x32_bf16 v[106:109], v[168:171], v[192:195], v[106:109]
	v_mfma_f32_16x16x32_bf16 v[98:101], v[172:175], v[188:191], 0
	v_mfma_f32_16x16x32_bf16 v[98:101], v[176:179], v[192:195], v[98:101]
	v_mfma_f32_16x16x32_bf16 v[90:93], v[164:167], v[196:199], 0
	v_mfma_f32_16x16x32_bf16 v[90:93], v[168:171], v[200:203], v[90:93]
	v_mfma_f32_16x16x32_bf16 v[82:85], v[172:175], v[196:199], 0
	v_mfma_f32_16x16x32_bf16 v[82:85], v[176:179], v[200:203], v[82:85]
	v_mfma_f32_16x16x32_bf16 v[74:77], v[164:167], v[208:211], 0
	v_mfma_f32_16x16x32_bf16 v[74:77], v[168:171], v[212:215], v[74:77]
	v_mfma_f32_16x16x32_bf16 v[66:69], v[172:175], v[208:211], 0
	v_mfma_f32_16x16x32_bf16 v[66:69], v[176:179], v[212:215], v[66:69]
	s_setprio 0
	s_barrier
	s_add_i32 s73, s52, s33
	s_mov_b32 m0, s73
	ds_read_b128 v[180:183], v146 offset:16384
	ds_read_b128 v[184:187], v146 offset:17408
	ds_read_b128 v[188:191], v146 offset:18432
	ds_read_b128 v[192:195], v146 offset:19456
	ds_read_b128 v[196:199], v146 offset:20480
	ds_read_b128 v[200:203], v146 offset:21504
	ds_read_b128 v[208:211], v146 offset:22528
	ds_read_b128 v[212:215], v146 offset:23552
	global_load_lds_dwordx4 v132, s[2:3]
	s_add_i32 m0, s73, 0x2000
	s_add_u32 s74, s2, 0x80000
	s_addc_u32 s75, s3, 0
	s_add_i32 s73, s53, s33
	global_load_lds_dwordx4 v136, s[2:3]
	s_mov_b32 m0, s73
	v_lshl_add_u64 v[220:221], s[40:41], 0, v[134:135]
	global_load_lds_dwordx4 v132, s[74:75]
	s_add_i32 m0, s73, 0x2000
	s_nop 0
	global_load_lds_dwordx4 v136, s[74:75]
	v_lshl_add_u64 v[218:219], s[40:41], 0, v[130:131]
	s_mov_b32 m0, s29
	s_nop 0
	global_load_lds_dwordx4 v130, s[40:41]
	s_mov_b32 m0, s35
	s_nop 0
	global_load_lds_dwordx4 v134, s[40:41]
	s_waitcnt vmcnt(8)
	s_waitcnt lgkmcnt(0)
	v_mfma_f32_16x16x32_bf16 v[62:65], v[148:151], v[180:183], 0
	v_mfma_f32_16x16x32_bf16 v[62:65], v[152:155], v[184:187], v[62:65]
	v_mfma_f32_16x16x32_bf16 v[54:57], v[156:159], v[180:183], 0
	v_mfma_f32_16x16x32_bf16 v[54:57], v[160:163], v[184:187], v[54:57]
	s_barrier
	s_setprio 1
	s_waitcnt lgkmcnt(0)
	v_mfma_f32_16x16x32_bf16 v[46:49], v[148:151], v[188:191], 0
	v_mfma_f32_16x16x32_bf16 v[46:49], v[152:155], v[192:195], v[46:49]
	v_mfma_f32_16x16x32_bf16 v[38:41], v[156:159], v[188:191], 0
	v_mfma_f32_16x16x32_bf16 v[38:41], v[160:163], v[192:195], v[38:41]
	v_mfma_f32_16x16x32_bf16 v[30:33], v[148:151], v[196:199], 0
	v_mfma_f32_16x16x32_bf16 v[30:33], v[152:155], v[200:203], v[30:33]
	v_mfma_f32_16x16x32_bf16 v[22:25], v[156:159], v[196:199], 0
	v_mfma_f32_16x16x32_bf16 v[22:25], v[160:163], v[200:203], v[22:25]
	v_mfma_f32_16x16x32_bf16 v[14:17], v[148:151], v[208:211], 0
	v_mfma_f32_16x16x32_bf16 v[14:17], v[152:155], v[212:215], v[14:17]
	v_mfma_f32_16x16x32_bf16 v[6:9], v[156:159], v[208:211], 0
	v_mfma_f32_16x16x32_bf16 v[6:9], v[160:163], v[212:215], v[6:9]
	s_setprio 0
	s_setprio 1
	v_mfma_f32_16x16x32_bf16 v[58:61], v[164:167], v[180:183], 0
	v_mfma_f32_16x16x32_bf16 v[58:61], v[168:171], v[184:187], v[58:61]
	v_mfma_f32_16x16x32_bf16 v[50:53], v[172:175], v[180:183], 0
	v_mfma_f32_16x16x32_bf16 v[50:53], v[176:179], v[184:187], v[50:53]
	v_mfma_f32_16x16x32_bf16 v[42:45], v[164:167], v[188:191], 0
	v_mfma_f32_16x16x32_bf16 v[42:45], v[168:171], v[192:195], v[42:45]
	v_mfma_f32_16x16x32_bf16 v[34:37], v[172:175], v[188:191], 0
	v_mfma_f32_16x16x32_bf16 v[34:37], v[176:179], v[192:195], v[34:37]
	v_mfma_f32_16x16x32_bf16 v[26:29], v[164:167], v[196:199], 0
	v_mfma_f32_16x16x32_bf16 v[26:29], v[168:171], v[200:203], v[26:29]
	v_mfma_f32_16x16x32_bf16 v[18:21], v[172:175], v[196:199], 0
	v_mfma_f32_16x16x32_bf16 v[18:21], v[176:179], v[200:203], v[18:21]
	v_mfma_f32_16x16x32_bf16 v[10:13], v[164:167], v[208:211], 0
	v_mfma_f32_16x16x32_bf16 v[10:13], v[168:171], v[212:215], v[10:13]
	v_mfma_f32_16x16x32_bf16 v[2:5], v[172:175], v[208:211], 0
	v_mfma_f32_16x16x32_bf16 v[2:5], v[176:179], v[212:215], v[2:5]
	s_setprio 0
	s_barrier
	s_add_i32 s73, 0, 0x18000
	v_add_u32_e32 v147, s73, v142
	s_add_i32 s74, 0, 0x1c000
	ds_read_b128 v[148:151], v147
	ds_read_b128 v[152:155], v147 offset:1024
	ds_read_b128 v[156:159], v147 offset:2048
	ds_read_b128 v[160:163], v147 offset:3072
	v_add_u32_e32 v147, s74, v142
	ds_read_b128 v[164:167], v147
	ds_read_b128 v[168:171], v147 offset:1024
	ds_read_b128 v[172:175], v147 offset:2048
	ds_read_b128 v[176:179], v147 offset:3072
	s_add_u32 s40, s40, 0x80000
	s_addc_u32 s41, s41, 0
	s_mov_b32 m0, s43
	ds_read_b128 v[180:183], v146 offset:32768
	ds_read_b128 v[184:187], v146 offset:33792
	ds_read_b128 v[188:191], v146 offset:34816
	ds_read_b128 v[192:195], v146 offset:35840
	ds_read_b128 v[196:199], v146 offset:36864
	ds_read_b128 v[200:203], v146 offset:37888
	ds_read_b128 v[208:211], v146 offset:38912
	ds_read_b128 v[212:215], v146 offset:39936
	global_load_lds_dwordx4 v130, s[40:41]
	s_mov_b32 m0, s44
	s_nop 0
	global_load_lds_dwordx4 v134, s[40:41]
	s_waitcnt vmcnt(8)
	s_waitcnt lgkmcnt(0)
	v_mfma_f32_16x16x32_bf16 v[126:129], v[148:151], v[180:183], v[126:129]
	v_mfma_f32_16x16x32_bf16 v[126:129], v[152:155], v[184:187], v[126:129]
	v_mfma_f32_16x16x32_bf16 v[122:125], v[156:159], v[180:183], v[122:125]
	v_mfma_f32_16x16x32_bf16 v[122:125], v[160:163], v[184:187], v[122:125]
	s_barrier
	s_setprio 1
	s_waitcnt lgkmcnt(0)
	v_mfma_f32_16x16x32_bf16 v[110:113], v[148:151], v[188:191], v[110:113]
	v_mfma_f32_16x16x32_bf16 v[110:113], v[152:155], v[192:195], v[110:113]
	v_mfma_f32_16x16x32_bf16 v[102:105], v[156:159], v[188:191], v[102:105]
	v_mfma_f32_16x16x32_bf16 v[102:105], v[160:163], v[192:195], v[102:105]
	v_mfma_f32_16x16x32_bf16 v[94:97], v[148:151], v[196:199], v[94:97]
	v_mfma_f32_16x16x32_bf16 v[94:97], v[152:155], v[200:203], v[94:97]
	v_mfma_f32_16x16x32_bf16 v[86:89], v[156:159], v[196:199], v[86:89]
	v_mfma_f32_16x16x32_bf16 v[86:89], v[160:163], v[200:203], v[86:89]
	v_mfma_f32_16x16x32_bf16 v[78:81], v[148:151], v[208:211], v[78:81]
	v_mfma_f32_16x16x32_bf16 v[78:81], v[152:155], v[212:215], v[78:81]
	v_mfma_f32_16x16x32_bf16 v[70:73], v[156:159], v[208:211], v[70:73]
	v_mfma_f32_16x16x32_bf16 v[70:73], v[160:163], v[212:215], v[70:73]
	s_setprio 0
	s_setprio 1
	v_mfma_f32_16x16x32_bf16 v[118:121], v[164:167], v[180:183], v[118:121]
	v_mfma_f32_16x16x32_bf16 v[118:121], v[168:171], v[184:187], v[118:121]
	v_mfma_f32_16x16x32_bf16 v[114:117], v[172:175], v[180:183], v[114:117]
	v_mfma_f32_16x16x32_bf16 v[114:117], v[176:179], v[184:187], v[114:117]
	v_mfma_f32_16x16x32_bf16 v[106:109], v[164:167], v[188:191], v[106:109]
	v_mfma_f32_16x16x32_bf16 v[106:109], v[168:171], v[192:195], v[106:109]
	v_mfma_f32_16x16x32_bf16 v[98:101], v[172:175], v[188:191], v[98:101]
	v_mfma_f32_16x16x32_bf16 v[98:101], v[176:179], v[192:195], v[98:101]
	v_mfma_f32_16x16x32_bf16 v[90:93], v[164:167], v[196:199], v[90:93]
	v_mfma_f32_16x16x32_bf16 v[90:93], v[168:171], v[200:203], v[90:93]
	v_mfma_f32_16x16x32_bf16 v[82:85], v[172:175], v[196:199], v[82:85]
	v_mfma_f32_16x16x32_bf16 v[82:85], v[176:179], v[200:203], v[82:85]
	v_mfma_f32_16x16x32_bf16 v[74:77], v[164:167], v[208:211], v[74:77]
	v_mfma_f32_16x16x32_bf16 v[74:77], v[168:171], v[212:215], v[74:77]
	v_mfma_f32_16x16x32_bf16 v[66:69], v[172:175], v[208:211], v[66:69]
	v_mfma_f32_16x16x32_bf16 v[66:69], v[176:179], v[212:215], v[66:69]
	s_setprio 0
	s_barrier
	s_add_i32 s40, s73, s33
	s_add_u32 s98, s2, s16
	s_addc_u32 s99, s3, s17
	s_mov_b32 m0, s40
	ds_read_b128 v[180:183], v146 offset:49152
	ds_read_b128 v[184:187], v146 offset:50176
	ds_read_b128 v[188:191], v146 offset:51200
	ds_read_b128 v[192:195], v146 offset:52224
	ds_read_b128 v[196:199], v146 offset:53248
	ds_read_b128 v[200:203], v146 offset:54272
	ds_read_b128 v[208:211], v146 offset:55296
	ds_read_b128 v[212:215], v146 offset:56320
	global_load_lds_dwordx4 v132, s[98:99]
	s_add_i32 m0, s40, 0x2000
	s_add_u32 s2, s2, 0x80080
	s_addc_u32 s3, s3, 0
	s_add_i32 s40, s74, s33
	global_load_lds_dwordx4 v136, s[98:99]
	s_mov_b32 m0, s40
	s_nop 0
	global_load_lds_dwordx4 v132, s[2:3]
	s_add_i32 m0, s40, 0x2000
	s_nop 0
	global_load_lds_dwordx4 v136, s[2:3]
	v_lshl_add_u64 v[204:205], v[218:219], 0, s[16:17]
	s_mov_b32 m0, s46
	s_nop 0
	global_load_lds_dwordx4 v[204:205], off
	v_lshl_add_u64 v[204:205], v[220:221], 0, s[16:17]
	s_mov_b32 m0, s47
	s_nop 0
	global_load_lds_dwordx4 v[204:205], off
	s_waitcnt vmcnt(8)
	s_waitcnt lgkmcnt(0)
	v_mfma_f32_16x16x32_bf16 v[62:65], v[148:151], v[180:183], v[62:65]
	v_mfma_f32_16x16x32_bf16 v[62:65], v[152:155], v[184:187], v[62:65]
	v_mfma_f32_16x16x32_bf16 v[54:57], v[156:159], v[180:183], v[54:57]
	v_mfma_f32_16x16x32_bf16 v[54:57], v[160:163], v[184:187], v[54:57]
	s_barrier
	s_setprio 1
	s_waitcnt lgkmcnt(0)
	v_mfma_f32_16x16x32_bf16 v[46:49], v[148:151], v[188:191], v[46:49]
	v_mfma_f32_16x16x32_bf16 v[46:49], v[152:155], v[192:195], v[46:49]
	v_mfma_f32_16x16x32_bf16 v[38:41], v[156:159], v[188:191], v[38:41]
	v_mfma_f32_16x16x32_bf16 v[38:41], v[160:163], v[192:195], v[38:41]
	v_mfma_f32_16x16x32_bf16 v[30:33], v[148:151], v[196:199], v[30:33]
	v_mfma_f32_16x16x32_bf16 v[30:33], v[152:155], v[200:203], v[30:33]
	v_mfma_f32_16x16x32_bf16 v[22:25], v[156:159], v[196:199], v[22:25]
	v_mfma_f32_16x16x32_bf16 v[22:25], v[160:163], v[200:203], v[22:25]
	v_mfma_f32_16x16x32_bf16 v[14:17], v[148:151], v[208:211], v[14:17]
	v_mfma_f32_16x16x32_bf16 v[14:17], v[152:155], v[212:215], v[14:17]
	v_mfma_f32_16x16x32_bf16 v[6:9], v[156:159], v[208:211], v[6:9]
	v_mfma_f32_16x16x32_bf16 v[6:9], v[160:163], v[212:215], v[6:9]
	s_setprio 0
	s_setprio 1
	v_mfma_f32_16x16x32_bf16 v[58:61], v[164:167], v[180:183], v[58:61]
	v_mfma_f32_16x16x32_bf16 v[58:61], v[168:171], v[184:187], v[58:61]
	v_mfma_f32_16x16x32_bf16 v[50:53], v[172:175], v[180:183], v[50:53]
	v_mfma_f32_16x16x32_bf16 v[50:53], v[176:179], v[184:187], v[50:53]
	v_mfma_f32_16x16x32_bf16 v[42:45], v[164:167], v[188:191], v[42:45]
	v_mfma_f32_16x16x32_bf16 v[42:45], v[168:171], v[192:195], v[42:45]
	v_mfma_f32_16x16x32_bf16 v[34:37], v[172:175], v[188:191], v[34:37]
	v_mfma_f32_16x16x32_bf16 v[34:37], v[176:179], v[192:195], v[34:37]
	v_mfma_f32_16x16x32_bf16 v[26:29], v[164:167], v[196:199], v[26:29]
	v_mfma_f32_16x16x32_bf16 v[26:29], v[168:171], v[200:203], v[26:29]
	v_mfma_f32_16x16x32_bf16 v[18:21], v[172:175], v[196:199], v[18:21]
	v_mfma_f32_16x16x32_bf16 v[18:21], v[176:179], v[200:203], v[18:21]
	v_mfma_f32_16x16x32_bf16 v[10:13], v[164:167], v[208:211], v[10:13]
	v_mfma_f32_16x16x32_bf16 v[10:13], v[168:171], v[212:215], v[10:13]
	v_mfma_f32_16x16x32_bf16 v[2:5], v[172:175], v[208:211], v[2:5]
	v_mfma_f32_16x16x32_bf16 v[2:5], v[176:179], v[212:215], v[2:5]
	s_setprio 0
	s_barrier
	s_add_u32 s38, s38, 0x100
	s_addc_u32 s39, s39, 0
	s_add_u32 s68, s68, 0x100
	s_addc_u32 s69, s69, 0
	s_cmp_ge_i32 s72, s37
	s_mov_b32 s2, s72
	s_cbranch_scc1 .Lkpeel_exit_2
.LBB0_526:
	ds_read_b128 v[148:151], v144
	ds_read_b128 v[152:155], v144 offset:1024
	ds_read_b128 v[156:159], v144 offset:2048
	ds_read_b128 v[160:163], v144 offset:3072
	ds_read_b128 v[164:167], v145
	ds_read_b128 v[168:171], v145 offset:1024
	ds_read_b128 v[172:175], v145 offset:2048
	ds_read_b128 v[176:179], v145 offset:3072
	s_waitcnt lgkmcnt(0)
	s_add_i32 s72, s2, 2
	s_add_u32 s3, s38, 0xfff80080
	s_addc_u32 s40, s39, -1
	s_cmp_eq_u32 s67, s2
	s_cselect_b32 s2, s66, s68
	s_cselect_b32 s41, s0, s40
	s_cselect_b32 s40, s36, s3
	s_cselect_b32 s3, s65, s69
	s_add_i32 m0, s29, 0xc000
	ds_read_b128 v[180:183], v146
	ds_read_b128 v[184:187], v146 offset:1024
	ds_read_b128 v[188:191], v146 offset:2048
	ds_read_b128 v[192:195], v146 offset:3072
	ds_read_b128 v[196:199], v146 offset:4096
	ds_read_b128 v[200:203], v146 offset:5120
	ds_read_b128 v[208:211], v146 offset:6144
	ds_read_b128 v[212:215], v146 offset:7168
	global_load_lds_dwordx4 v138, s[38:39]
	s_add_i32 m0, s29, 0xe000
	s_nop 0
	global_load_lds_dwordx4 v140, s[38:39]
	s_waitcnt vmcnt(8)
	s_waitcnt lgkmcnt(0)
	v_mfma_f32_16x16x32_bf16 v[126:129], v[148:151], v[180:183], v[126:129]
	v_mfma_f32_16x16x32_bf16 v[126:129], v[152:155], v[184:187], v[126:129]
	v_mfma_f32_16x16x32_bf16 v[122:125], v[156:159], v[180:183], v[122:125]
	v_mfma_f32_16x16x32_bf16 v[122:125], v[160:163], v[184:187], v[122:125]
	s_barrier
	s_setprio 1
	s_waitcnt lgkmcnt(0)
	v_mfma_f32_16x16x32_bf16 v[110:113], v[148:151], v[188:191], v[110:113]
	v_mfma_f32_16x16x32_bf16 v[110:113], v[152:155], v[192:195], v[110:113]
	v_mfma_f32_16x16x32_bf16 v[102:105], v[156:159], v[188:191], v[102:105]
	v_mfma_f32_16x16x32_bf16 v[102:105], v[160:163], v[192:195], v[102:105]
	v_mfma_f32_16x16x32_bf16 v[94:97], v[148:151], v[196:199], v[94:97]
	v_mfma_f32_16x16x32_bf16 v[94:97], v[152:155], v[200:203], v[94:97]
	v_mfma_f32_16x16x32_bf16 v[86:89], v[156:159], v[196:199], v[86:89]
	v_mfma_f32_16x16x32_bf16 v[86:89], v[160:163], v[200:203], v[86:89]
	v_mfma_f32_16x16x32_bf16 v[78:81], v[148:151], v[208:211], v[78:81]
	v_mfma_f32_16x16x32_bf16 v[78:81], v[152:155], v[212:215], v[78:81]
	v_mfma_f32_16x16x32_bf16 v[70:73], v[156:159], v[208:211], v[70:73]
	v_mfma_f32_16x16x32_bf16 v[70:73], v[160:163], v[212:215], v[70:73]
	s_setprio 0
	s_setprio 1
	v_mfma_f32_16x16x32_bf16 v[118:121], v[164:167], v[180:183], v[118:121]
	v_mfma_f32_16x16x32_bf16 v[118:121], v[168:171], v[184:187], v[118:121]
	v_mfma_f32_16x16x32_bf16 v[114:117], v[172:175], v[180:183], v[114:117]
	v_mfma_f32_16x16x32_bf16 v[114:117], v[176:179], v[184:187], v[114:117]
	v_mfma_f32_16x16x32_bf16 v[106:109], v[164:167], v[188:191], v[106:109]
	v_mfma_f32_16x16x32_bf16 v[106:109], v[168:171], v[192:195], v[106:109]
	v_mfma_f32_16x16x32_bf16 v[98:101], v[172:175], v[188:191], v[98:101]
	v_mfma_f32_16x16x32_bf16 v[98:101], v[176:179], v[192:195], v[98:101]
	v_mfma_f32_16x16x32_bf16 v[90:93], v[164:167], v[196:199], v[90:93]
	v_mfma_f32_16x16x32_bf16 v[90:93], v[168:171], v[200:203], v[90:93]
	v_mfma_f32_16x16x32_bf16 v[82:85], v[172:175], v[196:199], v[82:85]
	v_mfma_f32_16x16x32_bf16 v[82:85], v[176:179], v[200:203], v[82:85]
	v_mfma_f32_16x16x32_bf16 v[74:77], v[164:167], v[208:211], v[74:77]
	v_mfma_f32_16x16x32_bf16 v[74:77], v[168:171], v[212:215], v[74:77]
	v_mfma_f32_16x16x32_bf16 v[66:69], v[172:175], v[208:211], v[66:69]
	v_mfma_f32_16x16x32_bf16 v[66:69], v[176:179], v[212:215], v[66:69]
	s_setprio 0
	s_barrier
	s_add_i32 s73, s52, s33
	s_mov_b32 m0, s73
	ds_read_b128 v[180:183], v146 offset:16384
	ds_read_b128 v[184:187], v146 offset:17408
	ds_read_b128 v[188:191], v146 offset:18432
	ds_read_b128 v[192:195], v146 offset:19456
	ds_read_b128 v[196:199], v146 offset:20480
	ds_read_b128 v[200:203], v146 offset:21504
	ds_read_b128 v[208:211], v146 offset:22528
	ds_read_b128 v[212:215], v146 offset:23552
	global_load_lds_dwordx4 v132, s[2:3]
	s_add_i32 m0, s73, 0x2000
	s_add_u32 s74, s2, 0x80000
	s_addc_u32 s75, s3, 0
	s_add_i32 s73, s53, s33
	global_load_lds_dwordx4 v136, s[2:3]
	s_mov_b32 m0, s73
	v_lshl_add_u64 v[220:221], s[40:41], 0, v[134:135]
	global_load_lds_dwordx4 v132, s[74:75]
	s_add_i32 m0, s73, 0x2000
	s_nop 0
	global_load_lds_dwordx4 v136, s[74:75]
	v_lshl_add_u64 v[218:219], s[40:41], 0, v[130:131]
	s_mov_b32 m0, s29
	s_nop 0
	global_load_lds_dwordx4 v130, s[40:41]
	s_mov_b32 m0, s35
	s_nop 0
	global_load_lds_dwordx4 v134, s[40:41]
	s_waitcnt vmcnt(8)
	s_waitcnt lgkmcnt(0)
	v_mfma_f32_16x16x32_bf16 v[62:65], v[148:151], v[180:183], v[62:65]
	v_mfma_f32_16x16x32_bf16 v[62:65], v[152:155], v[184:187], v[62:65]
	v_mfma_f32_16x16x32_bf16 v[54:57], v[156:159], v[180:183], v[54:57]
	v_mfma_f32_16x16x32_bf16 v[54:57], v[160:163], v[184:187], v[54:57]
	s_barrier
	s_setprio 1
	s_waitcnt lgkmcnt(0)
	v_mfma_f32_16x16x32_bf16 v[46:49], v[148:151], v[188:191], v[46:49]
	v_mfma_f32_16x16x32_bf16 v[46:49], v[152:155], v[192:195], v[46:49]
	v_mfma_f32_16x16x32_bf16 v[38:41], v[156:159], v[188:191], v[38:41]
	v_mfma_f32_16x16x32_bf16 v[38:41], v[160:163], v[192:195], v[38:41]
	v_mfma_f32_16x16x32_bf16 v[30:33], v[148:151], v[196:199], v[30:33]
	v_mfma_f32_16x16x32_bf16 v[30:33], v[152:155], v[200:203], v[30:33]
	v_mfma_f32_16x16x32_bf16 v[22:25], v[156:159], v[196:199], v[22:25]
	v_mfma_f32_16x16x32_bf16 v[22:25], v[160:163], v[200:203], v[22:25]
	v_mfma_f32_16x16x32_bf16 v[14:17], v[148:151], v[208:211], v[14:17]
	v_mfma_f32_16x16x32_bf16 v[14:17], v[152:155], v[212:215], v[14:17]
	v_mfma_f32_16x16x32_bf16 v[6:9], v[156:159], v[208:211], v[6:9]
	v_mfma_f32_16x16x32_bf16 v[6:9], v[160:163], v[212:215], v[6:9]
	s_setprio 0
	s_setprio 1
	v_mfma_f32_16x16x32_bf16 v[58:61], v[164:167], v[180:183], v[58:61]
	v_mfma_f32_16x16x32_bf16 v[58:61], v[168:171], v[184:187], v[58:61]
	v_mfma_f32_16x16x32_bf16 v[50:53], v[172:175], v[180:183], v[50:53]
	v_mfma_f32_16x16x32_bf16 v[50:53], v[176:179], v[184:187], v[50:53]
	v_mfma_f32_16x16x32_bf16 v[42:45], v[164:167], v[188:191], v[42:45]
	v_mfma_f32_16x16x32_bf16 v[42:45], v[168:171], v[192:195], v[42:45]
	v_mfma_f32_16x16x32_bf16 v[34:37], v[172:175], v[188:191], v[34:37]
	v_mfma_f32_16x16x32_bf16 v[34:37], v[176:179], v[192:195], v[34:37]
	v_mfma_f32_16x16x32_bf16 v[26:29], v[164:167], v[196:199], v[26:29]
	v_mfma_f32_16x16x32_bf16 v[26:29], v[168:171], v[200:203], v[26:29]
	v_mfma_f32_16x16x32_bf16 v[18:21], v[172:175], v[196:199], v[18:21]
	v_mfma_f32_16x16x32_bf16 v[18:21], v[176:179], v[200:203], v[18:21]
	v_mfma_f32_16x16x32_bf16 v[10:13], v[164:167], v[208:211], v[10:13]
	v_mfma_f32_16x16x32_bf16 v[10:13], v[168:171], v[212:215], v[10:13]
	v_mfma_f32_16x16x32_bf16 v[2:5], v[172:175], v[208:211], v[2:5]
	v_mfma_f32_16x16x32_bf16 v[2:5], v[176:179], v[212:215], v[2:5]
	s_setprio 0
	s_barrier
	s_add_i32 s73, 0, 0x18000
	v_add_u32_e32 v147, s73, v142
	s_add_i32 s74, 0, 0x1c000
	ds_read_b128 v[148:151], v147
	ds_read_b128 v[152:155], v147 offset:1024
	ds_read_b128 v[156:159], v147 offset:2048
	ds_read_b128 v[160:163], v147 offset:3072
	v_add_u32_e32 v147, s74, v142
	ds_read_b128 v[164:167], v147
	ds_read_b128 v[168:171], v147 offset:1024
	ds_read_b128 v[172:175], v147 offset:2048
	ds_read_b128 v[176:179], v147 offset:3072
	s_add_u32 s40, s40, 0x80000
	s_addc_u32 s41, s41, 0
	s_mov_b32 m0, s43
	ds_read_b128 v[180:183], v146 offset:32768
	ds_read_b128 v[184:187], v146 offset:33792
	ds_read_b128 v[188:191], v146 offset:34816
	ds_read_b128 v[192:195], v146 offset:35840
	ds_read_b128 v[196:199], v146 offset:36864
	ds_read_b128 v[200:203], v146 offset:37888
	ds_read_b128 v[208:211], v146 offset:38912
	ds_read_b128 v[212:215], v146 offset:39936
	global_load_lds_dwordx4 v130, s[40:41]
	s_mov_b32 m0, s44
	s_nop 0
	global_load_lds_dwordx4 v134, s[40:41]
	s_waitcnt vmcnt(8)
	s_waitcnt lgkmcnt(0)
	v_mfma_f32_16x16x32_bf16 v[126:129], v[148:151], v[180:183], v[126:129]
	v_mfma_f32_16x16x32_bf16 v[126:129], v[152:155], v[184:187], v[126:129]
	v_mfma_f32_16x16x32_bf16 v[122:125], v[156:159], v[180:183], v[122:125]
	v_mfma_f32_16x16x32_bf16 v[122:125], v[160:163], v[184:187], v[122:125]
	s_barrier
	s_setprio 1
	s_waitcnt lgkmcnt(0)
	v_mfma_f32_16x16x32_bf16 v[110:113], v[148:151], v[188:191], v[110:113]
	v_mfma_f32_16x16x32_bf16 v[110:113], v[152:155], v[192:195], v[110:113]
	v_mfma_f32_16x16x32_bf16 v[102:105], v[156:159], v[188:191], v[102:105]
	v_mfma_f32_16x16x32_bf16 v[102:105], v[160:163], v[192:195], v[102:105]
	v_mfma_f32_16x16x32_bf16 v[94:97], v[148:151], v[196:199], v[94:97]
	v_mfma_f32_16x16x32_bf16 v[94:97], v[152:155], v[200:203], v[94:97]
	v_mfma_f32_16x16x32_bf16 v[86:89], v[156:159], v[196:199], v[86:89]
	v_mfma_f32_16x16x32_bf16 v[86:89], v[160:163], v[200:203], v[86:89]
	v_mfma_f32_16x16x32_bf16 v[78:81], v[148:151], v[208:211], v[78:81]
	v_mfma_f32_16x16x32_bf16 v[78:81], v[152:155], v[212:215], v[78:81]
	v_mfma_f32_16x16x32_bf16 v[70:73], v[156:159], v[208:211], v[70:73]
	v_mfma_f32_16x16x32_bf16 v[70:73], v[160:163], v[212:215], v[70:73]
	s_setprio 0
	s_setprio 1
	v_mfma_f32_16x16x32_bf16 v[118:121], v[164:167], v[180:183], v[118:121]
	v_mfma_f32_16x16x32_bf16 v[118:121], v[168:171], v[184:187], v[118:121]
	v_mfma_f32_16x16x32_bf16 v[114:117], v[172:175], v[180:183], v[114:117]
	v_mfma_f32_16x16x32_bf16 v[114:117], v[176:179], v[184:187], v[114:117]
	v_mfma_f32_16x16x32_bf16 v[106:109], v[164:167], v[188:191], v[106:109]
	v_mfma_f32_16x16x32_bf16 v[106:109], v[168:171], v[192:195], v[106:109]
	v_mfma_f32_16x16x32_bf16 v[98:101], v[172:175], v[188:191], v[98:101]
	v_mfma_f32_16x16x32_bf16 v[98:101], v[176:179], v[192:195], v[98:101]
	v_mfma_f32_16x16x32_bf16 v[90:93], v[164:167], v[196:199], v[90:93]
	v_mfma_f32_16x16x32_bf16 v[90:93], v[168:171], v[200:203], v[90:93]
	v_mfma_f32_16x16x32_bf16 v[82:85], v[172:175], v[196:199], v[82:85]
	v_mfma_f32_16x16x32_bf16 v[82:85], v[176:179], v[200:203], v[82:85]
	v_mfma_f32_16x16x32_bf16 v[74:77], v[164:167], v[208:211], v[74:77]
	v_mfma_f32_16x16x32_bf16 v[74:77], v[168:171], v[212:215], v[74:77]
	v_mfma_f32_16x16x32_bf16 v[66:69], v[172:175], v[208:211], v[66:69]
	v_mfma_f32_16x16x32_bf16 v[66:69], v[176:179], v[212:215], v[66:69]
	s_setprio 0
	s_barrier
	s_add_i32 s40, s73, s33
	s_add_u32 s98, s2, s16
	s_addc_u32 s99, s3, s17
	s_mov_b32 m0, s40
	ds_read_b128 v[180:183], v146 offset:49152
	ds_read_b128 v[184:187], v146 offset:50176
	ds_read_b128 v[188:191], v146 offset:51200
	ds_read_b128 v[192:195], v146 offset:52224
	ds_read_b128 v[196:199], v146 offset:53248
	ds_read_b128 v[200:203], v146 offset:54272
	ds_read_b128 v[208:211], v146 offset:55296
	ds_read_b128 v[212:215], v146 offset:56320
	global_load_lds_dwordx4 v132, s[98:99]
	s_add_i32 m0, s40, 0x2000
	s_add_u32 s2, s2, 0x80080
	s_addc_u32 s3, s3, 0
	s_add_i32 s40, s74, s33
	global_load_lds_dwordx4 v136, s[98:99]
	s_mov_b32 m0, s40
	s_nop 0
	global_load_lds_dwordx4 v132, s[2:3]
	s_add_i32 m0, s40, 0x2000
	s_nop 0
	global_load_lds_dwordx4 v136, s[2:3]
	v_lshl_add_u64 v[204:205], v[218:219], 0, s[16:17]
	s_mov_b32 m0, s46
	s_nop 0
	global_load_lds_dwordx4 v[204:205], off
	v_lshl_add_u64 v[204:205], v[220:221], 0, s[16:17]
	s_mov_b32 m0, s47
	s_nop 0
	global_load_lds_dwordx4 v[204:205], off
	s_waitcnt vmcnt(8)
	s_waitcnt lgkmcnt(0)
	v_mfma_f32_16x16x32_bf16 v[62:65], v[148:151], v[180:183], v[62:65]
	v_mfma_f32_16x16x32_bf16 v[62:65], v[152:155], v[184:187], v[62:65]
	v_mfma_f32_16x16x32_bf16 v[54:57], v[156:159], v[180:183], v[54:57]
	v_mfma_f32_16x16x32_bf16 v[54:57], v[160:163], v[184:187], v[54:57]
	s_barrier
	s_setprio 1
	s_waitcnt lgkmcnt(0)
	v_mfma_f32_16x16x32_bf16 v[46:49], v[148:151], v[188:191], v[46:49]
	v_mfma_f32_16x16x32_bf16 v[46:49], v[152:155], v[192:195], v[46:49]
	v_mfma_f32_16x16x32_bf16 v[38:41], v[156:159], v[188:191], v[38:41]
	v_mfma_f32_16x16x32_bf16 v[38:41], v[160:163], v[192:195], v[38:41]
	v_mfma_f32_16x16x32_bf16 v[30:33], v[148:151], v[196:199], v[30:33]
	v_mfma_f32_16x16x32_bf16 v[30:33], v[152:155], v[200:203], v[30:33]
	v_mfma_f32_16x16x32_bf16 v[22:25], v[156:159], v[196:199], v[22:25]
	v_mfma_f32_16x16x32_bf16 v[22:25], v[160:163], v[200:203], v[22:25]
	v_mfma_f32_16x16x32_bf16 v[14:17], v[148:151], v[208:211], v[14:17]
	v_mfma_f32_16x16x32_bf16 v[14:17], v[152:155], v[212:215], v[14:17]
	v_mfma_f32_16x16x32_bf16 v[6:9], v[156:159], v[208:211], v[6:9]
	v_mfma_f32_16x16x32_bf16 v[6:9], v[160:163], v[212:215], v[6:9]
	s_setprio 0
	s_setprio 1
	v_mfma_f32_16x16x32_bf16 v[58:61], v[164:167], v[180:183], v[58:61]
	v_mfma_f32_16x16x32_bf16 v[58:61], v[168:171], v[184:187], v[58:61]
	v_mfma_f32_16x16x32_bf16 v[50:53], v[172:175], v[180:183], v[50:53]
	v_mfma_f32_16x16x32_bf16 v[50:53], v[176:179], v[184:187], v[50:53]
	v_mfma_f32_16x16x32_bf16 v[42:45], v[164:167], v[188:191], v[42:45]
	v_mfma_f32_16x16x32_bf16 v[42:45], v[168:171], v[192:195], v[42:45]
	v_mfma_f32_16x16x32_bf16 v[34:37], v[172:175], v[188:191], v[34:37]
	v_mfma_f32_16x16x32_bf16 v[34:37], v[176:179], v[192:195], v[34:37]
	v_mfma_f32_16x16x32_bf16 v[26:29], v[164:167], v[196:199], v[26:29]
	v_mfma_f32_16x16x32_bf16 v[26:29], v[168:171], v[200:203], v[26:29]
	v_mfma_f32_16x16x32_bf16 v[18:21], v[172:175], v[196:199], v[18:21]
	v_mfma_f32_16x16x32_bf16 v[18:21], v[176:179], v[200:203], v[18:21]
	v_mfma_f32_16x16x32_bf16 v[10:13], v[164:167], v[208:211], v[10:13]
	v_mfma_f32_16x16x32_bf16 v[10:13], v[168:171], v[212:215], v[10:13]
	v_mfma_f32_16x16x32_bf16 v[2:5], v[172:175], v[208:211], v[2:5]
	v_mfma_f32_16x16x32_bf16 v[2:5], v[176:179], v[212:215], v[2:5]
	s_setprio 0
	s_barrier
	s_add_u32 s38, s38, 0x100
	s_addc_u32 s39, s39, 0
	s_add_u32 s68, s68, 0x100
	s_addc_u32 s69, s69, 0
	s_cmp_ge_i32 s72, s37
	s_mov_b32 s2, s72
	s_cbranch_scc0 .LBB0_526

.LBB0_632:
	s_lshl_b32 s11, s26, 20
	s_and_b32 s11, s11, 0xff00000
	v_readlane_b32 s46, v248, 20
	v_readlane_b32 s47, v248, 21
	s_add_u32 s11, s46, s11
	v_cmp_gt_i64_e64 s[0:1], s[26:27], -1
	s_addc_u32 s16, s47, 0
	s_lshr_b32 s27, s26, 13
	s_and_b32 s27, s27, 0x7ff80
	s_add_u32 s76, s11, s27
	s_addc_u32 s77, s16, 0
	s_lshl_b32 s11, s26, 12
	s_and_b32 s11, s11, 0xff00000
	s_add_u32 s11, s60, s11
	s_addc_u32 s16, s61, 0
	s_add_u32 s78, s11, s27
	s_addc_u32 s79, s16, 0
	s_cmp_lt_i32 s17, 1
	s_cbranch_scc1 .LBB0_640
	s_and_b64 s[26:27], s[0:1], exec
	s_cselect_b32 s11, s77, s19
	s_cselect_b32 s16, s76, s18
	s_cselect_b32 s46, s79, s3
	s_cselect_b32 s47, s78, s2
	s_add_i32 s50, s17, -2
	s_add_u32 s18, s18, 0x80080
	s_addc_u32 s19, s19, 0
	s_add_u32 s51, s2, 0x100
	s_addc_u32 s52, s3, 0
	s_mov_b32 s2, 0
	ds_read_b128 v[130:133], v197
	ds_read_b128 v[134:137], v197 offset:1024
	ds_read_b128 v[138:141], v197 offset:2048
	ds_read_b128 v[142:145], v197 offset:3072
	ds_read_b128 v[146:149], v198
	ds_read_b128 v[150:153], v198 offset:1024
	ds_read_b128 v[154:157], v198 offset:2048
	ds_read_b128 v[170:173], v198 offset:3072
	s_add_i32 s53, s2, 2
	s_add_u32 s3, s18, 0xfff80080
	s_addc_u32 s26, s19, -1
	s_cmp_eq_u32 s50, s2
	s_cselect_b32 s2, s47, s51
	s_cselect_b32 s27, s11, s26
	s_cselect_b32 s26, s16, s3
	s_cselect_b32 s3, s46, s52
	s_add_i32 m0, s13, 0xc000
	ds_read_b128 v[174:177], v199
	ds_read_b128 v[178:181], v199 offset:1024
	ds_read_b128 v[182:185], v199 offset:2048
	ds_read_b128 v[186:189], v199 offset:3072
	ds_read_b128 v[190:193], v199 offset:4096
	ds_read_b128 v[200:203], v199 offset:5120
	ds_read_b128 v[208:211], v199 offset:6144
	ds_read_b128 v[212:215], v199 offset:7168
	global_load_lds_dwordx4 v166, s[18:19]
	s_add_i32 m0, s13, 0xe000
	s_nop 0
	global_load_lds_dwordx4 v168, s[18:19]
	s_waitcnt vmcnt(8)
	s_waitcnt lgkmcnt(0)
	v_mfma_f32_16x16x32_bf16 v[122:125], v[130:133], v[174:177], 0
	v_mfma_f32_16x16x32_bf16 v[122:125], v[134:137], v[178:181], v[122:125]
	v_mfma_f32_16x16x32_bf16 v[114:117], v[138:141], v[174:177], 0
	v_mfma_f32_16x16x32_bf16 v[114:117], v[142:145], v[178:181], v[114:117]
	s_barrier
	s_setprio 1
	s_waitcnt lgkmcnt(0)
	v_mfma_f32_16x16x32_bf16 v[106:109], v[130:133], v[182:185], 0
	v_mfma_f32_16x16x32_bf16 v[106:109], v[134:137], v[186:189], v[106:109]
	v_mfma_f32_16x16x32_bf16 v[98:101], v[138:141], v[182:185], 0
	v_mfma_f32_16x16x32_bf16 v[98:101], v[142:145], v[186:189], v[98:101]
	v_mfma_f32_16x16x32_bf16 v[90:93], v[130:133], v[190:193], 0
	v_mfma_f32_16x16x32_bf16 v[90:93], v[134:137], v[200:203], v[90:93]
	v_mfma_f32_16x16x32_bf16 v[82:85], v[138:141], v[190:193], 0
	v_mfma_f32_16x16x32_bf16 v[82:85], v[142:145], v[200:203], v[82:85]
	v_mfma_f32_16x16x32_bf16 v[74:77], v[130:133], v[208:211], 0
	v_mfma_f32_16x16x32_bf16 v[74:77], v[134:137], v[212:215], v[74:77]
	v_mfma_f32_16x16x32_bf16 v[66:69], v[138:141], v[208:211], 0
	v_mfma_f32_16x16x32_bf16 v[66:69], v[142:145], v[212:215], v[66:69]
	s_setprio 0
	s_setprio 1
	v_mfma_f32_16x16x32_bf16 v[126:129], v[146:149], v[174:177], 0
	v_mfma_f32_16x16x32_bf16 v[126:129], v[150:153], v[178:181], v[126:129]
	v_mfma_f32_16x16x32_bf16 v[118:121], v[154:157], v[174:177], 0
	v_mfma_f32_16x16x32_bf16 v[118:121], v[170:173], v[178:181], v[118:121]
	v_mfma_f32_16x16x32_bf16 v[110:113], v[146:149], v[182:185], 0
	v_mfma_f32_16x16x32_bf16 v[110:113], v[150:153], v[186:189], v[110:113]
	v_mfma_f32_16x16x32_bf16 v[102:105], v[154:157], v[182:185], 0
	v_mfma_f32_16x16x32_bf16 v[102:105], v[170:173], v[186:189], v[102:105]
	v_mfma_f32_16x16x32_bf16 v[94:97], v[146:149], v[190:193], 0
	v_mfma_f32_16x16x32_bf16 v[94:97], v[150:153], v[200:203], v[94:97]
	v_mfma_f32_16x16x32_bf16 v[86:89], v[154:157], v[190:193], 0
	v_mfma_f32_16x16x32_bf16 v[86:89], v[170:173], v[200:203], v[86:89]
	v_mfma_f32_16x16x32_bf16 v[78:81], v[146:149], v[208:211], 0
	v_mfma_f32_16x16x32_bf16 v[78:81], v[150:153], v[212:215], v[78:81]
	v_mfma_f32_16x16x32_bf16 v[70:73], v[154:157], v[208:211], 0
	v_mfma_f32_16x16x32_bf16 v[70:73], v[170:173], v[212:215], v[70:73]
	s_setprio 0
	s_barrier
	s_add_i32 s64, s44, s35
	s_mov_b32 m0, s64
	ds_read_b128 v[174:177], v199 offset:16384
	ds_read_b128 v[178:181], v199 offset:17408
	ds_read_b128 v[182:185], v199 offset:18432
	ds_read_b128 v[186:189], v199 offset:19456
	ds_read_b128 v[190:193], v199 offset:20480
	ds_read_b128 v[200:203], v199 offset:21504
	ds_read_b128 v[208:211], v199 offset:22528
	ds_read_b128 v[212:215], v199 offset:23552
	global_load_lds_dwordx4 v160, s[2:3]
	s_add_i32 m0, s64, 0x2000
	s_add_u32 s80, s2, 0x80000
	s_addc_u32 s81, s3, 0
	s_add_i32 s64, s45, s35
	global_load_lds_dwordx4 v164, s[2:3]
	s_mov_b32 m0, s64
	v_lshl_add_u64 v[220:221], s[26:27], 0, v[162:163]
	global_load_lds_dwordx4 v160, s[80:81]
	s_add_i32 m0, s64, 0x2000
	s_nop 0
	global_load_lds_dwordx4 v164, s[80:81]
	v_lshl_add_u64 v[218:219], s[26:27], 0, v[158:159]
	s_mov_b32 m0, s13
	s_nop 0
	global_load_lds_dwordx4 v158, s[26:27]
	s_mov_b32 m0, s36
	s_nop 0
	global_load_lds_dwordx4 v162, s[26:27]
	s_waitcnt vmcnt(8)
	s_waitcnt lgkmcnt(0)
	v_mfma_f32_16x16x32_bf16 v[58:61], v[130:133], v[174:177], 0
	v_mfma_f32_16x16x32_bf16 v[58:61], v[134:137], v[178:181], v[58:61]
	v_mfma_f32_16x16x32_bf16 v[50:53], v[138:141], v[174:177], 0
	v_mfma_f32_16x16x32_bf16 v[50:53], v[142:145], v[178:181], v[50:53]
	s_barrier
	s_setprio 1
	s_waitcnt lgkmcnt(0)
	v_mfma_f32_16x16x32_bf16 v[42:45], v[130:133], v[182:185], 0
	v_mfma_f32_16x16x32_bf16 v[42:45], v[134:137], v[186:189], v[42:45]
	v_mfma_f32_16x16x32_bf16 v[34:37], v[138:141], v[182:185], 0
	v_mfma_f32_16x16x32_bf16 v[34:37], v[142:145], v[186:189], v[34:37]
	v_mfma_f32_16x16x32_bf16 v[26:29], v[130:133], v[190:193], 0
	v_mfma_f32_16x16x32_bf16 v[26:29], v[134:137], v[200:203], v[26:29]
	v_mfma_f32_16x16x32_bf16 v[18:21], v[138:141], v[190:193], 0
	v_mfma_f32_16x16x32_bf16 v[18:21], v[142:145], v[200:203], v[18:21]
	v_mfma_f32_16x16x32_bf16 v[10:13], v[130:133], v[208:211], 0
	v_mfma_f32_16x16x32_bf16 v[10:13], v[134:137], v[212:215], v[10:13]
	v_mfma_f32_16x16x32_bf16 v[2:5], v[138:141], v[208:211], 0
	v_mfma_f32_16x16x32_bf16 v[2:5], v[142:145], v[212:215], v[2:5]
	s_setprio 0
	s_setprio 1
	v_mfma_f32_16x16x32_bf16 v[62:65], v[146:149], v[174:177], 0
	v_mfma_f32_16x16x32_bf16 v[62:65], v[150:153], v[178:181], v[62:65]
	v_mfma_f32_16x16x32_bf16 v[54:57], v[154:157], v[174:177], 0
	v_mfma_f32_16x16x32_bf16 v[54:57], v[170:173], v[178:181], v[54:57]
	v_mfma_f32_16x16x32_bf16 v[46:49], v[146:149], v[182:185], 0
	v_mfma_f32_16x16x32_bf16 v[46:49], v[150:153], v[186:189], v[46:49]
	v_mfma_f32_16x16x32_bf16 v[38:41], v[154:157], v[182:185], 0
	v_mfma_f32_16x16x32_bf16 v[38:41], v[170:173], v[186:189], v[38:41]
	v_mfma_f32_16x16x32_bf16 v[30:33], v[146:149], v[190:193], 0
	v_mfma_f32_16x16x32_bf16 v[30:33], v[150:153], v[200:203], v[30:33]
	v_mfma_f32_16x16x32_bf16 v[22:25], v[154:157], v[190:193], 0
	v_mfma_f32_16x16x32_bf16 v[22:25], v[170:173], v[200:203], v[22:25]
	v_mfma_f32_16x16x32_bf16 v[14:17], v[146:149], v[208:211], 0
	v_mfma_f32_16x16x32_bf16 v[14:17], v[150:153], v[212:215], v[14:17]
	v_mfma_f32_16x16x32_bf16 v[6:9], v[154:157], v[208:211], 0
	v_mfma_f32_16x16x32_bf16 v[6:9], v[170:173], v[212:215], v[6:9]
	s_setprio 0
	s_barrier
	s_add_i32 s64, 0, 0x18000
	s_add_i32 s75, 0, 0x1c000
	v_add_u32_e32 v142, s64, v194
	v_add_u32_e32 v170, s75, v194
	ds_read_b128 v[130:133], v142
	ds_read_b128 v[134:137], v142 offset:1024
	ds_read_b128 v[138:141], v142 offset:2048
	ds_read_b128 v[142:145], v142 offset:3072
	ds_read_b128 v[146:149], v170
	ds_read_b128 v[150:153], v170 offset:1024
	ds_read_b128 v[154:157], v170 offset:2048
	ds_read_b128 v[170:173], v170 offset:3072
	s_add_u32 s26, s26, 0x80000
	s_addc_u32 s27, s27, 0
	s_mov_b32 m0, s37
	ds_read_b128 v[174:177], v199 offset:32768
	ds_read_b128 v[178:181], v199 offset:33792
	ds_read_b128 v[182:185], v199 offset:34816
	ds_read_b128 v[186:189], v199 offset:35840
	ds_read_b128 v[190:193], v199 offset:36864
	ds_read_b128 v[200:203], v199 offset:37888
	ds_read_b128 v[208:211], v199 offset:38912
	ds_read_b128 v[212:215], v199 offset:39936
	global_load_lds_dwordx4 v158, s[26:27]
	s_mov_b32 m0, s38
	s_nop 0
	global_load_lds_dwordx4 v162, s[26:27]
	s_waitcnt vmcnt(8)
	s_waitcnt lgkmcnt(0)
	v_mfma_f32_16x16x32_bf16 v[122:125], v[130:133], v[174:177], v[122:125]
	v_mfma_f32_16x16x32_bf16 v[122:125], v[134:137], v[178:181], v[122:125]
	v_mfma_f32_16x16x32_bf16 v[114:117], v[138:141], v[174:177], v[114:117]
	v_mfma_f32_16x16x32_bf16 v[114:117], v[142:145], v[178:181], v[114:117]
	s_barrier
	s_setprio 1
	s_waitcnt lgkmcnt(0)
	v_mfma_f32_16x16x32_bf16 v[106:109], v[130:133], v[182:185], v[106:109]
	v_mfma_f32_16x16x32_bf16 v[106:109], v[134:137], v[186:189], v[106:109]
	v_mfma_f32_16x16x32_bf16 v[98:101], v[138:141], v[182:185], v[98:101]
	v_mfma_f32_16x16x32_bf16 v[98:101], v[142:145], v[186:189], v[98:101]
	v_mfma_f32_16x16x32_bf16 v[90:93], v[130:133], v[190:193], v[90:93]
	v_mfma_f32_16x16x32_bf16 v[90:93], v[134:137], v[200:203], v[90:93]
	v_mfma_f32_16x16x32_bf16 v[82:85], v[138:141], v[190:193], v[82:85]
	v_mfma_f32_16x16x32_bf16 v[82:85], v[142:145], v[200:203], v[82:85]
	v_mfma_f32_16x16x32_bf16 v[74:77], v[130:133], v[208:211], v[74:77]
	v_mfma_f32_16x16x32_bf16 v[74:77], v[134:137], v[212:215], v[74:77]
	v_mfma_f32_16x16x32_bf16 v[66:69], v[138:141], v[208:211], v[66:69]
	v_mfma_f32_16x16x32_bf16 v[66:69], v[142:145], v[212:215], v[66:69]
	s_setprio 0
	s_setprio 1
	v_mfma_f32_16x16x32_bf16 v[126:129], v[146:149], v[174:177], v[126:129]
	v_mfma_f32_16x16x32_bf16 v[126:129], v[150:153], v[178:181], v[126:129]
	v_mfma_f32_16x16x32_bf16 v[118:121], v[154:157], v[174:177], v[118:121]
	v_mfma_f32_16x16x32_bf16 v[118:121], v[170:173], v[178:181], v[118:121]
	v_mfma_f32_16x16x32_bf16 v[110:113], v[146:149], v[182:185], v[110:113]
	v_mfma_f32_16x16x32_bf16 v[110:113], v[150:153], v[186:189], v[110:113]
	v_mfma_f32_16x16x32_bf16 v[102:105], v[154:157], v[182:185], v[102:105]
	v_mfma_f32_16x16x32_bf16 v[102:105], v[170:173], v[186:189], v[102:105]
	v_mfma_f32_16x16x32_bf16 v[94:97], v[146:149], v[190:193], v[94:97]
	v_mfma_f32_16x16x32_bf16 v[94:97], v[150:153], v[200:203], v[94:97]
	v_mfma_f32_16x16x32_bf16 v[86:89], v[154:157], v[190:193], v[86:89]
	v_mfma_f32_16x16x32_bf16 v[86:89], v[170:173], v[200:203], v[86:89]
	v_mfma_f32_16x16x32_bf16 v[78:81], v[146:149], v[208:211], v[78:81]
	v_mfma_f32_16x16x32_bf16 v[78:81], v[150:153], v[212:215], v[78:81]
	v_mfma_f32_16x16x32_bf16 v[70:73], v[154:157], v[208:211], v[70:73]
	v_mfma_f32_16x16x32_bf16 v[70:73], v[170:173], v[212:215], v[70:73]
	s_setprio 0
	s_barrier
	s_add_i32 s26, s64, s35
	s_add_u32 s98, s2, s68
	s_addc_u32 s99, s3, s69
	s_mov_b32 m0, s26
	ds_read_b128 v[174:177], v199 offset:49152
	ds_read_b128 v[178:181], v199 offset:50176
	ds_read_b128 v[182:185], v199 offset:51200
	ds_read_b128 v[186:189], v199 offset:52224
	ds_read_b128 v[190:193], v199 offset:53248
	ds_read_b128 v[200:203], v199 offset:54272
	ds_read_b128 v[208:211], v199 offset:55296
	ds_read_b128 v[212:215], v199 offset:56320
	global_load_lds_dwordx4 v160, s[98:99]
	s_add_i32 m0, s26, 0x2000
	s_add_u32 s2, s2, 0x80080
	s_addc_u32 s3, s3, 0
	s_add_i32 s26, s75, s35
	global_load_lds_dwordx4 v164, s[98:99]
	s_mov_b32 m0, s26
	s_nop 0
	global_load_lds_dwordx4 v160, s[2:3]
	s_add_i32 m0, s26, 0x2000
	s_nop 0
	global_load_lds_dwordx4 v164, s[2:3]
	v_lshl_add_u64 v[204:205], v[218:219], 0, s[68:69]
	s_mov_b32 m0, s40
	s_nop 0
	global_load_lds_dwordx4 v[204:205], off
	v_lshl_add_u64 v[204:205], v[220:221], 0, s[68:69]
	s_mov_b32 m0, s41
	s_nop 0
	global_load_lds_dwordx4 v[204:205], off
	s_waitcnt vmcnt(8)
	s_waitcnt lgkmcnt(0)
	v_mfma_f32_16x16x32_bf16 v[58:61], v[130:133], v[174:177], v[58:61]
	v_mfma_f32_16x16x32_bf16 v[58:61], v[134:137], v[178:181], v[58:61]
	v_mfma_f32_16x16x32_bf16 v[50:53], v[138:141], v[174:177], v[50:53]
	v_mfma_f32_16x16x32_bf16 v[50:53], v[142:145], v[178:181], v[50:53]
	s_barrier
	s_setprio 1
	s_waitcnt lgkmcnt(0)
	v_mfma_f32_16x16x32_bf16 v[42:45], v[130:133], v[182:185], v[42:45]
	v_mfma_f32_16x16x32_bf16 v[42:45], v[134:137], v[186:189], v[42:45]
	v_mfma_f32_16x16x32_bf16 v[34:37], v[138:141], v[182:185], v[34:37]
	v_mfma_f32_16x16x32_bf16 v[34:37], v[142:145], v[186:189], v[34:37]
	v_mfma_f32_16x16x32_bf16 v[26:29], v[130:133], v[190:193], v[26:29]
	v_mfma_f32_16x16x32_bf16 v[26:29], v[134:137], v[200:203], v[26:29]
	v_mfma_f32_16x16x32_bf16 v[18:21], v[138:141], v[190:193], v[18:21]
	v_mfma_f32_16x16x32_bf16 v[18:21], v[142:145], v[200:203], v[18:21]
	v_mfma_f32_16x16x32_bf16 v[10:13], v[130:133], v[208:211], v[10:13]
	v_mfma_f32_16x16x32_bf16 v[10:13], v[134:137], v[212:215], v[10:13]
	v_mfma_f32_16x16x32_bf16 v[2:5], v[138:141], v[208:211], v[2:5]
	v_mfma_f32_16x16x32_bf16 v[2:5], v[142:145], v[212:215], v[2:5]
	s_setprio 0
	s_setprio 1
	v_mfma_f32_16x16x32_bf16 v[62:65], v[146:149], v[174:177], v[62:65]
	v_mfma_f32_16x16x32_bf16 v[62:65], v[150:153], v[178:181], v[62:65]
	v_mfma_f32_16x16x32_bf16 v[54:57], v[154:157], v[174:177], v[54:57]
	v_mfma_f32_16x16x32_bf16 v[54:57], v[170:173], v[178:181], v[54:57]
	v_mfma_f32_16x16x32_bf16 v[46:49], v[146:149], v[182:185], v[46:49]
	v_mfma_f32_16x16x32_bf16 v[46:49], v[150:153], v[186:189], v[46:49]
	v_mfma_f32_16x16x32_bf16 v[38:41], v[154:157], v[182:185], v[38:41]
	v_mfma_f32_16x16x32_bf16 v[38:41], v[170:173], v[186:189], v[38:41]
	v_mfma_f32_16x16x32_bf16 v[30:33], v[146:149], v[190:193], v[30:33]
	v_mfma_f32_16x16x32_bf16 v[30:33], v[150:153], v[200:203], v[30:33]
	v_mfma_f32_16x16x32_bf16 v[22:25], v[154:157], v[190:193], v[22:25]
	v_mfma_f32_16x16x32_bf16 v[22:25], v[170:173], v[200:203], v[22:25]
	v_mfma_f32_16x16x32_bf16 v[14:17], v[146:149], v[208:211], v[14:17]
	v_mfma_f32_16x16x32_bf16 v[14:17], v[150:153], v[212:215], v[14:17]
	v_mfma_f32_16x16x32_bf16 v[6:9], v[154:157], v[208:211], v[6:9]
	v_mfma_f32_16x16x32_bf16 v[6:9], v[170:173], v[212:215], v[6:9]
	s_setprio 0
	s_barrier
	s_add_u32 s18, s18, 0x100
	s_addc_u32 s19, s19, 0
	s_add_u32 s51, s51, 0x100
	s_addc_u32 s52, s52, 0
	s_cmp_ge_i32 s53, s17
	s_mov_b32 s2, s53
	s_cbranch_scc1 .Lkpeel_exit_3
.LBB0_634:
	ds_read_b128 v[130:133], v197
	ds_read_b128 v[134:137], v197 offset:1024
	ds_read_b128 v[138:141], v197 offset:2048
	ds_read_b128 v[142:145], v197 offset:3072
	ds_read_b128 v[146:149], v198
	ds_read_b128 v[150:153], v198 offset:1024
	ds_read_b128 v[154:157], v198 offset:2048
	ds_read_b128 v[170:173], v198 offset:3072
	s_add_i32 s53, s2, 2
	s_add_u32 s3, s18, 0xfff80080
	s_addc_u32 s26, s19, -1
	s_cmp_eq_u32 s50, s2
	s_cselect_b32 s2, s47, s51
	s_cselect_b32 s27, s11, s26
	s_cselect_b32 s26, s16, s3
	s_cselect_b32 s3, s46, s52
	s_add_i32 m0, s13, 0xc000
	ds_read_b128 v[174:177], v199
	ds_read_b128 v[178:181], v199 offset:1024
	ds_read_b128 v[182:185], v199 offset:2048
	ds_read_b128 v[186:189], v199 offset:3072
	ds_read_b128 v[190:193], v199 offset:4096
	ds_read_b128 v[200:203], v199 offset:5120
	ds_read_b128 v[208:211], v199 offset:6144
	ds_read_b128 v[212:215], v199 offset:7168
	global_load_lds_dwordx4 v166, s[18:19]
	s_add_i32 m0, s13, 0xe000
	s_nop 0
	global_load_lds_dwordx4 v168, s[18:19]
	s_waitcnt vmcnt(8)
	s_waitcnt lgkmcnt(0)
	v_mfma_f32_16x16x32_bf16 v[122:125], v[130:133], v[174:177], v[122:125]
	v_mfma_f32_16x16x32_bf16 v[122:125], v[134:137], v[178:181], v[122:125]
	v_mfma_f32_16x16x32_bf16 v[114:117], v[138:141], v[174:177], v[114:117]
	v_mfma_f32_16x16x32_bf16 v[114:117], v[142:145], v[178:181], v[114:117]
	s_barrier
	s_setprio 1
	s_waitcnt lgkmcnt(0)
	v_mfma_f32_16x16x32_bf16 v[106:109], v[130:133], v[182:185], v[106:109]
	v_mfma_f32_16x16x32_bf16 v[106:109], v[134:137], v[186:189], v[106:109]
	v_mfma_f32_16x16x32_bf16 v[98:101], v[138:141], v[182:185], v[98:101]
	v_mfma_f32_16x16x32_bf16 v[98:101], v[142:145], v[186:189], v[98:101]
	v_mfma_f32_16x16x32_bf16 v[90:93], v[130:133], v[190:193], v[90:93]
	v_mfma_f32_16x16x32_bf16 v[90:93], v[134:137], v[200:203], v[90:93]
	v_mfma_f32_16x16x32_bf16 v[82:85], v[138:141], v[190:193], v[82:85]
	v_mfma_f32_16x16x32_bf16 v[82:85], v[142:145], v[200:203], v[82:85]
	v_mfma_f32_16x16x32_bf16 v[74:77], v[130:133], v[208:211], v[74:77]
	v_mfma_f32_16x16x32_bf16 v[74:77], v[134:137], v[212:215], v[74:77]
	v_mfma_f32_16x16x32_bf16 v[66:69], v[138:141], v[208:211], v[66:69]
	v_mfma_f32_16x16x32_bf16 v[66:69], v[142:145], v[212:215], v[66:69]
	s_setprio 0
	s_setprio 1
	v_mfma_f32_16x16x32_bf16 v[126:129], v[146:149], v[174:177], v[126:129]
	v_mfma_f32_16x16x32_bf16 v[126:129], v[150:153], v[178:181], v[126:129]
	v_mfma_f32_16x16x32_bf16 v[118:121], v[154:157], v[174:177], v[118:121]
	v_mfma_f32_16x16x32_bf16 v[118:121], v[170:173], v[178:181], v[118:121]
	v_mfma_f32_16x16x32_bf16 v[110:113], v[146:149], v[182:185], v[110:113]
	v_mfma_f32_16x16x32_bf16 v[110:113], v[150:153], v[186:189], v[110:113]
	v_mfma_f32_16x16x32_bf16 v[102:105], v[154:157], v[182:185], v[102:105]
	v_mfma_f32_16x16x32_bf16 v[102:105], v[170:173], v[186:189], v[102:105]
	v_mfma_f32_16x16x32_bf16 v[94:97], v[146:149], v[190:193], v[94:97]
	v_mfma_f32_16x16x32_bf16 v[94:97], v[150:153], v[200:203], v[94:97]
	v_mfma_f32_16x16x32_bf16 v[86:89], v[154:157], v[190:193], v[86:89]
	v_mfma_f32_16x16x32_bf16 v[86:89], v[170:173], v[200:203], v[86:89]
	v_mfma_f32_16x16x32_bf16 v[78:81], v[146:149], v[208:211], v[78:81]
	v_mfma_f32_16x16x32_bf16 v[78:81], v[150:153], v[212:215], v[78:81]
	v_mfma_f32_16x16x32_bf16 v[70:73], v[154:157], v[208:211], v[70:73]
	v_mfma_f32_16x16x32_bf16 v[70:73], v[170:173], v[212:215], v[70:73]
	s_setprio 0
	s_barrier
	s_add_i32 s64, s44, s35
	s_mov_b32 m0, s64
	ds_read_b128 v[174:177], v199 offset:16384
	ds_read_b128 v[178:181], v199 offset:17408
	ds_read_b128 v[182:185], v199 offset:18432
	ds_read_b128 v[186:189], v199 offset:19456
	ds_read_b128 v[190:193], v199 offset:20480
	ds_read_b128 v[200:203], v199 offset:21504
	ds_read_b128 v[208:211], v199 offset:22528
	ds_read_b128 v[212:215], v199 offset:23552
	global_load_lds_dwordx4 v160, s[2:3]
	s_add_i32 m0, s64, 0x2000
	s_add_u32 s80, s2, 0x80000
	s_addc_u32 s81, s3, 0
	s_add_i32 s64, s45, s35
	global_load_lds_dwordx4 v164, s[2:3]
	s_mov_b32 m0, s64
	v_lshl_add_u64 v[220:221], s[26:27], 0, v[162:163]
	global_load_lds_dwordx4 v160, s[80:81]
	s_add_i32 m0, s64, 0x2000
	s_nop 0
	global_load_lds_dwordx4 v164, s[80:81]
	v_lshl_add_u64 v[218:219], s[26:27], 0, v[158:159]
	s_mov_b32 m0, s13
	s_nop 0
	global_load_lds_dwordx4 v158, s[26:27]
	s_mov_b32 m0, s36
	s_nop 0
	global_load_lds_dwordx4 v162, s[26:27]
	s_waitcnt vmcnt(8)
	s_waitcnt lgkmcnt(0)
	v_mfma_f32_16x16x32_bf16 v[58:61], v[130:133], v[174:177], v[58:61]
	v_mfma_f32_16x16x32_bf16 v[58:61], v[134:137], v[178:181], v[58:61]
	v_mfma_f32_16x16x32_bf16 v[50:53], v[138:141], v[174:177], v[50:53]
	v_mfma_f32_16x16x32_bf16 v[50:53], v[142:145], v[178:181], v[50:53]
	s_barrier
	s_setprio 1
	s_waitcnt lgkmcnt(0)
	v_mfma_f32_16x16x32_bf16 v[42:45], v[130:133], v[182:185], v[42:45]
	v_mfma_f32_16x16x32_bf16 v[42:45], v[134:137], v[186:189], v[42:45]
	v_mfma_f32_16x16x32_bf16 v[34:37], v[138:141], v[182:185], v[34:37]
	v_mfma_f32_16x16x32_bf16 v[34:37], v[142:145], v[186:189], v[34:37]
	v_mfma_f32_16x16x32_bf16 v[26:29], v[130:133], v[190:193], v[26:29]
	v_mfma_f32_16x16x32_bf16 v[26:29], v[134:137], v[200:203], v[26:29]
	v_mfma_f32_16x16x32_bf16 v[18:21], v[138:141], v[190:193], v[18:21]
	v_mfma_f32_16x16x32_bf16 v[18:21], v[142:145], v[200:203], v[18:21]
	v_mfma_f32_16x16x32_bf16 v[10:13], v[130:133], v[208:211], v[10:13]
	v_mfma_f32_16x16x32_bf16 v[10:13], v[134:137], v[212:215], v[10:13]
	v_mfma_f32_16x16x32_bf16 v[2:5], v[138:141], v[208:211], v[2:5]
	v_mfma_f32_16x16x32_bf16 v[2:5], v[142:145], v[212:215], v[2:5]
	s_setprio 0
	s_setprio 1
	v_mfma_f32_16x16x32_bf16 v[62:65], v[146:149], v[174:177], v[62:65]
	v_mfma_f32_16x16x32_bf16 v[62:65], v[150:153], v[178:181], v[62:65]
	v_mfma_f32_16x16x32_bf16 v[54:57], v[154:157], v[174:177], v[54:57]
	v_mfma_f32_16x16x32_bf16 v[54:57], v[170:173], v[178:181], v[54:57]
	v_mfma_f32_16x16x32_bf16 v[46:49], v[146:149], v[182:185], v[46:49]
	v_mfma_f32_16x16x32_bf16 v[46:49], v[150:153], v[186:189], v[46:49]
	v_mfma_f32_16x16x32_bf16 v[38:41], v[154:157], v[182:185], v[38:41]
	v_mfma_f32_16x16x32_bf16 v[38:41], v[170:173], v[186:189], v[38:41]
	v_mfma_f32_16x16x32_bf16 v[30:33], v[146:149], v[190:193], v[30:33]
	v_mfma_f32_16x16x32_bf16 v[30:33], v[150:153], v[200:203], v[30:33]
	v_mfma_f32_16x16x32_bf16 v[22:25], v[154:157], v[190:193], v[22:25]
	v_mfma_f32_16x16x32_bf16 v[22:25], v[170:173], v[200:203], v[22:25]
	v_mfma_f32_16x16x32_bf16 v[14:17], v[146:149], v[208:211], v[14:17]
	v_mfma_f32_16x16x32_bf16 v[14:17], v[150:153], v[212:215], v[14:17]
	v_mfma_f32_16x16x32_bf16 v[6:9], v[154:157], v[208:211], v[6:9]
	v_mfma_f32_16x16x32_bf16 v[6:9], v[170:173], v[212:215], v[6:9]
	s_setprio 0
	s_barrier
	s_add_i32 s64, 0, 0x18000
	s_add_i32 s75, 0, 0x1c000
	v_add_u32_e32 v142, s64, v194
	v_add_u32_e32 v170, s75, v194
	ds_read_b128 v[130:133], v142
	ds_read_b128 v[134:137], v142 offset:1024
	ds_read_b128 v[138:141], v142 offset:2048
	ds_read_b128 v[142:145], v142 offset:3072
	ds_read_b128 v[146:149], v170
	ds_read_b128 v[150:153], v170 offset:1024
	ds_read_b128 v[154:157], v170 offset:2048
	ds_read_b128 v[170:173], v170 offset:3072
	s_add_u32 s26, s26, 0x80000
	s_addc_u32 s27, s27, 0
	s_mov_b32 m0, s37
	ds_read_b128 v[174:177], v199 offset:32768
	ds_read_b128 v[178:181], v199 offset:33792
	ds_read_b128 v[182:185], v199 offset:34816
	ds_read_b128 v[186:189], v199 offset:35840
	ds_read_b128 v[190:193], v199 offset:36864
	ds_read_b128 v[200:203], v199 offset:37888
	ds_read_b128 v[208:211], v199 offset:38912
	ds_read_b128 v[212:215], v199 offset:39936
	global_load_lds_dwordx4 v158, s[26:27]
	s_mov_b32 m0, s38
	s_nop 0
	global_load_lds_dwordx4 v162, s[26:27]
	s_waitcnt vmcnt(8)
	s_waitcnt lgkmcnt(0)
	v_mfma_f32_16x16x32_bf16 v[122:125], v[130:133], v[174:177], v[122:125]
	v_mfma_f32_16x16x32_bf16 v[122:125], v[134:137], v[178:181], v[122:125]
	v_mfma_f32_16x16x32_bf16 v[114:117], v[138:141], v[174:177], v[114:117]
	v_mfma_f32_16x16x32_bf16 v[114:117], v[142:145], v[178:181], v[114:117]
	s_barrier
	s_setprio 1
	s_waitcnt lgkmcnt(0)
	v_mfma_f32_16x16x32_bf16 v[106:109], v[130:133], v[182:185], v[106:109]
	v_mfma_f32_16x16x32_bf16 v[106:109], v[134:137], v[186:189], v[106:109]
	v_mfma_f32_16x16x32_bf16 v[98:101], v[138:141], v[182:185], v[98:101]
	v_mfma_f32_16x16x32_bf16 v[98:101], v[142:145], v[186:189], v[98:101]
	v_mfma_f32_16x16x32_bf16 v[90:93], v[130:133], v[190:193], v[90:93]
	v_mfma_f32_16x16x32_bf16 v[90:93], v[134:137], v[200:203], v[90:93]
	v_mfma_f32_16x16x32_bf16 v[82:85], v[138:141], v[190:193], v[82:85]
	v_mfma_f32_16x16x32_bf16 v[82:85], v[142:145], v[200:203], v[82:85]
	v_mfma_f32_16x16x32_bf16 v[74:77], v[130:133], v[208:211], v[74:77]
	v_mfma_f32_16x16x32_bf16 v[74:77], v[134:137], v[212:215], v[74:77]
	v_mfma_f32_16x16x32_bf16 v[66:69], v[138:141], v[208:211], v[66:69]
	v_mfma_f32_16x16x32_bf16 v[66:69], v[142:145], v[212:215], v[66:69]
	s_setprio 0
	s_setprio 1
	v_mfma_f32_16x16x32_bf16 v[126:129], v[146:149], v[174:177], v[126:129]
	v_mfma_f32_16x16x32_bf16 v[126:129], v[150:153], v[178:181], v[126:129]
	v_mfma_f32_16x16x32_bf16 v[118:121], v[154:157], v[174:177], v[118:121]
	v_mfma_f32_16x16x32_bf16 v[118:121], v[170:173], v[178:181], v[118:121]
	v_mfma_f32_16x16x32_bf16 v[110:113], v[146:149], v[182:185], v[110:113]
	v_mfma_f32_16x16x32_bf16 v[110:113], v[150:153], v[186:189], v[110:113]
	v_mfma_f32_16x16x32_bf16 v[102:105], v[154:157], v[182:185], v[102:105]
	v_mfma_f32_16x16x32_bf16 v[102:105], v[170:173], v[186:189], v[102:105]
	v_mfma_f32_16x16x32_bf16 v[94:97], v[146:149], v[190:193], v[94:97]
	v_mfma_f32_16x16x32_bf16 v[94:97], v[150:153], v[200:203], v[94:97]
	v_mfma_f32_16x16x32_bf16 v[86:89], v[154:157], v[190:193], v[86:89]
	v_mfma_f32_16x16x32_bf16 v[86:89], v[170:173], v[200:203], v[86:89]
	v_mfma_f32_16x16x32_bf16 v[78:81], v[146:149], v[208:211], v[78:81]
	v_mfma_f32_16x16x32_bf16 v[78:81], v[150:153], v[212:215], v[78:81]
	v_mfma_f32_16x16x32_bf16 v[70:73], v[154:157], v[208:211], v[70:73]
	v_mfma_f32_16x16x32_bf16 v[70:73], v[170:173], v[212:215], v[70:73]
	s_setprio 0
	s_barrier
	s_add_i32 s26, s64, s35
	s_add_u32 s98, s2, s68
	s_addc_u32 s99, s3, s69
	s_mov_b32 m0, s26
	ds_read_b128 v[174:177], v199 offset:49152
	ds_read_b128 v[178:181], v199 offset:50176
	ds_read_b128 v[182:185], v199 offset:51200
	ds_read_b128 v[186:189], v199 offset:52224
	ds_read_b128 v[190:193], v199 offset:53248
	ds_read_b128 v[200:203], v199 offset:54272
	ds_read_b128 v[208:211], v199 offset:55296
	ds_read_b128 v[212:215], v199 offset:56320
	global_load_lds_dwordx4 v160, s[98:99]
	s_add_i32 m0, s26, 0x2000
	s_add_u32 s2, s2, 0x80080
	s_addc_u32 s3, s3, 0
	s_add_i32 s26, s75, s35
	global_load_lds_dwordx4 v164, s[98:99]
	s_mov_b32 m0, s26
	s_nop 0
	global_load_lds_dwordx4 v160, s[2:3]
	s_add_i32 m0, s26, 0x2000
	s_nop 0
	global_load_lds_dwordx4 v164, s[2:3]
	v_lshl_add_u64 v[204:205], v[218:219], 0, s[68:69]
	s_mov_b32 m0, s40
	s_nop 0
	global_load_lds_dwordx4 v[204:205], off
	v_lshl_add_u64 v[204:205], v[220:221], 0, s[68:69]
	s_mov_b32 m0, s41
	s_nop 0
	global_load_lds_dwordx4 v[204:205], off
	s_waitcnt vmcnt(8)
	s_waitcnt lgkmcnt(0)
	v_mfma_f32_16x16x32_bf16 v[58:61], v[130:133], v[174:177], v[58:61]
	v_mfma_f32_16x16x32_bf16 v[58:61], v[134:137], v[178:181], v[58:61]
	v_mfma_f32_16x16x32_bf16 v[50:53], v[138:141], v[174:177], v[50:53]
	v_mfma_f32_16x16x32_bf16 v[50:53], v[142:145], v[178:181], v[50:53]
	s_barrier
	s_setprio 1
	s_waitcnt lgkmcnt(0)
	v_mfma_f32_16x16x32_bf16 v[42:45], v[130:133], v[182:185], v[42:45]
	v_mfma_f32_16x16x32_bf16 v[42:45], v[134:137], v[186:189], v[42:45]
	v_mfma_f32_16x16x32_bf16 v[34:37], v[138:141], v[182:185], v[34:37]
	v_mfma_f32_16x16x32_bf16 v[34:37], v[142:145], v[186:189], v[34:37]
	v_mfma_f32_16x16x32_bf16 v[26:29], v[130:133], v[190:193], v[26:29]
	v_mfma_f32_16x16x32_bf16 v[26:29], v[134:137], v[200:203], v[26:29]
	v_mfma_f32_16x16x32_bf16 v[18:21], v[138:141], v[190:193], v[18:21]
	v_mfma_f32_16x16x32_bf16 v[18:21], v[142:145], v[200:203], v[18:21]
	v_mfma_f32_16x16x32_bf16 v[10:13], v[130:133], v[208:211], v[10:13]
	v_mfma_f32_16x16x32_bf16 v[10:13], v[134:137], v[212:215], v[10:13]
	v_mfma_f32_16x16x32_bf16 v[2:5], v[138:141], v[208:211], v[2:5]
	v_mfma_f32_16x16x32_bf16 v[2:5], v[142:145], v[212:215], v[2:5]
	s_setprio 0
	s_setprio 1
	v_mfma_f32_16x16x32_bf16 v[62:65], v[146:149], v[174:177], v[62:65]
	v_mfma_f32_16x16x32_bf16 v[62:65], v[150:153], v[178:181], v[62:65]
	v_mfma_f32_16x16x32_bf16 v[54:57], v[154:157], v[174:177], v[54:57]
	v_mfma_f32_16x16x32_bf16 v[54:57], v[170:173], v[178:181], v[54:57]
	v_mfma_f32_16x16x32_bf16 v[46:49], v[146:149], v[182:185], v[46:49]
	v_mfma_f32_16x16x32_bf16 v[46:49], v[150:153], v[186:189], v[46:49]
	v_mfma_f32_16x16x32_bf16 v[38:41], v[154:157], v[182:185], v[38:41]
	v_mfma_f32_16x16x32_bf16 v[38:41], v[170:173], v[186:189], v[38:41]
	v_mfma_f32_16x16x32_bf16 v[30:33], v[146:149], v[190:193], v[30:33]
	v_mfma_f32_16x16x32_bf16 v[30:33], v[150:153], v[200:203], v[30:33]
	v_mfma_f32_16x16x32_bf16 v[22:25], v[154:157], v[190:193], v[22:25]
	v_mfma_f32_16x16x32_bf16 v[22:25], v[170:173], v[200:203], v[22:25]
	v_mfma_f32_16x16x32_bf16 v[14:17], v[146:149], v[208:211], v[14:17]
	v_mfma_f32_16x16x32_bf16 v[14:17], v[150:153], v[212:215], v[14:17]
	v_mfma_f32_16x16x32_bf16 v[6:9], v[154:157], v[208:211], v[6:9]
	v_mfma_f32_16x16x32_bf16 v[6:9], v[170:173], v[212:215], v[6:9]
	s_setprio 0
	s_barrier
	s_add_u32 s18, s18, 0x100
	s_addc_u32 s19, s19, 0
	s_add_u32 s51, s51, 0x100
	s_addc_u32 s52, s52, 0
	s_cmp_ge_i32 s53, s17
	s_mov_b32 s2, s53
	s_cbranch_scc0 .LBB0_634

.LBB0_798:
	s_lshl_b32 s0, s26, 21
	s_and_b32 s0, s0, 0x1fe00000
	v_readlane_b32 s22, v248, 22
	v_readlane_b32 s23, v248, 23
	s_add_u32 s0, s22, s0
	s_addc_u32 s23, s23, 0
	s_lshr_b32 s22, s26, 13
	s_and_b32 s24, s22, 0x7ff80
	s_add_u32 s22, s0, s24
	s_addc_u32 s23, s23, 0
	s_lshl_b32 s0, s26, 13
	s_and_b32 s0, s0, 0x1fe00000
	s_add_u32 s0, s82, s0
	s_addc_u32 s25, s83, 0
	s_add_u32 s24, s0, s24
	s_addc_u32 s25, s25, 0
	s_cmp_lt_i32 s35, 1
	v_cmp_gt_i64_e64 s[26:27], s[26:27], -1
	s_cbranch_scc1 .LBB0_820
	s_and_b64 s[38:39], s[26:27], exec
	s_cselect_b32 s0, s23, s37
	s_cselect_b32 s34, s22, s36
	s_cselect_b32 s56, s25, s3
	s_cselect_b32 s57, s24, s2
	s_add_i32 s58, s35, -2
	s_add_u32 s36, s36, 0x100080
	s_addc_u32 s37, s37, 0
	s_add_u32 s59, s2, 0x100
	s_addc_u32 s60, s3, 0
	s_mov_b32 s2, 0
	ds_read_b128 v[148:151], v144
	ds_read_b128 v[152:155], v144 offset:1024
	ds_read_b128 v[156:159], v144 offset:2048
	ds_read_b128 v[160:163], v144 offset:3072
	ds_read_b128 v[164:167], v145
	ds_read_b128 v[168:171], v145 offset:1024
	ds_read_b128 v[172:175], v145 offset:2048
	ds_read_b128 v[176:179], v145 offset:3072
	s_add_i32 s61, s2, 2
	s_add_u32 s3, s36, 0xfff00080
	s_addc_u32 s38, s37, -1
	s_cmp_eq_u32 s58, s2
	s_cselect_b32 s2, s57, s59
	s_cselect_b32 s39, s0, s38
	s_cselect_b32 s38, s34, s3
	s_cselect_b32 s3, s56, s60
	s_add_i32 m0, s29, 0xc000
	ds_read_b128 v[180:183], v146
	ds_read_b128 v[184:187], v146 offset:1024
	ds_read_b128 v[188:191], v146 offset:2048
	ds_read_b128 v[192:195], v146 offset:3072
	ds_read_b128 v[196:199], v146 offset:4096
	ds_read_b128 v[200:203], v146 offset:5120
	ds_read_b128 v[208:211], v146 offset:6144
	ds_read_b128 v[212:215], v146 offset:7168
	global_load_lds_dwordx4 v138, s[36:37]
	s_add_i32 m0, s29, 0xe000
	s_nop 0
	global_load_lds_dwordx4 v140, s[36:37]
	s_waitcnt vmcnt(8)
	s_waitcnt lgkmcnt(0)
	v_mfma_f32_16x16x32_bf16 v[126:129], v[148:151], v[180:183], 0
	v_mfma_f32_16x16x32_bf16 v[126:129], v[152:155], v[184:187], v[126:129]
	v_mfma_f32_16x16x32_bf16 v[122:125], v[156:159], v[180:183], 0
	v_mfma_f32_16x16x32_bf16 v[122:125], v[160:163], v[184:187], v[122:125]
	s_barrier
	s_setprio 1
	s_waitcnt lgkmcnt(0)
	v_mfma_f32_16x16x32_bf16 v[110:113], v[148:151], v[188:191], 0
	v_mfma_f32_16x16x32_bf16 v[110:113], v[152:155], v[192:195], v[110:113]
	v_mfma_f32_16x16x32_bf16 v[102:105], v[156:159], v[188:191], 0
	v_mfma_f32_16x16x32_bf16 v[102:105], v[160:163], v[192:195], v[102:105]
	v_mfma_f32_16x16x32_bf16 v[94:97], v[148:151], v[196:199], 0
	v_mfma_f32_16x16x32_bf16 v[94:97], v[152:155], v[200:203], v[94:97]
	v_mfma_f32_16x16x32_bf16 v[86:89], v[156:159], v[196:199], 0
	v_mfma_f32_16x16x32_bf16 v[86:89], v[160:163], v[200:203], v[86:89]
	v_mfma_f32_16x16x32_bf16 v[78:81], v[148:151], v[208:211], 0
	v_mfma_f32_16x16x32_bf16 v[78:81], v[152:155], v[212:215], v[78:81]
	v_mfma_f32_16x16x32_bf16 v[70:73], v[156:159], v[208:211], 0
	v_mfma_f32_16x16x32_bf16 v[70:73], v[160:163], v[212:215], v[70:73]
	s_setprio 0
	s_setprio 1
	v_mfma_f32_16x16x32_bf16 v[118:121], v[164:167], v[180:183], 0
	v_mfma_f32_16x16x32_bf16 v[118:121], v[168:171], v[184:187], v[118:121]
	v_mfma_f32_16x16x32_bf16 v[114:117], v[172:175], v[180:183], 0
	v_mfma_f32_16x16x32_bf16 v[114:117], v[176:179], v[184:187], v[114:117]
	v_mfma_f32_16x16x32_bf16 v[106:109], v[164:167], v[188:191], 0
	v_mfma_f32_16x16x32_bf16 v[106:109], v[168:171], v[192:195], v[106:109]
	v_mfma_f32_16x16x32_bf16 v[98:101], v[172:175], v[188:191], 0
	v_mfma_f32_16x16x32_bf16 v[98:101], v[176:179], v[192:195], v[98:101]
	v_mfma_f32_16x16x32_bf16 v[90:93], v[164:167], v[196:199], 0
	v_mfma_f32_16x16x32_bf16 v[90:93], v[168:171], v[200:203], v[90:93]
	v_mfma_f32_16x16x32_bf16 v[82:85], v[172:175], v[196:199], 0
	v_mfma_f32_16x16x32_bf16 v[82:85], v[176:179], v[200:203], v[82:85]
	v_mfma_f32_16x16x32_bf16 v[74:77], v[164:167], v[208:211], 0
	v_mfma_f32_16x16x32_bf16 v[74:77], v[168:171], v[212:215], v[74:77]
	v_mfma_f32_16x16x32_bf16 v[66:69], v[172:175], v[208:211], 0
	v_mfma_f32_16x16x32_bf16 v[66:69], v[176:179], v[212:215], v[66:69]
	s_setprio 0
	s_barrier
	s_add_i32 s64, s50, s33
	s_mov_b32 m0, s64
	ds_read_b128 v[180:183], v146 offset:16384
	ds_read_b128 v[184:187], v146 offset:17408
	ds_read_b128 v[188:191], v146 offset:18432
	ds_read_b128 v[192:195], v146 offset:19456
	ds_read_b128 v[196:199], v146 offset:20480
	ds_read_b128 v[200:203], v146 offset:21504
	ds_read_b128 v[208:211], v146 offset:22528
	ds_read_b128 v[212:215], v146 offset:23552
	global_load_lds_dwordx4 v132, s[2:3]
	s_add_i32 m0, s64, 0x2000
	s_add_u32 s64, s2, 0x100000
	s_addc_u32 s65, s3, 0
	s_add_i32 s66, s51, s33
	global_load_lds_dwordx4 v136, s[2:3]
	s_mov_b32 m0, s66
	v_lshl_add_u64 v[220:221], s[38:39], 0, v[134:135]
	global_load_lds_dwordx4 v132, s[64:65]
	s_add_i32 m0, s66, 0x2000
	s_nop 0
	global_load_lds_dwordx4 v136, s[64:65]
	v_lshl_add_u64 v[218:219], s[38:39], 0, v[130:131]
	s_mov_b32 m0, s29
	s_nop 0
	global_load_lds_dwordx4 v130, s[38:39]
	s_mov_b32 m0, s31
	s_nop 0
	global_load_lds_dwordx4 v134, s[38:39]
	s_waitcnt vmcnt(8)
	s_waitcnt lgkmcnt(0)
	v_mfma_f32_16x16x32_bf16 v[62:65], v[148:151], v[180:183], 0
	v_mfma_f32_16x16x32_bf16 v[62:65], v[152:155], v[184:187], v[62:65]
	v_mfma_f32_16x16x32_bf16 v[54:57], v[156:159], v[180:183], 0
	v_mfma_f32_16x16x32_bf16 v[54:57], v[160:163], v[184:187], v[54:57]
	s_barrier
	s_setprio 1
	s_waitcnt lgkmcnt(0)
	v_mfma_f32_16x16x32_bf16 v[46:49], v[148:151], v[188:191], 0
	v_mfma_f32_16x16x32_bf16 v[46:49], v[152:155], v[192:195], v[46:49]
	v_mfma_f32_16x16x32_bf16 v[38:41], v[156:159], v[188:191], 0
	v_mfma_f32_16x16x32_bf16 v[38:41], v[160:163], v[192:195], v[38:41]
	v_mfma_f32_16x16x32_bf16 v[30:33], v[148:151], v[196:199], 0
	v_mfma_f32_16x16x32_bf16 v[30:33], v[152:155], v[200:203], v[30:33]
	v_mfma_f32_16x16x32_bf16 v[22:25], v[156:159], v[196:199], 0
	v_mfma_f32_16x16x32_bf16 v[22:25], v[160:163], v[200:203], v[22:25]
	v_mfma_f32_16x16x32_bf16 v[14:17], v[148:151], v[208:211], 0
	v_mfma_f32_16x16x32_bf16 v[14:17], v[152:155], v[212:215], v[14:17]
	v_mfma_f32_16x16x32_bf16 v[6:9], v[156:159], v[208:211], 0
	v_mfma_f32_16x16x32_bf16 v[6:9], v[160:163], v[212:215], v[6:9]
	s_setprio 0
	s_setprio 1
	v_mfma_f32_16x16x32_bf16 v[58:61], v[164:167], v[180:183], 0
	v_mfma_f32_16x16x32_bf16 v[58:61], v[168:171], v[184:187], v[58:61]
	v_mfma_f32_16x16x32_bf16 v[50:53], v[172:175], v[180:183], 0
	v_mfma_f32_16x16x32_bf16 v[50:53], v[176:179], v[184:187], v[50:53]
	v_mfma_f32_16x16x32_bf16 v[42:45], v[164:167], v[188:191], 0
	v_mfma_f32_16x16x32_bf16 v[42:45], v[168:171], v[192:195], v[42:45]
	v_mfma_f32_16x16x32_bf16 v[34:37], v[172:175], v[188:191], 0
	v_mfma_f32_16x16x32_bf16 v[34:37], v[176:179], v[192:195], v[34:37]
	v_mfma_f32_16x16x32_bf16 v[26:29], v[164:167], v[196:199], 0
	v_mfma_f32_16x16x32_bf16 v[26:29], v[168:171], v[200:203], v[26:29]
	v_mfma_f32_16x16x32_bf16 v[18:21], v[172:175], v[196:199], 0
	v_mfma_f32_16x16x32_bf16 v[18:21], v[176:179], v[200:203], v[18:21]
	v_mfma_f32_16x16x32_bf16 v[10:13], v[164:167], v[208:211], 0
	v_mfma_f32_16x16x32_bf16 v[10:13], v[168:171], v[212:215], v[10:13]
	v_mfma_f32_16x16x32_bf16 v[2:5], v[172:175], v[208:211], 0
	v_mfma_f32_16x16x32_bf16 v[2:5], v[176:179], v[212:215], v[2:5]
	s_setprio 0
	s_barrier
	s_add_i32 s64, 0, 0x18000
	v_add_u32_e32 v147, s64, v142
	s_add_i32 s65, 0, 0x1c000
	ds_read_b128 v[148:151], v147
	ds_read_b128 v[152:155], v147 offset:1024
	ds_read_b128 v[156:159], v147 offset:2048
	ds_read_b128 v[160:163], v147 offset:3072
	v_add_u32_e32 v147, s65, v142
	ds_read_b128 v[164:167], v147
	ds_read_b128 v[168:171], v147 offset:1024
	ds_read_b128 v[172:175], v147 offset:2048
	ds_read_b128 v[176:179], v147 offset:3072
	s_add_u32 s38, s38, 0x100000
	s_addc_u32 s39, s39, 0
	s_mov_b32 m0, s41
	ds_read_b128 v[180:183], v146 offset:32768
	ds_read_b128 v[184:187], v146 offset:33792
	ds_read_b128 v[188:191], v146 offset:34816
	ds_read_b128 v[192:195], v146 offset:35840
	ds_read_b128 v[196:199], v146 offset:36864
	ds_read_b128 v[200:203], v146 offset:37888
	ds_read_b128 v[208:211], v146 offset:38912
	ds_read_b128 v[212:215], v146 offset:39936
	global_load_lds_dwordx4 v130, s[38:39]
	s_mov_b32 m0, s42
	s_nop 0
	global_load_lds_dwordx4 v134, s[38:39]
	s_waitcnt vmcnt(8)
	s_waitcnt lgkmcnt(0)
	v_mfma_f32_16x16x32_bf16 v[126:129], v[148:151], v[180:183], v[126:129]
	v_mfma_f32_16x16x32_bf16 v[126:129], v[152:155], v[184:187], v[126:129]
	v_mfma_f32_16x16x32_bf16 v[122:125], v[156:159], v[180:183], v[122:125]
	v_mfma_f32_16x16x32_bf16 v[122:125], v[160:163], v[184:187], v[122:125]
	s_barrier
	s_setprio 1
	s_waitcnt lgkmcnt(0)
	v_mfma_f32_16x16x32_bf16 v[110:113], v[148:151], v[188:191], v[110:113]
	v_mfma_f32_16x16x32_bf16 v[110:113], v[152:155], v[192:195], v[110:113]
	v_mfma_f32_16x16x32_bf16 v[102:105], v[156:159], v[188:191], v[102:105]
	v_mfma_f32_16x16x32_bf16 v[102:105], v[160:163], v[192:195], v[102:105]
	v_mfma_f32_16x16x32_bf16 v[94:97], v[148:151], v[196:199], v[94:97]
	v_mfma_f32_16x16x32_bf16 v[94:97], v[152:155], v[200:203], v[94:97]
	v_mfma_f32_16x16x32_bf16 v[86:89], v[156:159], v[196:199], v[86:89]
	v_mfma_f32_16x16x32_bf16 v[86:89], v[160:163], v[200:203], v[86:89]
	v_mfma_f32_16x16x32_bf16 v[78:81], v[148:151], v[208:211], v[78:81]
	v_mfma_f32_16x16x32_bf16 v[78:81], v[152:155], v[212:215], v[78:81]
	v_mfma_f32_16x16x32_bf16 v[70:73], v[156:159], v[208:211], v[70:73]
	v_mfma_f32_16x16x32_bf16 v[70:73], v[160:163], v[212:215], v[70:73]
	s_setprio 0
	s_setprio 1
	v_mfma_f32_16x16x32_bf16 v[118:121], v[164:167], v[180:183], v[118:121]
	v_mfma_f32_16x16x32_bf16 v[118:121], v[168:171], v[184:187], v[118:121]
	v_mfma_f32_16x16x32_bf16 v[114:117], v[172:175], v[180:183], v[114:117]
	v_mfma_f32_16x16x32_bf16 v[114:117], v[176:179], v[184:187], v[114:117]
	v_mfma_f32_16x16x32_bf16 v[106:109], v[164:167], v[188:191], v[106:109]
	v_mfma_f32_16x16x32_bf16 v[106:109], v[168:171], v[192:195], v[106:109]
	v_mfma_f32_16x16x32_bf16 v[98:101], v[172:175], v[188:191], v[98:101]
	v_mfma_f32_16x16x32_bf16 v[98:101], v[176:179], v[192:195], v[98:101]
	v_mfma_f32_16x16x32_bf16 v[90:93], v[164:167], v[196:199], v[90:93]
	v_mfma_f32_16x16x32_bf16 v[90:93], v[168:171], v[200:203], v[90:93]
	v_mfma_f32_16x16x32_bf16 v[82:85], v[172:175], v[196:199], v[82:85]
	v_mfma_f32_16x16x32_bf16 v[82:85], v[176:179], v[200:203], v[82:85]
	v_mfma_f32_16x16x32_bf16 v[74:77], v[164:167], v[208:211], v[74:77]
	v_mfma_f32_16x16x32_bf16 v[74:77], v[168:171], v[212:215], v[74:77]
	v_mfma_f32_16x16x32_bf16 v[66:69], v[172:175], v[208:211], v[66:69]
	v_mfma_f32_16x16x32_bf16 v[66:69], v[176:179], v[212:215], v[66:69]
	s_setprio 0
	s_barrier
	s_add_i32 s38, s64, s33
	s_add_u32 s98, s2, s16
	s_addc_u32 s99, s3, s17
	s_mov_b32 m0, s38
	ds_read_b128 v[180:183], v146 offset:49152
	ds_read_b128 v[184:187], v146 offset:50176
	ds_read_b128 v[188:191], v146 offset:51200
	ds_read_b128 v[192:195], v146 offset:52224
	ds_read_b128 v[196:199], v146 offset:53248
	ds_read_b128 v[200:203], v146 offset:54272
	ds_read_b128 v[208:211], v146 offset:55296
	ds_read_b128 v[212:215], v146 offset:56320
	global_load_lds_dwordx4 v132, s[98:99]
	s_add_i32 m0, s38, 0x2000
	s_add_u32 s2, s2, 0x100080
	s_addc_u32 s3, s3, 0
	s_add_i32 s38, s65, s33
	global_load_lds_dwordx4 v136, s[98:99]
	s_mov_b32 m0, s38
	s_nop 0
	global_load_lds_dwordx4 v132, s[2:3]
	s_add_i32 m0, s38, 0x2000
	s_nop 0
	global_load_lds_dwordx4 v136, s[2:3]
	v_lshl_add_u64 v[204:205], v[218:219], 0, s[16:17]
	s_mov_b32 m0, s44
	s_nop 0
	global_load_lds_dwordx4 v[204:205], off
	v_lshl_add_u64 v[204:205], v[220:221], 0, s[16:17]
	s_mov_b32 m0, s45
	s_nop 0
	global_load_lds_dwordx4 v[204:205], off
	s_waitcnt vmcnt(8)
	s_waitcnt lgkmcnt(0)
	v_mfma_f32_16x16x32_bf16 v[62:65], v[148:151], v[180:183], v[62:65]
	v_mfma_f32_16x16x32_bf16 v[62:65], v[152:155], v[184:187], v[62:65]
	v_mfma_f32_16x16x32_bf16 v[54:57], v[156:159], v[180:183], v[54:57]
	v_mfma_f32_16x16x32_bf16 v[54:57], v[160:163], v[184:187], v[54:57]
	s_barrier
	s_setprio 1
	s_waitcnt lgkmcnt(0)
	v_mfma_f32_16x16x32_bf16 v[46:49], v[148:151], v[188:191], v[46:49]
	v_mfma_f32_16x16x32_bf16 v[46:49], v[152:155], v[192:195], v[46:49]
	v_mfma_f32_16x16x32_bf16 v[38:41], v[156:159], v[188:191], v[38:41]
	v_mfma_f32_16x16x32_bf16 v[38:41], v[160:163], v[192:195], v[38:41]
	v_mfma_f32_16x16x32_bf16 v[30:33], v[148:151], v[196:199], v[30:33]
	v_mfma_f32_16x16x32_bf16 v[30:33], v[152:155], v[200:203], v[30:33]
	v_mfma_f32_16x16x32_bf16 v[22:25], v[156:159], v[196:199], v[22:25]
	v_mfma_f32_16x16x32_bf16 v[22:25], v[160:163], v[200:203], v[22:25]
	v_mfma_f32_16x16x32_bf16 v[14:17], v[148:151], v[208:211], v[14:17]
	v_mfma_f32_16x16x32_bf16 v[14:17], v[152:155], v[212:215], v[14:17]
	v_mfma_f32_16x16x32_bf16 v[6:9], v[156:159], v[208:211], v[6:9]
	v_mfma_f32_16x16x32_bf16 v[6:9], v[160:163], v[212:215], v[6:9]
	s_setprio 0
	s_setprio 1
	v_mfma_f32_16x16x32_bf16 v[58:61], v[164:167], v[180:183], v[58:61]
	v_mfma_f32_16x16x32_bf16 v[58:61], v[168:171], v[184:187], v[58:61]
	v_mfma_f32_16x16x32_bf16 v[50:53], v[172:175], v[180:183], v[50:53]
	v_mfma_f32_16x16x32_bf16 v[50:53], v[176:179], v[184:187], v[50:53]
	v_mfma_f32_16x16x32_bf16 v[42:45], v[164:167], v[188:191], v[42:45]
	v_mfma_f32_16x16x32_bf16 v[42:45], v[168:171], v[192:195], v[42:45]
	v_mfma_f32_16x16x32_bf16 v[34:37], v[172:175], v[188:191], v[34:37]
	v_mfma_f32_16x16x32_bf16 v[34:37], v[176:179], v[192:195], v[34:37]
	v_mfma_f32_16x16x32_bf16 v[26:29], v[164:167], v[196:199], v[26:29]
	v_mfma_f32_16x16x32_bf16 v[26:29], v[168:171], v[200:203], v[26:29]
	v_mfma_f32_16x16x32_bf16 v[18:21], v[172:175], v[196:199], v[18:21]
	v_mfma_f32_16x16x32_bf16 v[18:21], v[176:179], v[200:203], v[18:21]
	v_mfma_f32_16x16x32_bf16 v[10:13], v[164:167], v[208:211], v[10:13]
	v_mfma_f32_16x16x32_bf16 v[10:13], v[168:171], v[212:215], v[10:13]
	v_mfma_f32_16x16x32_bf16 v[2:5], v[172:175], v[208:211], v[2:5]
	v_mfma_f32_16x16x32_bf16 v[2:5], v[176:179], v[212:215], v[2:5]
	s_setprio 0
	s_barrier
	s_add_u32 s36, s36, 0x100
	s_addc_u32 s37, s37, 0
	s_add_u32 s59, s59, 0x100
	s_addc_u32 s60, s60, 0
	s_cmp_ge_i32 s61, s35
	s_mov_b32 s2, s61
	s_cbranch_scc1 .Lkpeel_exit_4
.LBB0_800:
	ds_read_b128 v[148:151], v144
	ds_read_b128 v[152:155], v144 offset:1024
	ds_read_b128 v[156:159], v144 offset:2048
	ds_read_b128 v[160:163], v144 offset:3072
	ds_read_b128 v[164:167], v145
	ds_read_b128 v[168:171], v145 offset:1024
	ds_read_b128 v[172:175], v145 offset:2048
	ds_read_b128 v[176:179], v145 offset:3072
	s_add_i32 s61, s2, 2
	s_add_u32 s3, s36, 0xfff00080
	s_addc_u32 s38, s37, -1
	s_cmp_eq_u32 s58, s2
	s_cselect_b32 s2, s57, s59
	s_cselect_b32 s39, s0, s38
	s_cselect_b32 s38, s34, s3
	s_cselect_b32 s3, s56, s60
	s_add_i32 m0, s29, 0xc000
	ds_read_b128 v[180:183], v146
	ds_read_b128 v[184:187], v146 offset:1024
	ds_read_b128 v[188:191], v146 offset:2048
	ds_read_b128 v[192:195], v146 offset:3072
	ds_read_b128 v[196:199], v146 offset:4096
	ds_read_b128 v[200:203], v146 offset:5120
	ds_read_b128 v[208:211], v146 offset:6144
	ds_read_b128 v[212:215], v146 offset:7168
	global_load_lds_dwordx4 v138, s[36:37]
	s_add_i32 m0, s29, 0xe000
	s_nop 0
	global_load_lds_dwordx4 v140, s[36:37]
	s_waitcnt vmcnt(8)
	s_waitcnt lgkmcnt(0)
	v_mfma_f32_16x16x32_bf16 v[126:129], v[148:151], v[180:183], v[126:129]
	v_mfma_f32_16x16x32_bf16 v[126:129], v[152:155], v[184:187], v[126:129]
	v_mfma_f32_16x16x32_bf16 v[122:125], v[156:159], v[180:183], v[122:125]
	v_mfma_f32_16x16x32_bf16 v[122:125], v[160:163], v[184:187], v[122:125]
	s_barrier
	s_setprio 1
	s_waitcnt lgkmcnt(0)
	v_mfma_f32_16x16x32_bf16 v[110:113], v[148:151], v[188:191], v[110:113]
	v_mfma_f32_16x16x32_bf16 v[110:113], v[152:155], v[192:195], v[110:113]
	v_mfma_f32_16x16x32_bf16 v[102:105], v[156:159], v[188:191], v[102:105]
	v_mfma_f32_16x16x32_bf16 v[102:105], v[160:163], v[192:195], v[102:105]
	v_mfma_f32_16x16x32_bf16 v[94:97], v[148:151], v[196:199], v[94:97]
	v_mfma_f32_16x16x32_bf16 v[94:97], v[152:155], v[200:203], v[94:97]
	v_mfma_f32_16x16x32_bf16 v[86:89], v[156:159], v[196:199], v[86:89]
	v_mfma_f32_16x16x32_bf16 v[86:89], v[160:163], v[200:203], v[86:89]
	v_mfma_f32_16x16x32_bf16 v[78:81], v[148:151], v[208:211], v[78:81]
	v_mfma_f32_16x16x32_bf16 v[78:81], v[152:155], v[212:215], v[78:81]
	v_mfma_f32_16x16x32_bf16 v[70:73], v[156:159], v[208:211], v[70:73]
	v_mfma_f32_16x16x32_bf16 v[70:73], v[160:163], v[212:215], v[70:73]
	s_setprio 0
	s_setprio 1
	v_mfma_f32_16x16x32_bf16 v[118:121], v[164:167], v[180:183], v[118:121]
	v_mfma_f32_16x16x32_bf16 v[118:121], v[168:171], v[184:187], v[118:121]
	v_mfma_f32_16x16x32_bf16 v[114:117], v[172:175], v[180:183], v[114:117]
	v_mfma_f32_16x16x32_bf16 v[114:117], v[176:179], v[184:187], v[114:117]
	v_mfma_f32_16x16x32_bf16 v[106:109], v[164:167], v[188:191], v[106:109]
	v_mfma_f32_16x16x32_bf16 v[106:109], v[168:171], v[192:195], v[106:109]
	v_mfma_f32_16x16x32_bf16 v[98:101], v[172:175], v[188:191], v[98:101]
	v_mfma_f32_16x16x32_bf16 v[98:101], v[176:179], v[192:195], v[98:101]
	v_mfma_f32_16x16x32_bf16 v[90:93], v[164:167], v[196:199], v[90:93]
	v_mfma_f32_16x16x32_bf16 v[90:93], v[168:171], v[200:203], v[90:93]
	v_mfma_f32_16x16x32_bf16 v[82:85], v[172:175], v[196:199], v[82:85]
	v_mfma_f32_16x16x32_bf16 v[82:85], v[176:179], v[200:203], v[82:85]
	v_mfma_f32_16x16x32_bf16 v[74:77], v[164:167], v[208:211], v[74:77]
	v_mfma_f32_16x16x32_bf16 v[74:77], v[168:171], v[212:215], v[74:77]
	v_mfma_f32_16x16x32_bf16 v[66:69], v[172:175], v[208:211], v[66:69]
	v_mfma_f32_16x16x32_bf16 v[66:69], v[176:179], v[212:215], v[66:69]
	s_setprio 0
	s_barrier
	s_add_i32 s64, s50, s33
	s_mov_b32 m0, s64
	ds_read_b128 v[180:183], v146 offset:16384
	ds_read_b128 v[184:187], v146 offset:17408
	ds_read_b128 v[188:191], v146 offset:18432
	ds_read_b128 v[192:195], v146 offset:19456
	ds_read_b128 v[196:199], v146 offset:20480
	ds_read_b128 v[200:203], v146 offset:21504
	ds_read_b128 v[208:211], v146 offset:22528
	ds_read_b128 v[212:215], v146 offset:23552
	global_load_lds_dwordx4 v132, s[2:3]
	s_add_i32 m0, s64, 0x2000
	s_add_u32 s64, s2, 0x100000
	s_addc_u32 s65, s3, 0
	s_add_i32 s66, s51, s33
	global_load_lds_dwordx4 v136, s[2:3]
	s_mov_b32 m0, s66
	v_lshl_add_u64 v[220:221], s[38:39], 0, v[134:135]
	global_load_lds_dwordx4 v132, s[64:65]
	s_add_i32 m0, s66, 0x2000
	s_nop 0
	global_load_lds_dwordx4 v136, s[64:65]
	v_lshl_add_u64 v[218:219], s[38:39], 0, v[130:131]
	s_mov_b32 m0, s29
	s_nop 0
	global_load_lds_dwordx4 v130, s[38:39]
	s_mov_b32 m0, s31
	s_nop 0
	global_load_lds_dwordx4 v134, s[38:39]
	s_waitcnt vmcnt(8)
	s_waitcnt lgkmcnt(0)
	v_mfma_f32_16x16x32_bf16 v[62:65], v[148:151], v[180:183], v[62:65]
	v_mfma_f32_16x16x32_bf16 v[62:65], v[152:155], v[184:187], v[62:65]
	v_mfma_f32_16x16x32_bf16 v[54:57], v[156:159], v[180:183], v[54:57]
	v_mfma_f32_16x16x32_bf16 v[54:57], v[160:163], v[184:187], v[54:57]
	s_barrier
	s_setprio 1
	s_waitcnt lgkmcnt(0)
	v_mfma_f32_16x16x32_bf16 v[46:49], v[148:151], v[188:191], v[46:49]
	v_mfma_f32_16x16x32_bf16 v[46:49], v[152:155], v[192:195], v[46:49]
	v_mfma_f32_16x16x32_bf16 v[38:41], v[156:159], v[188:191], v[38:41]
	v_mfma_f32_16x16x32_bf16 v[38:41], v[160:163], v[192:195], v[38:41]
	v_mfma_f32_16x16x32_bf16 v[30:33], v[148:151], v[196:199], v[30:33]
	v_mfma_f32_16x16x32_bf16 v[30:33], v[152:155], v[200:203], v[30:33]
	v_mfma_f32_16x16x32_bf16 v[22:25], v[156:159], v[196:199], v[22:25]
	v_mfma_f32_16x16x32_bf16 v[22:25], v[160:163], v[200:203], v[22:25]
	v_mfma_f32_16x16x32_bf16 v[14:17], v[148:151], v[208:211], v[14:17]
	v_mfma_f32_16x16x32_bf16 v[14:17], v[152:155], v[212:215], v[14:17]
	v_mfma_f32_16x16x32_bf16 v[6:9], v[156:159], v[208:211], v[6:9]
	v_mfma_f32_16x16x32_bf16 v[6:9], v[160:163], v[212:215], v[6:9]
	s_setprio 0
	s_setprio 1
	v_mfma_f32_16x16x32_bf16 v[58:61], v[164:167], v[180:183], v[58:61]
	v_mfma_f32_16x16x32_bf16 v[58:61], v[168:171], v[184:187], v[58:61]
	v_mfma_f32_16x16x32_bf16 v[50:53], v[172:175], v[180:183], v[50:53]
	v_mfma_f32_16x16x32_bf16 v[50:53], v[176:179], v[184:187], v[50:53]
	v_mfma_f32_16x16x32_bf16 v[42:45], v[164:167], v[188:191], v[42:45]
	v_mfma_f32_16x16x32_bf16 v[42:45], v[168:171], v[192:195], v[42:45]
	v_mfma_f32_16x16x32_bf16 v[34:37], v[172:175], v[188:191], v[34:37]
	v_mfma_f32_16x16x32_bf16 v[34:37], v[176:179], v[192:195], v[34:37]
	v_mfma_f32_16x16x32_bf16 v[26:29], v[164:167], v[196:199], v[26:29]
	v_mfma_f32_16x16x32_bf16 v[26:29], v[168:171], v[200:203], v[26:29]
	v_mfma_f32_16x16x32_bf16 v[18:21], v[172:175], v[196:199], v[18:21]
	v_mfma_f32_16x16x32_bf16 v[18:21], v[176:179], v[200:203], v[18:21]
	v_mfma_f32_16x16x32_bf16 v[10:13], v[164:167], v[208:211], v[10:13]
	v_mfma_f32_16x16x32_bf16 v[10:13], v[168:171], v[212:215], v[10:13]
	v_mfma_f32_16x16x32_bf16 v[2:5], v[172:175], v[208:211], v[2:5]
	v_mfma_f32_16x16x32_bf16 v[2:5], v[176:179], v[212:215], v[2:5]
	s_setprio 0
	s_barrier
	s_add_i32 s64, 0, 0x18000
	v_add_u32_e32 v147, s64, v142
	s_add_i32 s65, 0, 0x1c000
	ds_read_b128 v[148:151], v147
	ds_read_b128 v[152:155], v147 offset:1024
	ds_read_b128 v[156:159], v147 offset:2048
	ds_read_b128 v[160:163], v147 offset:3072
	v_add_u32_e32 v147, s65, v142
	ds_read_b128 v[164:167], v147
	ds_read_b128 v[168:171], v147 offset:1024
	ds_read_b128 v[172:175], v147 offset:2048
	ds_read_b128 v[176:179], v147 offset:3072
	s_add_u32 s38, s38, 0x100000
	s_addc_u32 s39, s39, 0
	s_mov_b32 m0, s41
	ds_read_b128 v[180:183], v146 offset:32768
	ds_read_b128 v[184:187], v146 offset:33792
	ds_read_b128 v[188:191], v146 offset:34816
	ds_read_b128 v[192:195], v146 offset:35840
	ds_read_b128 v[196:199], v146 offset:36864
	ds_read_b128 v[200:203], v146 offset:37888
	ds_read_b128 v[208:211], v146 offset:38912
	ds_read_b128 v[212:215], v146 offset:39936
	global_load_lds_dwordx4 v130, s[38:39]
	s_mov_b32 m0, s42
	s_nop 0
	global_load_lds_dwordx4 v134, s[38:39]
	s_waitcnt vmcnt(8)
	s_waitcnt lgkmcnt(0)
	v_mfma_f32_16x16x32_bf16 v[126:129], v[148:151], v[180:183], v[126:129]
	v_mfma_f32_16x16x32_bf16 v[126:129], v[152:155], v[184:187], v[126:129]
	v_mfma_f32_16x16x32_bf16 v[122:125], v[156:159], v[180:183], v[122:125]
	v_mfma_f32_16x16x32_bf16 v[122:125], v[160:163], v[184:187], v[122:125]
	s_barrier
	s_setprio 1
	s_waitcnt lgkmcnt(0)
	v_mfma_f32_16x16x32_bf16 v[110:113], v[148:151], v[188:191], v[110:113]
	v_mfma_f32_16x16x32_bf16 v[110:113], v[152:155], v[192:195], v[110:113]
	v_mfma_f32_16x16x32_bf16 v[102:105], v[156:159], v[188:191], v[102:105]
	v_mfma_f32_16x16x32_bf16 v[102:105], v[160:163], v[192:195], v[102:105]
	v_mfma_f32_16x16x32_bf16 v[94:97], v[148:151], v[196:199], v[94:97]
	v_mfma_f32_16x16x32_bf16 v[94:97], v[152:155], v[200:203], v[94:97]
	v_mfma_f32_16x16x32_bf16 v[86:89], v[156:159], v[196:199], v[86:89]
	v_mfma_f32_16x16x32_bf16 v[86:89], v[160:163], v[200:203], v[86:89]
	v_mfma_f32_16x16x32_bf16 v[78:81], v[148:151], v[208:211], v[78:81]
	v_mfma_f32_16x16x32_bf16 v[78:81], v[152:155], v[212:215], v[78:81]
	v_mfma_f32_16x16x32_bf16 v[70:73], v[156:159], v[208:211], v[70:73]
	v_mfma_f32_16x16x32_bf16 v[70:73], v[160:163], v[212:215], v[70:73]
	s_setprio 0
	s_setprio 1
	v_mfma_f32_16x16x32_bf16 v[118:121], v[164:167], v[180:183], v[118:121]
	v_mfma_f32_16x16x32_bf16 v[118:121], v[168:171], v[184:187], v[118:121]
	v_mfma_f32_16x16x32_bf16 v[114:117], v[172:175], v[180:183], v[114:117]
	v_mfma_f32_16x16x32_bf16 v[114:117], v[176:179], v[184:187], v[114:117]
	v_mfma_f32_16x16x32_bf16 v[106:109], v[164:167], v[188:191], v[106:109]
	v_mfma_f32_16x16x32_bf16 v[106:109], v[168:171], v[192:195], v[106:109]
	v_mfma_f32_16x16x32_bf16 v[98:101], v[172:175], v[188:191], v[98:101]
	v_mfma_f32_16x16x32_bf16 v[98:101], v[176:179], v[192:195], v[98:101]
	v_mfma_f32_16x16x32_bf16 v[90:93], v[164:167], v[196:199], v[90:93]
	v_mfma_f32_16x16x32_bf16 v[90:93], v[168:171], v[200:203], v[90:93]
	v_mfma_f32_16x16x32_bf16 v[82:85], v[172:175], v[196:199], v[82:85]
	v_mfma_f32_16x16x32_bf16 v[82:85], v[176:179], v[200:203], v[82:85]
	v_mfma_f32_16x16x32_bf16 v[74:77], v[164:167], v[208:211], v[74:77]
	v_mfma_f32_16x16x32_bf16 v[74:77], v[168:171], v[212:215], v[74:77]
	v_mfma_f32_16x16x32_bf16 v[66:69], v[172:175], v[208:211], v[66:69]
	v_mfma_f32_16x16x32_bf16 v[66:69], v[176:179], v[212:215], v[66:69]
	s_setprio 0
	s_barrier
	s_add_i32 s38, s64, s33
	s_add_u32 s98, s2, s16
	s_addc_u32 s99, s3, s17
	s_mov_b32 m0, s38
	ds_read_b128 v[180:183], v146 offset:49152
	ds_read_b128 v[184:187], v146 offset:50176
	ds_read_b128 v[188:191], v146 offset:51200
	ds_read_b128 v[192:195], v146 offset:52224
	ds_read_b128 v[196:199], v146 offset:53248
	ds_read_b128 v[200:203], v146 offset:54272
	ds_read_b128 v[208:211], v146 offset:55296
	ds_read_b128 v[212:215], v146 offset:56320
	global_load_lds_dwordx4 v132, s[98:99]
	s_add_i32 m0, s38, 0x2000
	s_add_u32 s2, s2, 0x100080
	s_addc_u32 s3, s3, 0
	s_add_i32 s38, s65, s33
	global_load_lds_dwordx4 v136, s[98:99]
	s_mov_b32 m0, s38
	s_nop 0
	global_load_lds_dwordx4 v132, s[2:3]
	s_add_i32 m0, s38, 0x2000
	s_nop 0
	global_load_lds_dwordx4 v136, s[2:3]
	v_lshl_add_u64 v[204:205], v[218:219], 0, s[16:17]
	s_mov_b32 m0, s44
	s_nop 0
	global_load_lds_dwordx4 v[204:205], off
	v_lshl_add_u64 v[204:205], v[220:221], 0, s[16:17]
	s_mov_b32 m0, s45
	s_nop 0
	global_load_lds_dwordx4 v[204:205], off
	s_waitcnt vmcnt(8)
	s_waitcnt lgkmcnt(0)
	v_mfma_f32_16x16x32_bf16 v[62:65], v[148:151], v[180:183], v[62:65]
	v_mfma_f32_16x16x32_bf16 v[62:65], v[152:155], v[184:187], v[62:65]
	v_mfma_f32_16x16x32_bf16 v[54:57], v[156:159], v[180:183], v[54:57]
	v_mfma_f32_16x16x32_bf16 v[54:57], v[160:163], v[184:187], v[54:57]
	s_barrier
	s_setprio 1
	s_waitcnt lgkmcnt(0)
	v_mfma_f32_16x16x32_bf16 v[46:49], v[148:151], v[188:191], v[46:49]
	v_mfma_f32_16x16x32_bf16 v[46:49], v[152:155], v[192:195], v[46:49]
	v_mfma_f32_16x16x32_bf16 v[38:41], v[156:159], v[188:191], v[38:41]
	v_mfma_f32_16x16x32_bf16 v[38:41], v[160:163], v[192:195], v[38:41]
	v_mfma_f32_16x16x32_bf16 v[30:33], v[148:151], v[196:199], v[30:33]
	v_mfma_f32_16x16x32_bf16 v[30:33], v[152:155], v[200:203], v[30:33]
	v_mfma_f32_16x16x32_bf16 v[22:25], v[156:159], v[196:199], v[22:25]
	v_mfma_f32_16x16x32_bf16 v[22:25], v[160:163], v[200:203], v[22:25]
	v_mfma_f32_16x16x32_bf16 v[14:17], v[148:151], v[208:211], v[14:17]
	v_mfma_f32_16x16x32_bf16 v[14:17], v[152:155], v[212:215], v[14:17]
	v_mfma_f32_16x16x32_bf16 v[6:9], v[156:159], v[208:211], v[6:9]
	v_mfma_f32_16x16x32_bf16 v[6:9], v[160:163], v[212:215], v[6:9]
	s_setprio 0
	s_setprio 1
	v_mfma_f32_16x16x32_bf16 v[58:61], v[164:167], v[180:183], v[58:61]
	v_mfma_f32_16x16x32_bf16 v[58:61], v[168:171], v[184:187], v[58:61]
	v_mfma_f32_16x16x32_bf16 v[50:53], v[172:175], v[180:183], v[50:53]
	v_mfma_f32_16x16x32_bf16 v[50:53], v[176:179], v[184:187], v[50:53]
	v_mfma_f32_16x16x32_bf16 v[42:45], v[164:167], v[188:191], v[42:45]
	v_mfma_f32_16x16x32_bf16 v[42:45], v[168:171], v[192:195], v[42:45]
	v_mfma_f32_16x16x32_bf16 v[34:37], v[172:175], v[188:191], v[34:37]
	v_mfma_f32_16x16x32_bf16 v[34:37], v[176:179], v[192:195], v[34:37]
	v_mfma_f32_16x16x32_bf16 v[26:29], v[164:167], v[196:199], v[26:29]
	v_mfma_f32_16x16x32_bf16 v[26:29], v[168:171], v[200:203], v[26:29]
	v_mfma_f32_16x16x32_bf16 v[18:21], v[172:175], v[196:199], v[18:21]
	v_mfma_f32_16x16x32_bf16 v[18:21], v[176:179], v[200:203], v[18:21]
	v_mfma_f32_16x16x32_bf16 v[10:13], v[164:167], v[208:211], v[10:13]
	v_mfma_f32_16x16x32_bf16 v[10:13], v[168:171], v[212:215], v[10:13]
	v_mfma_f32_16x16x32_bf16 v[2:5], v[172:175], v[208:211], v[2:5]
	v_mfma_f32_16x16x32_bf16 v[2:5], v[176:179], v[212:215], v[2:5]
	s_setprio 0
	s_barrier
	s_add_u32 s36, s36, 0x100
	s_addc_u32 s37, s37, 0
	s_add_u32 s59, s59, 0x100
	s_addc_u32 s60, s60, 0
	s_cmp_ge_i32 s61, s35
	s_mov_b32 s2, s61
	s_cbranch_scc0 .LBB0_800

.LBB0_959:
	s_lshl_b32 s0, s16, 20
	s_and_b32 s0, s0, 0xff00000
	v_readlane_b32 s12, v248, 20
	v_readlane_b32 s13, v248, 21
	s_add_u32 s0, s12, s0
	s_addc_u32 s1, s13, 0
	s_lshr_b32 s12, s16, 13
	s_and_b32 s12, s12, 0x7ff80
	s_add_u32 s0, s0, s12
	s_addc_u32 s1, s1, 0
	s_lshl_b32 s13, s16, 12
	s_and_b32 s13, s13, 0xff00000
	v_readlane_b32 s24, v248, 51
	s_add_u32 s13, s24, s13
	v_readlane_b32 s24, v248, 53
	s_addc_u32 s24, s24, 0
	s_add_u32 s12, s13, s12
	s_addc_u32 s13, s24, 0
	s_cmp_lt_i32 s19, 1
	v_cmp_gt_i64_e64 s[16:17], s[16:17], -1
	s_cbranch_scc1 .LBB0_976
	s_and_b64 s[36:37], s[16:17], exec
	s_cselect_b32 s24, s1, s35
	s_cselect_b32 s53, s0, s34
	s_cselect_b32 s56, s13, s3
	s_cselect_b32 s57, s12, s2
	s_add_i32 s58, s19, -2
	s_add_u32 s34, s34, 0x80080
	s_addc_u32 s35, s35, 0
	s_add_u32 s59, s2, 0x100
	s_addc_u32 s60, s3, 0
	s_mov_b32 s2, 0
	s_add_i32 s61, s2, 2
	s_add_u32 s3, s34, 0xfff80080
	s_addc_u32 s36, s35, -1
	s_add_i32 s64, 0, 0x10000
	s_cmp_eq_u32 s58, s2
	s_cselect_b32 s37, s24, s36
	s_cselect_b32 s36, s53, s3
	v_add_u32_e32 v142, s64, v131
	s_cselect_b32 s3, s56, s60
	s_cselect_b32 s2, s57, s59
	s_add_i32 s66, 0, 0x14000
	ds_read_b128 v[148:151], v142
	ds_read_b128 v[152:155], v142 offset:1024
	ds_read_b128 v[156:159], v142 offset:2048
	ds_read_b128 v[160:163], v142 offset:3072
	v_add_u32_e32 v142, s66, v131
	ds_read_b128 v[188:191], v142
	ds_read_b128 v[192:195], v142 offset:1024
	ds_read_b128 v[196:199], v142 offset:2048
	ds_read_b128 v[200:203], v142 offset:3072
	s_add_i32 m0, s40, 0xc000
	ds_read_b128 v[204:207], v186
	ds_read_b128 v[208:211], v186 offset:1024
	ds_read_b128 v[212:215], v186 offset:2048
	ds_read_b128 v[216:219], v186 offset:3072
	ds_read_b128 v[220:223], v186 offset:4096
	ds_read_b128 v[224:227], v186 offset:5120
	ds_read_b128 v[228:231], v186 offset:6144
	ds_read_b128 v[232:235], v186 offset:7168
	global_load_lds_dwordx4 v144, s[34:35]
	s_add_i32 m0, s40, 0xe000
	s_nop 0
	global_load_lds_dwordx4 v146, s[34:35]
	s_waitcnt vmcnt(8)
	s_waitcnt lgkmcnt(0)
	v_mfma_i32_16x16x64_i8 v[126:129], v[148:151], v[204:207], 0
	v_mfma_i32_16x16x64_i8 v[126:129], v[152:155], v[208:211], v[126:129]
	v_mfma_i32_16x16x64_i8 v[122:125], v[156:159], v[204:207], 0
	v_mfma_i32_16x16x64_i8 v[122:125], v[160:163], v[208:211], v[122:125]
	s_barrier
	s_setprio 1
	s_waitcnt lgkmcnt(0)
	v_mfma_i32_16x16x64_i8 v[118:121], v[148:151], v[212:215], 0
	v_mfma_i32_16x16x64_i8 v[118:121], v[152:155], v[216:219], v[118:121]
	v_mfma_i32_16x16x64_i8 v[114:117], v[156:159], v[212:215], 0
	v_mfma_i32_16x16x64_i8 v[114:117], v[160:163], v[216:219], v[114:117]
	v_mfma_i32_16x16x64_i8 v[110:113], v[148:151], v[220:223], 0
	v_mfma_i32_16x16x64_i8 v[110:113], v[152:155], v[224:227], v[110:113]
	v_mfma_i32_16x16x64_i8 v[106:109], v[156:159], v[220:223], 0
	v_mfma_i32_16x16x64_i8 v[106:109], v[160:163], v[224:227], v[106:109]
	v_mfma_i32_16x16x64_i8 v[102:105], v[148:151], v[228:231], 0
	v_mfma_i32_16x16x64_i8 v[102:105], v[152:155], v[232:235], v[102:105]
	v_mfma_i32_16x16x64_i8 v[98:101], v[156:159], v[228:231], 0
	v_mfma_i32_16x16x64_i8 v[98:101], v[160:163], v[232:235], v[98:101]
	s_setprio 0
	s_setprio 1
	v_mfma_i32_16x16x64_i8 v[94:97], v[188:191], v[204:207], 0
	v_mfma_i32_16x16x64_i8 v[94:97], v[192:195], v[208:211], v[94:97]
	v_mfma_i32_16x16x64_i8 v[90:93], v[196:199], v[204:207], 0
	v_mfma_i32_16x16x64_i8 v[90:93], v[200:203], v[208:211], v[90:93]
	v_mfma_i32_16x16x64_i8 v[86:89], v[188:191], v[212:215], 0
	v_mfma_i32_16x16x64_i8 v[86:89], v[192:195], v[216:219], v[86:89]
	v_mfma_i32_16x16x64_i8 v[82:85], v[196:199], v[212:215], 0
	v_mfma_i32_16x16x64_i8 v[82:85], v[200:203], v[216:219], v[82:85]
	v_mfma_i32_16x16x64_i8 v[78:81], v[188:191], v[220:223], 0
	v_mfma_i32_16x16x64_i8 v[78:81], v[192:195], v[224:227], v[78:81]
	v_mfma_i32_16x16x64_i8 v[74:77], v[196:199], v[220:223], 0
	v_mfma_i32_16x16x64_i8 v[74:77], v[200:203], v[224:227], v[74:77]
	v_mfma_i32_16x16x64_i8 v[70:73], v[188:191], v[228:231], 0
	v_mfma_i32_16x16x64_i8 v[70:73], v[192:195], v[232:235], v[70:73]
	v_mfma_i32_16x16x64_i8 v[66:69], v[196:199], v[228:231], 0
	v_mfma_i32_16x16x64_i8 v[66:69], v[200:203], v[232:235], v[66:69]
	s_setprio 0
	s_barrier
	s_add_i32 s64, s64, s39
	s_mov_b32 m0, s64
	ds_read_b128 v[204:207], v186 offset:16384
	ds_read_b128 v[208:211], v186 offset:17408
	ds_read_b128 v[212:215], v186 offset:18432
	ds_read_b128 v[216:219], v186 offset:19456
	ds_read_b128 v[220:223], v186 offset:20480
	ds_read_b128 v[224:227], v186 offset:21504
	ds_read_b128 v[228:231], v186 offset:22528
	ds_read_b128 v[232:235], v186 offset:23552
	global_load_lds_dwordx4 v136, s[2:3]
	s_add_i32 m0, s64, 0x2000
	s_add_u32 s64, s2, 0x80000
	s_addc_u32 s65, s3, 0
	s_add_i32 s66, s66, s39
	global_load_lds_dwordx4 v140, s[2:3]
	s_mov_b32 m0, s66
	v_lshl_add_u64 v[242:243], s[36:37], 0, v[138:139]
	global_load_lds_dwordx4 v136, s[64:65]
	s_add_i32 m0, s66, 0x2000
	s_nop 0
	global_load_lds_dwordx4 v140, s[64:65]
	v_lshl_add_u64 v[240:241], s[36:37], 0, v[134:135]
	s_mov_b32 m0, s40
	s_nop 0
	global_load_lds_dwordx4 v134, s[36:37]
	s_mov_b32 m0, s41
	s_nop 0
	global_load_lds_dwordx4 v138, s[36:37]
	s_waitcnt vmcnt(8)
	s_waitcnt lgkmcnt(0)
	v_mfma_i32_16x16x64_i8 v[62:65], v[148:151], v[204:207], 0
	v_mfma_i32_16x16x64_i8 v[62:65], v[152:155], v[208:211], v[62:65]
	v_mfma_i32_16x16x64_i8 v[58:61], v[156:159], v[204:207], 0
	v_mfma_i32_16x16x64_i8 v[58:61], v[160:163], v[208:211], v[58:61]
	s_barrier
	s_setprio 1
	s_waitcnt lgkmcnt(0)
	v_mfma_i32_16x16x64_i8 v[54:57], v[148:151], v[212:215], 0
	v_mfma_i32_16x16x64_i8 v[54:57], v[152:155], v[216:219], v[54:57]
	v_mfma_i32_16x16x64_i8 v[50:53], v[156:159], v[212:215], 0
	v_mfma_i32_16x16x64_i8 v[50:53], v[160:163], v[216:219], v[50:53]
	v_mfma_i32_16x16x64_i8 v[46:49], v[148:151], v[220:223], 0
	v_mfma_i32_16x16x64_i8 v[46:49], v[152:155], v[224:227], v[46:49]
	v_mfma_i32_16x16x64_i8 v[42:45], v[156:159], v[220:223], 0
	v_mfma_i32_16x16x64_i8 v[42:45], v[160:163], v[224:227], v[42:45]
	v_mfma_i32_16x16x64_i8 v[38:41], v[148:151], v[228:231], 0
	v_mfma_i32_16x16x64_i8 v[38:41], v[152:155], v[232:235], v[38:41]
	v_mfma_i32_16x16x64_i8 v[34:37], v[156:159], v[228:231], 0
	v_mfma_i32_16x16x64_i8 v[34:37], v[160:163], v[232:235], v[34:37]
	s_setprio 0
	s_setprio 1
	v_mfma_i32_16x16x64_i8 v[30:33], v[188:191], v[204:207], 0
	v_mfma_i32_16x16x64_i8 v[30:33], v[192:195], v[208:211], v[30:33]
	v_mfma_i32_16x16x64_i8 v[26:29], v[196:199], v[204:207], 0
	v_mfma_i32_16x16x64_i8 v[26:29], v[200:203], v[208:211], v[26:29]
	v_mfma_i32_16x16x64_i8 v[22:25], v[188:191], v[212:215], 0
	v_mfma_i32_16x16x64_i8 v[22:25], v[192:195], v[216:219], v[22:25]
	v_mfma_i32_16x16x64_i8 v[18:21], v[196:199], v[212:215], 0
	v_mfma_i32_16x16x64_i8 v[18:21], v[200:203], v[216:219], v[18:21]
	v_mfma_i32_16x16x64_i8 v[14:17], v[188:191], v[220:223], 0
	v_mfma_i32_16x16x64_i8 v[14:17], v[192:195], v[224:227], v[14:17]
	v_mfma_i32_16x16x64_i8 v[10:13], v[196:199], v[220:223], 0
	v_mfma_i32_16x16x64_i8 v[10:13], v[200:203], v[224:227], v[10:13]
	v_mfma_i32_16x16x64_i8 v[6:9], v[188:191], v[228:231], 0
	v_mfma_i32_16x16x64_i8 v[6:9], v[192:195], v[232:235], v[6:9]
	v_mfma_i32_16x16x64_i8 v[2:5], v[196:199], v[228:231], 0
	v_mfma_i32_16x16x64_i8 v[2:5], v[200:203], v[232:235], v[2:5]
	s_setprio 0
	s_barrier
	s_add_i32 s64, 0, 0x18000
	v_add_u32_e32 v142, s64, v131
	s_add_i32 s65, 0, 0x1c000
	ds_read_b128 v[148:151], v142
	ds_read_b128 v[152:155], v142 offset:1024
	ds_read_b128 v[156:159], v142 offset:2048
	ds_read_b128 v[160:163], v142 offset:3072
	v_add_u32_e32 v142, s65, v131
	ds_read_b128 v[188:191], v142
	ds_read_b128 v[192:195], v142 offset:1024
	ds_read_b128 v[196:199], v142 offset:2048
	ds_read_b128 v[200:203], v142 offset:3072
	s_add_u32 s36, s36, 0x80000
	s_addc_u32 s37, s37, 0
	s_mov_b32 m0, s42
	ds_read_b128 v[204:207], v186 offset:32768
	ds_read_b128 v[208:211], v186 offset:33792
	ds_read_b128 v[212:215], v186 offset:34816
	ds_read_b128 v[216:219], v186 offset:35840
	ds_read_b128 v[220:223], v186 offset:36864
	ds_read_b128 v[224:227], v186 offset:37888
	ds_read_b128 v[228:231], v186 offset:38912
	ds_read_b128 v[232:235], v186 offset:39936
	global_load_lds_dwordx4 v134, s[36:37]
	s_mov_b32 m0, s43
	s_nop 0
	global_load_lds_dwordx4 v138, s[36:37]
	s_waitcnt vmcnt(8)
	s_waitcnt lgkmcnt(0)
	v_mfma_i32_16x16x64_i8 v[126:129], v[148:151], v[204:207], v[126:129]
	v_mfma_i32_16x16x64_i8 v[126:129], v[152:155], v[208:211], v[126:129]
	v_mfma_i32_16x16x64_i8 v[122:125], v[156:159], v[204:207], v[122:125]
	v_mfma_i32_16x16x64_i8 v[122:125], v[160:163], v[208:211], v[122:125]
	s_barrier
	s_setprio 1
	s_waitcnt lgkmcnt(0)
	v_mfma_i32_16x16x64_i8 v[118:121], v[148:151], v[212:215], v[118:121]
	v_mfma_i32_16x16x64_i8 v[118:121], v[152:155], v[216:219], v[118:121]
	v_mfma_i32_16x16x64_i8 v[114:117], v[156:159], v[212:215], v[114:117]
	v_mfma_i32_16x16x64_i8 v[114:117], v[160:163], v[216:219], v[114:117]
	v_mfma_i32_16x16x64_i8 v[110:113], v[148:151], v[220:223], v[110:113]
	v_mfma_i32_16x16x64_i8 v[110:113], v[152:155], v[224:227], v[110:113]
	v_mfma_i32_16x16x64_i8 v[106:109], v[156:159], v[220:223], v[106:109]
	v_mfma_i32_16x16x64_i8 v[106:109], v[160:163], v[224:227], v[106:109]
	v_mfma_i32_16x16x64_i8 v[102:105], v[148:151], v[228:231], v[102:105]
	v_mfma_i32_16x16x64_i8 v[102:105], v[152:155], v[232:235], v[102:105]
	v_mfma_i32_16x16x64_i8 v[98:101], v[156:159], v[228:231], v[98:101]
	v_mfma_i32_16x16x64_i8 v[98:101], v[160:163], v[232:235], v[98:101]
	s_setprio 0
	s_setprio 1
	v_mfma_i32_16x16x64_i8 v[94:97], v[188:191], v[204:207], v[94:97]
	v_mfma_i32_16x16x64_i8 v[94:97], v[192:195], v[208:211], v[94:97]
	v_mfma_i32_16x16x64_i8 v[90:93], v[196:199], v[204:207], v[90:93]
	v_mfma_i32_16x16x64_i8 v[90:93], v[200:203], v[208:211], v[90:93]
	v_mfma_i32_16x16x64_i8 v[86:89], v[188:191], v[212:215], v[86:89]
	v_mfma_i32_16x16x64_i8 v[86:89], v[192:195], v[216:219], v[86:89]
	v_mfma_i32_16x16x64_i8 v[82:85], v[196:199], v[212:215], v[82:85]
	v_mfma_i32_16x16x64_i8 v[82:85], v[200:203], v[216:219], v[82:85]
	v_mfma_i32_16x16x64_i8 v[78:81], v[188:191], v[220:223], v[78:81]
	v_mfma_i32_16x16x64_i8 v[78:81], v[192:195], v[224:227], v[78:81]
	v_mfma_i32_16x16x64_i8 v[74:77], v[196:199], v[220:223], v[74:77]
	v_mfma_i32_16x16x64_i8 v[74:77], v[200:203], v[224:227], v[74:77]
	v_mfma_i32_16x16x64_i8 v[70:73], v[188:191], v[228:231], v[70:73]
	v_mfma_i32_16x16x64_i8 v[70:73], v[192:195], v[232:235], v[70:73]
	v_mfma_i32_16x16x64_i8 v[66:69], v[196:199], v[228:231], v[66:69]
	v_mfma_i32_16x16x64_i8 v[66:69], v[200:203], v[232:235], v[66:69]
	s_setprio 0
	s_barrier
	s_add_i32 s36, s64, s39
	s_add_u32 s98, s2, s28
	s_addc_u32 s99, s3, s29
	s_mov_b32 m0, s36
	ds_read_b128 v[204:207], v186 offset:49152
	ds_read_b128 v[208:211], v186 offset:50176
	ds_read_b128 v[212:215], v186 offset:51200
	ds_read_b128 v[216:219], v186 offset:52224
	ds_read_b128 v[220:223], v186 offset:53248
	ds_read_b128 v[224:227], v186 offset:54272
	ds_read_b128 v[228:231], v186 offset:55296
	ds_read_b128 v[232:235], v186 offset:56320
	global_load_lds_dwordx4 v136, s[98:99]
	s_add_i32 m0, s36, 0x2000
	s_add_u32 s2, s2, 0x80080
	s_addc_u32 s3, s3, 0
	s_add_i32 s36, s65, s39
	global_load_lds_dwordx4 v140, s[98:99]
	s_mov_b32 m0, s36
	s_nop 0
	global_load_lds_dwordx4 v136, s[2:3]
	s_add_i32 m0, s36, 0x2000
	s_nop 0
	global_load_lds_dwordx4 v140, s[2:3]
	v_lshl_add_u64 v[236:237], v[240:241], 0, s[28:29]
	s_mov_b32 m0, s45
	s_nop 0
	global_load_lds_dwordx4 v[236:237], off
	v_lshl_add_u64 v[236:237], v[242:243], 0, s[28:29]
	s_mov_b32 m0, s52
	s_nop 0
	global_load_lds_dwordx4 v[236:237], off
	s_waitcnt vmcnt(8)
	s_waitcnt lgkmcnt(0)
	v_mfma_i32_16x16x64_i8 v[62:65], v[148:151], v[204:207], v[62:65]
	v_mfma_i32_16x16x64_i8 v[62:65], v[152:155], v[208:211], v[62:65]
	v_mfma_i32_16x16x64_i8 v[58:61], v[156:159], v[204:207], v[58:61]
	v_mfma_i32_16x16x64_i8 v[58:61], v[160:163], v[208:211], v[58:61]
	s_barrier
	s_setprio 1
	s_waitcnt lgkmcnt(0)
	v_mfma_i32_16x16x64_i8 v[54:57], v[148:151], v[212:215], v[54:57]
	v_mfma_i32_16x16x64_i8 v[54:57], v[152:155], v[216:219], v[54:57]
	v_mfma_i32_16x16x64_i8 v[50:53], v[156:159], v[212:215], v[50:53]
	v_mfma_i32_16x16x64_i8 v[50:53], v[160:163], v[216:219], v[50:53]
	v_mfma_i32_16x16x64_i8 v[46:49], v[148:151], v[220:223], v[46:49]
	v_mfma_i32_16x16x64_i8 v[46:49], v[152:155], v[224:227], v[46:49]
	v_mfma_i32_16x16x64_i8 v[42:45], v[156:159], v[220:223], v[42:45]
	v_mfma_i32_16x16x64_i8 v[42:45], v[160:163], v[224:227], v[42:45]
	v_mfma_i32_16x16x64_i8 v[38:41], v[148:151], v[228:231], v[38:41]
	v_mfma_i32_16x16x64_i8 v[38:41], v[152:155], v[232:235], v[38:41]
	v_mfma_i32_16x16x64_i8 v[34:37], v[156:159], v[228:231], v[34:37]
	v_mfma_i32_16x16x64_i8 v[34:37], v[160:163], v[232:235], v[34:37]
	s_setprio 0
	s_setprio 1
	v_mfma_i32_16x16x64_i8 v[30:33], v[188:191], v[204:207], v[30:33]
	v_mfma_i32_16x16x64_i8 v[30:33], v[192:195], v[208:211], v[30:33]
	v_mfma_i32_16x16x64_i8 v[26:29], v[196:199], v[204:207], v[26:29]
	v_mfma_i32_16x16x64_i8 v[26:29], v[200:203], v[208:211], v[26:29]
	v_mfma_i32_16x16x64_i8 v[22:25], v[188:191], v[212:215], v[22:25]
	v_mfma_i32_16x16x64_i8 v[22:25], v[192:195], v[216:219], v[22:25]
	v_mfma_i32_16x16x64_i8 v[18:21], v[196:199], v[212:215], v[18:21]
	v_mfma_i32_16x16x64_i8 v[18:21], v[200:203], v[216:219], v[18:21]
	v_mfma_i32_16x16x64_i8 v[14:17], v[188:191], v[220:223], v[14:17]
	v_mfma_i32_16x16x64_i8 v[14:17], v[192:195], v[224:227], v[14:17]
	v_mfma_i32_16x16x64_i8 v[10:13], v[196:199], v[220:223], v[10:13]
	v_mfma_i32_16x16x64_i8 v[10:13], v[200:203], v[224:227], v[10:13]
	v_mfma_i32_16x16x64_i8 v[6:9], v[188:191], v[228:231], v[6:9]
	v_mfma_i32_16x16x64_i8 v[6:9], v[192:195], v[232:235], v[6:9]
	v_mfma_i32_16x16x64_i8 v[2:5], v[196:199], v[228:231], v[2:5]
	v_mfma_i32_16x16x64_i8 v[2:5], v[200:203], v[232:235], v[2:5]
	s_setprio 0
	s_barrier
	s_add_u32 s34, s34, 0x100
	s_addc_u32 s35, s35, 0
	s_add_u32 s59, s59, 0x100
	s_addc_u32 s60, s60, 0
	s_cmp_ge_i32 s61, s19
	s_mov_b32 s2, s61
	s_cbranch_scc1 .Lkpeel_exit_5
.LBB0_961:
	s_add_i32 s61, s2, 2
	s_add_u32 s3, s34, 0xfff80080
	s_addc_u32 s36, s35, -1
	s_add_i32 s64, 0, 0x10000
	s_cmp_eq_u32 s58, s2
	s_cselect_b32 s37, s24, s36
	s_cselect_b32 s36, s53, s3
	v_add_u32_e32 v142, s64, v131
	s_cselect_b32 s3, s56, s60
	s_cselect_b32 s2, s57, s59
	s_add_i32 s66, 0, 0x14000
	ds_read_b128 v[148:151], v142
	ds_read_b128 v[152:155], v142 offset:1024
	ds_read_b128 v[156:159], v142 offset:2048
	ds_read_b128 v[160:163], v142 offset:3072
	v_add_u32_e32 v142, s66, v131
	ds_read_b128 v[188:191], v142
	ds_read_b128 v[192:195], v142 offset:1024
	ds_read_b128 v[196:199], v142 offset:2048
	ds_read_b128 v[200:203], v142 offset:3072
	s_add_i32 m0, s40, 0xc000
	ds_read_b128 v[204:207], v186
	ds_read_b128 v[208:211], v186 offset:1024
	ds_read_b128 v[212:215], v186 offset:2048
	ds_read_b128 v[216:219], v186 offset:3072
	ds_read_b128 v[220:223], v186 offset:4096
	ds_read_b128 v[224:227], v186 offset:5120
	ds_read_b128 v[228:231], v186 offset:6144
	ds_read_b128 v[232:235], v186 offset:7168
	global_load_lds_dwordx4 v144, s[34:35]
	s_add_i32 m0, s40, 0xe000
	s_nop 0
	global_load_lds_dwordx4 v146, s[34:35]
	s_waitcnt vmcnt(8)
	s_waitcnt lgkmcnt(0)
	v_mfma_i32_16x16x64_i8 v[126:129], v[148:151], v[204:207], v[126:129]
	v_mfma_i32_16x16x64_i8 v[126:129], v[152:155], v[208:211], v[126:129]
	v_mfma_i32_16x16x64_i8 v[122:125], v[156:159], v[204:207], v[122:125]
	v_mfma_i32_16x16x64_i8 v[122:125], v[160:163], v[208:211], v[122:125]
	s_barrier
	s_setprio 1
	s_waitcnt lgkmcnt(0)
	v_mfma_i32_16x16x64_i8 v[118:121], v[148:151], v[212:215], v[118:121]
	v_mfma_i32_16x16x64_i8 v[118:121], v[152:155], v[216:219], v[118:121]
	v_mfma_i32_16x16x64_i8 v[114:117], v[156:159], v[212:215], v[114:117]
	v_mfma_i32_16x16x64_i8 v[114:117], v[160:163], v[216:219], v[114:117]
	v_mfma_i32_16x16x64_i8 v[110:113], v[148:151], v[220:223], v[110:113]
	v_mfma_i32_16x16x64_i8 v[110:113], v[152:155], v[224:227], v[110:113]
	v_mfma_i32_16x16x64_i8 v[106:109], v[156:159], v[220:223], v[106:109]
	v_mfma_i32_16x16x64_i8 v[106:109], v[160:163], v[224:227], v[106:109]
	v_mfma_i32_16x16x64_i8 v[102:105], v[148:151], v[228:231], v[102:105]
	v_mfma_i32_16x16x64_i8 v[102:105], v[152:155], v[232:235], v[102:105]
	v_mfma_i32_16x16x64_i8 v[98:101], v[156:159], v[228:231], v[98:101]
	v_mfma_i32_16x16x64_i8 v[98:101], v[160:163], v[232:235], v[98:101]
	s_setprio 0
	s_setprio 1
	v_mfma_i32_16x16x64_i8 v[94:97], v[188:191], v[204:207], v[94:97]
	v_mfma_i32_16x16x64_i8 v[94:97], v[192:195], v[208:211], v[94:97]
	v_mfma_i32_16x16x64_i8 v[90:93], v[196:199], v[204:207], v[90:93]
	v_mfma_i32_16x16x64_i8 v[90:93], v[200:203], v[208:211], v[90:93]
	v_mfma_i32_16x16x64_i8 v[86:89], v[188:191], v[212:215], v[86:89]
	v_mfma_i32_16x16x64_i8 v[86:89], v[192:195], v[216:219], v[86:89]
	v_mfma_i32_16x16x64_i8 v[82:85], v[196:199], v[212:215], v[82:85]
	v_mfma_i32_16x16x64_i8 v[82:85], v[200:203], v[216:219], v[82:85]
	v_mfma_i32_16x16x64_i8 v[78:81], v[188:191], v[220:223], v[78:81]
	v_mfma_i32_16x16x64_i8 v[78:81], v[192:195], v[224:227], v[78:81]
	v_mfma_i32_16x16x64_i8 v[74:77], v[196:199], v[220:223], v[74:77]
	v_mfma_i32_16x16x64_i8 v[74:77], v[200:203], v[224:227], v[74:77]
	v_mfma_i32_16x16x64_i8 v[70:73], v[188:191], v[228:231], v[70:73]
	v_mfma_i32_16x16x64_i8 v[70:73], v[192:195], v[232:235], v[70:73]
	v_mfma_i32_16x16x64_i8 v[66:69], v[196:199], v[228:231], v[66:69]
	v_mfma_i32_16x16x64_i8 v[66:69], v[200:203], v[232:235], v[66:69]
	s_setprio 0
	s_barrier
	s_add_i32 s64, s64, s39
	s_mov_b32 m0, s64
	ds_read_b128 v[204:207], v186 offset:16384
	ds_read_b128 v[208:211], v186 offset:17408
	ds_read_b128 v[212:215], v186 offset:18432
	ds_read_b128 v[216:219], v186 offset:19456
	ds_read_b128 v[220:223], v186 offset:20480
	ds_read_b128 v[224:227], v186 offset:21504
	ds_read_b128 v[228:231], v186 offset:22528
	ds_read_b128 v[232:235], v186 offset:23552
	global_load_lds_dwordx4 v136, s[2:3]
	s_add_i32 m0, s64, 0x2000
	s_add_u32 s64, s2, 0x80000
	s_addc_u32 s65, s3, 0
	s_add_i32 s66, s66, s39
	global_load_lds_dwordx4 v140, s[2:3]
	s_mov_b32 m0, s66
	v_lshl_add_u64 v[242:243], s[36:37], 0, v[138:139]
	global_load_lds_dwordx4 v136, s[64:65]
	s_add_i32 m0, s66, 0x2000
	s_nop 0
	global_load_lds_dwordx4 v140, s[64:65]
	v_lshl_add_u64 v[240:241], s[36:37], 0, v[134:135]
	s_mov_b32 m0, s40
	s_nop 0
	global_load_lds_dwordx4 v134, s[36:37]
	s_mov_b32 m0, s41
	s_nop 0
	global_load_lds_dwordx4 v138, s[36:37]
	s_waitcnt vmcnt(8)
	s_waitcnt lgkmcnt(0)
	v_mfma_i32_16x16x64_i8 v[62:65], v[148:151], v[204:207], v[62:65]
	v_mfma_i32_16x16x64_i8 v[62:65], v[152:155], v[208:211], v[62:65]
	v_mfma_i32_16x16x64_i8 v[58:61], v[156:159], v[204:207], v[58:61]
	v_mfma_i32_16x16x64_i8 v[58:61], v[160:163], v[208:211], v[58:61]
	s_barrier
	s_setprio 1
	s_waitcnt lgkmcnt(0)
	v_mfma_i32_16x16x64_i8 v[54:57], v[148:151], v[212:215], v[54:57]
	v_mfma_i32_16x16x64_i8 v[54:57], v[152:155], v[216:219], v[54:57]
	v_mfma_i32_16x16x64_i8 v[50:53], v[156:159], v[212:215], v[50:53]
	v_mfma_i32_16x16x64_i8 v[50:53], v[160:163], v[216:219], v[50:53]
	v_mfma_i32_16x16x64_i8 v[46:49], v[148:151], v[220:223], v[46:49]
	v_mfma_i32_16x16x64_i8 v[46:49], v[152:155], v[224:227], v[46:49]
	v_mfma_i32_16x16x64_i8 v[42:45], v[156:159], v[220:223], v[42:45]
	v_mfma_i32_16x16x64_i8 v[42:45], v[160:163], v[224:227], v[42:45]
	v_mfma_i32_16x16x64_i8 v[38:41], v[148:151], v[228:231], v[38:41]
	v_mfma_i32_16x16x64_i8 v[38:41], v[152:155], v[232:235], v[38:41]
	v_mfma_i32_16x16x64_i8 v[34:37], v[156:159], v[228:231], v[34:37]
	v_mfma_i32_16x16x64_i8 v[34:37], v[160:163], v[232:235], v[34:37]
	s_setprio 0
	s_setprio 1
	v_mfma_i32_16x16x64_i8 v[30:33], v[188:191], v[204:207], v[30:33]
	v_mfma_i32_16x16x64_i8 v[30:33], v[192:195], v[208:211], v[30:33]
	v_mfma_i32_16x16x64_i8 v[26:29], v[196:199], v[204:207], v[26:29]
	v_mfma_i32_16x16x64_i8 v[26:29], v[200:203], v[208:211], v[26:29]
	v_mfma_i32_16x16x64_i8 v[22:25], v[188:191], v[212:215], v[22:25]
	v_mfma_i32_16x16x64_i8 v[22:25], v[192:195], v[216:219], v[22:25]
	v_mfma_i32_16x16x64_i8 v[18:21], v[196:199], v[212:215], v[18:21]
	v_mfma_i32_16x16x64_i8 v[18:21], v[200:203], v[216:219], v[18:21]
	v_mfma_i32_16x16x64_i8 v[14:17], v[188:191], v[220:223], v[14:17]
	v_mfma_i32_16x16x64_i8 v[14:17], v[192:195], v[224:227], v[14:17]
	v_mfma_i32_16x16x64_i8 v[10:13], v[196:199], v[220:223], v[10:13]
	v_mfma_i32_16x16x64_i8 v[10:13], v[200:203], v[224:227], v[10:13]
	v_mfma_i32_16x16x64_i8 v[6:9], v[188:191], v[228:231], v[6:9]
	v_mfma_i32_16x16x64_i8 v[6:9], v[192:195], v[232:235], v[6:9]
	v_mfma_i32_16x16x64_i8 v[2:5], v[196:199], v[228:231], v[2:5]
	v_mfma_i32_16x16x64_i8 v[2:5], v[200:203], v[232:235], v[2:5]
	s_setprio 0
	s_barrier
	s_add_i32 s64, 0, 0x18000
	v_add_u32_e32 v142, s64, v131
	s_add_i32 s65, 0, 0x1c000
	ds_read_b128 v[148:151], v142
	ds_read_b128 v[152:155], v142 offset:1024
	ds_read_b128 v[156:159], v142 offset:2048
	ds_read_b128 v[160:163], v142 offset:3072
	v_add_u32_e32 v142, s65, v131
	ds_read_b128 v[188:191], v142
	ds_read_b128 v[192:195], v142 offset:1024
	ds_read_b128 v[196:199], v142 offset:2048
	ds_read_b128 v[200:203], v142 offset:3072
	s_add_u32 s36, s36, 0x80000
	s_addc_u32 s37, s37, 0
	s_mov_b32 m0, s42
	ds_read_b128 v[204:207], v186 offset:32768
	ds_read_b128 v[208:211], v186 offset:33792
	ds_read_b128 v[212:215], v186 offset:34816
	ds_read_b128 v[216:219], v186 offset:35840
	ds_read_b128 v[220:223], v186 offset:36864
	ds_read_b128 v[224:227], v186 offset:37888
	ds_read_b128 v[228:231], v186 offset:38912
	ds_read_b128 v[232:235], v186 offset:39936
	global_load_lds_dwordx4 v134, s[36:37]
	s_mov_b32 m0, s43
	s_nop 0
	global_load_lds_dwordx4 v138, s[36:37]
	s_waitcnt vmcnt(8)
	s_waitcnt lgkmcnt(0)
	v_mfma_i32_16x16x64_i8 v[126:129], v[148:151], v[204:207], v[126:129]
	v_mfma_i32_16x16x64_i8 v[126:129], v[152:155], v[208:211], v[126:129]
	v_mfma_i32_16x16x64_i8 v[122:125], v[156:159], v[204:207], v[122:125]
	v_mfma_i32_16x16x64_i8 v[122:125], v[160:163], v[208:211], v[122:125]
	s_barrier
	s_setprio 1
	s_waitcnt lgkmcnt(0)
	v_mfma_i32_16x16x64_i8 v[118:121], v[148:151], v[212:215], v[118:121]
	v_mfma_i32_16x16x64_i8 v[118:121], v[152:155], v[216:219], v[118:121]
	v_mfma_i32_16x16x64_i8 v[114:117], v[156:159], v[212:215], v[114:117]
	v_mfma_i32_16x16x64_i8 v[114:117], v[160:163], v[216:219], v[114:117]
	v_mfma_i32_16x16x64_i8 v[110:113], v[148:151], v[220:223], v[110:113]
	v_mfma_i32_16x16x64_i8 v[110:113], v[152:155], v[224:227], v[110:113]
	v_mfma_i32_16x16x64_i8 v[106:109], v[156:159], v[220:223], v[106:109]
	v_mfma_i32_16x16x64_i8 v[106:109], v[160:163], v[224:227], v[106:109]
	v_mfma_i32_16x16x64_i8 v[102:105], v[148:151], v[228:231], v[102:105]
	v_mfma_i32_16x16x64_i8 v[102:105], v[152:155], v[232:235], v[102:105]
	v_mfma_i32_16x16x64_i8 v[98:101], v[156:159], v[228:231], v[98:101]
	v_mfma_i32_16x16x64_i8 v[98:101], v[160:163], v[232:235], v[98:101]
	s_setprio 0
	s_setprio 1
	v_mfma_i32_16x16x64_i8 v[94:97], v[188:191], v[204:207], v[94:97]
	v_mfma_i32_16x16x64_i8 v[94:97], v[192:195], v[208:211], v[94:97]
	v_mfma_i32_16x16x64_i8 v[90:93], v[196:199], v[204:207], v[90:93]
	v_mfma_i32_16x16x64_i8 v[90:93], v[200:203], v[208:211], v[90:93]
	v_mfma_i32_16x16x64_i8 v[86:89], v[188:191], v[212:215], v[86:89]
	v_mfma_i32_16x16x64_i8 v[86:89], v[192:195], v[216:219], v[86:89]
	v_mfma_i32_16x16x64_i8 v[82:85], v[196:199], v[212:215], v[82:85]
	v_mfma_i32_16x16x64_i8 v[82:85], v[200:203], v[216:219], v[82:85]
	v_mfma_i32_16x16x64_i8 v[78:81], v[188:191], v[220:223], v[78:81]
	v_mfma_i32_16x16x64_i8 v[78:81], v[192:195], v[224:227], v[78:81]
	v_mfma_i32_16x16x64_i8 v[74:77], v[196:199], v[220:223], v[74:77]
	v_mfma_i32_16x16x64_i8 v[74:77], v[200:203], v[224:227], v[74:77]
	v_mfma_i32_16x16x64_i8 v[70:73], v[188:191], v[228:231], v[70:73]
	v_mfma_i32_16x16x64_i8 v[70:73], v[192:195], v[232:235], v[70:73]
	v_mfma_i32_16x16x64_i8 v[66:69], v[196:199], v[228:231], v[66:69]
	v_mfma_i32_16x16x64_i8 v[66:69], v[200:203], v[232:235], v[66:69]
	s_setprio 0
	s_barrier
	s_add_i32 s36, s64, s39
	s_add_u32 s98, s2, s28
	s_addc_u32 s99, s3, s29
	s_mov_b32 m0, s36
	ds_read_b128 v[204:207], v186 offset:49152
	ds_read_b128 v[208:211], v186 offset:50176
	ds_read_b128 v[212:215], v186 offset:51200
	ds_read_b128 v[216:219], v186 offset:52224
	ds_read_b128 v[220:223], v186 offset:53248
	ds_read_b128 v[224:227], v186 offset:54272
	ds_read_b128 v[228:231], v186 offset:55296
	ds_read_b128 v[232:235], v186 offset:56320
	global_load_lds_dwordx4 v136, s[98:99]
	s_add_i32 m0, s36, 0x2000
	s_add_u32 s2, s2, 0x80080
	s_addc_u32 s3, s3, 0
	s_add_i32 s36, s65, s39
	global_load_lds_dwordx4 v140, s[98:99]
	s_mov_b32 m0, s36
	s_nop 0
	global_load_lds_dwordx4 v136, s[2:3]
	s_add_i32 m0, s36, 0x2000
	s_nop 0
	global_load_lds_dwordx4 v140, s[2:3]
	v_lshl_add_u64 v[236:237], v[240:241], 0, s[28:29]
	s_mov_b32 m0, s45
	s_nop 0
	global_load_lds_dwordx4 v[236:237], off
	v_lshl_add_u64 v[236:237], v[242:243], 0, s[28:29]
	s_mov_b32 m0, s52
	s_nop 0
	global_load_lds_dwordx4 v[236:237], off
	s_waitcnt vmcnt(8)
	s_waitcnt lgkmcnt(0)
	v_mfma_i32_16x16x64_i8 v[62:65], v[148:151], v[204:207], v[62:65]
	v_mfma_i32_16x16x64_i8 v[62:65], v[152:155], v[208:211], v[62:65]
	v_mfma_i32_16x16x64_i8 v[58:61], v[156:159], v[204:207], v[58:61]
	v_mfma_i32_16x16x64_i8 v[58:61], v[160:163], v[208:211], v[58:61]
	s_barrier
	s_setprio 1
	s_waitcnt lgkmcnt(0)
	v_mfma_i32_16x16x64_i8 v[54:57], v[148:151], v[212:215], v[54:57]
	v_mfma_i32_16x16x64_i8 v[54:57], v[152:155], v[216:219], v[54:57]
	v_mfma_i32_16x16x64_i8 v[50:53], v[156:159], v[212:215], v[50:53]
	v_mfma_i32_16x16x64_i8 v[50:53], v[160:163], v[216:219], v[50:53]
	v_mfma_i32_16x16x64_i8 v[46:49], v[148:151], v[220:223], v[46:49]
	v_mfma_i32_16x16x64_i8 v[46:49], v[152:155], v[224:227], v[46:49]
	v_mfma_i32_16x16x64_i8 v[42:45], v[156:159], v[220:223], v[42:45]
	v_mfma_i32_16x16x64_i8 v[42:45], v[160:163], v[224:227], v[42:45]
	v_mfma_i32_16x16x64_i8 v[38:41], v[148:151], v[228:231], v[38:41]
	v_mfma_i32_16x16x64_i8 v[38:41], v[152:155], v[232:235], v[38:41]
	v_mfma_i32_16x16x64_i8 v[34:37], v[156:159], v[228:231], v[34:37]
	v_mfma_i32_16x16x64_i8 v[34:37], v[160:163], v[232:235], v[34:37]
	s_setprio 0
	s_setprio 1
	v_mfma_i32_16x16x64_i8 v[30:33], v[188:191], v[204:207], v[30:33]
	v_mfma_i32_16x16x64_i8 v[30:33], v[192:195], v[208:211], v[30:33]
	v_mfma_i32_16x16x64_i8 v[26:29], v[196:199], v[204:207], v[26:29]
	v_mfma_i32_16x16x64_i8 v[26:29], v[200:203], v[208:211], v[26:29]
	v_mfma_i32_16x16x64_i8 v[22:25], v[188:191], v[212:215], v[22:25]
	v_mfma_i32_16x16x64_i8 v[22:25], v[192:195], v[216:219], v[22:25]
	v_mfma_i32_16x16x64_i8 v[18:21], v[196:199], v[212:215], v[18:21]
	v_mfma_i32_16x16x64_i8 v[18:21], v[200:203], v[216:219], v[18:21]
	v_mfma_i32_16x16x64_i8 v[14:17], v[188:191], v[220:223], v[14:17]
	v_mfma_i32_16x16x64_i8 v[14:17], v[192:195], v[224:227], v[14:17]
	v_mfma_i32_16x16x64_i8 v[10:13], v[196:199], v[220:223], v[10:13]
	v_mfma_i32_16x16x64_i8 v[10:13], v[200:203], v[224:227], v[10:13]
	v_mfma_i32_16x16x64_i8 v[6:9], v[188:191], v[228:231], v[6:9]
	v_mfma_i32_16x16x64_i8 v[6:9], v[192:195], v[232:235], v[6:9]
	v_mfma_i32_16x16x64_i8 v[2:5], v[196:199], v[228:231], v[2:5]
	v_mfma_i32_16x16x64_i8 v[2:5], v[200:203], v[232:235], v[2:5]
	s_setprio 0
	s_barrier
	s_add_u32 s34, s34, 0x100
	s_addc_u32 s35, s35, 0
	s_add_u32 s59, s59, 0x100
	s_addc_u32 s60, s60, 0
	s_cmp_ge_i32 s61, s19
	s_mov_b32 s2, s61
	s_cbranch_scc0 .LBB0_961

.LBB0_1126:
	s_cmp_lt_i32 s29, 1
	s_cbranch_scc1 .LBB0_1148
	s_add_i32 s18, s29, -2
	s_add_u32 s30, s30, 0x2b0080
	s_addc_u32 s31, s31, 0
	s_add_u32 s28, s2, 0x100
	s_addc_u32 s52, s3, 0
	s_mov_b32 s2, 0
	ds_read_b128 v[148:151], v145
	ds_read_b128 v[152:155], v145 offset:1024
	ds_read_b128 v[156:159], v145 offset:2048
	ds_read_b128 v[160:163], v145 offset:3072
	ds_read_b128 v[164:167], v146
	ds_read_b128 v[170:173], v146 offset:1024
	ds_read_b128 v[174:177], v146 offset:2048
	ds_read_b128 v[178:181], v146 offset:3072
	s_add_i32 s53, s2, 2
	s_add_u32 s3, s30, 0xffd50080
	s_addc_u32 s34, s31, -1
	s_cmp_eq_u32 s18, s2
	s_cselect_b32 s2, s26, s28
	s_cselect_b32 s35, s25, s34
	s_cselect_b32 s34, s24, s3
	s_cselect_b32 s3, s27, s52
	s_add_i32 m0, s37, 0xc000
	ds_read_b128 v[182:185], v147
	ds_read_b128 v[186:189], v147 offset:1024
	ds_read_b128 v[190:193], v147 offset:2048
	ds_read_b128 v[194:197], v147 offset:3072
	ds_read_b128 v[198:201], v147 offset:4096
	ds_read_b128 v[202:205], v147 offset:5120
	ds_read_b128 v[206:209], v147 offset:6144
	ds_read_b128 v[210:213], v147 offset:7168
	global_load_lds_dwordx4 v140, s[30:31]
	s_add_i32 m0, s37, 0xe000
	s_nop 0
	global_load_lds_dwordx4 v142, s[30:31]
	s_waitcnt vmcnt(8)
	s_waitcnt lgkmcnt(0)
	v_mfma_f32_16x16x32_bf16 v[124:127], v[148:151], v[182:185], 0
	v_mfma_f32_16x16x32_bf16 v[124:127], v[152:155], v[186:189], v[124:127]
	v_mfma_f32_16x16x32_bf16 v[120:123], v[156:159], v[182:185], 0
	v_mfma_f32_16x16x32_bf16 v[120:123], v[160:163], v[186:189], v[120:123]
	s_barrier
	s_setprio 1
	s_waitcnt lgkmcnt(0)
	v_mfma_f32_16x16x32_bf16 v[108:111], v[148:151], v[190:193], 0
	v_mfma_f32_16x16x32_bf16 v[108:111], v[152:155], v[194:197], v[108:111]
	v_mfma_f32_16x16x32_bf16 v[100:103], v[156:159], v[190:193], 0
	v_mfma_f32_16x16x32_bf16 v[100:103], v[160:163], v[194:197], v[100:103]
	v_mfma_f32_16x16x32_bf16 v[92:95], v[148:151], v[198:201], 0
	v_mfma_f32_16x16x32_bf16 v[92:95], v[152:155], v[202:205], v[92:95]
	v_mfma_f32_16x16x32_bf16 v[84:87], v[156:159], v[198:201], 0
	v_mfma_f32_16x16x32_bf16 v[84:87], v[160:163], v[202:205], v[84:87]
	v_mfma_f32_16x16x32_bf16 v[76:79], v[148:151], v[206:209], 0
	v_mfma_f32_16x16x32_bf16 v[76:79], v[152:155], v[210:213], v[76:79]
	v_mfma_f32_16x16x32_bf16 v[68:71], v[156:159], v[206:209], 0
	v_mfma_f32_16x16x32_bf16 v[68:71], v[160:163], v[210:213], v[68:71]
	s_setprio 0
	s_setprio 1
	v_mfma_f32_16x16x32_bf16 v[116:119], v[164:167], v[182:185], 0
	v_mfma_f32_16x16x32_bf16 v[116:119], v[170:173], v[186:189], v[116:119]
	v_mfma_f32_16x16x32_bf16 v[112:115], v[174:177], v[182:185], 0
	v_mfma_f32_16x16x32_bf16 v[112:115], v[178:181], v[186:189], v[112:115]
	v_mfma_f32_16x16x32_bf16 v[104:107], v[164:167], v[190:193], 0
	v_mfma_f32_16x16x32_bf16 v[104:107], v[170:173], v[194:197], v[104:107]
	v_mfma_f32_16x16x32_bf16 v[96:99], v[174:177], v[190:193], 0
	v_mfma_f32_16x16x32_bf16 v[96:99], v[178:181], v[194:197], v[96:99]
	v_mfma_f32_16x16x32_bf16 v[88:91], v[164:167], v[198:201], 0
	v_mfma_f32_16x16x32_bf16 v[88:91], v[170:173], v[202:205], v[88:91]
	v_mfma_f32_16x16x32_bf16 v[80:83], v[174:177], v[198:201], 0
	v_mfma_f32_16x16x32_bf16 v[80:83], v[178:181], v[202:205], v[80:83]
	v_mfma_f32_16x16x32_bf16 v[72:75], v[164:167], v[206:209], 0
	v_mfma_f32_16x16x32_bf16 v[72:75], v[170:173], v[210:213], v[72:75]
	v_mfma_f32_16x16x32_bf16 v[64:67], v[174:177], v[206:209], 0
	v_mfma_f32_16x16x32_bf16 v[64:67], v[178:181], v[210:213], v[64:67]
	s_setprio 0
	s_barrier
	s_add_i32 s56, s46, s33
	s_mov_b32 m0, s56
	ds_read_b128 v[182:185], v147 offset:16384
	ds_read_b128 v[186:189], v147 offset:17408
	ds_read_b128 v[190:193], v147 offset:18432
	ds_read_b128 v[194:197], v147 offset:19456
	ds_read_b128 v[198:201], v147 offset:20480
	ds_read_b128 v[202:205], v147 offset:21504
	ds_read_b128 v[206:209], v147 offset:22528
	ds_read_b128 v[210:213], v147 offset:23552
	global_load_lds_dwordx4 v134, s[2:3]
	s_add_i32 m0, s56, 0x2000
	s_add_u32 s56, s2, 0x2b0000
	s_addc_u32 s57, s3, 0
	s_add_i32 s58, s47, s33
	global_load_lds_dwordx4 v138, s[2:3]
	s_mov_b32 m0, s58
	v_lshl_add_u64 v[220:221], s[34:35], 0, v[136:137]
	global_load_lds_dwordx4 v134, s[56:57]
	s_add_i32 m0, s58, 0x2000
	s_nop 0
	global_load_lds_dwordx4 v138, s[56:57]
	v_lshl_add_u64 v[218:219], s[34:35], 0, v[128:129]
	s_mov_b32 m0, s37
	s_nop 0
	global_load_lds_dwordx4 v128, s[34:35]
	s_mov_b32 m0, s38
	s_nop 0
	global_load_lds_dwordx4 v136, s[34:35]
	s_waitcnt vmcnt(8)
	s_waitcnt lgkmcnt(0)
	v_mfma_f32_16x16x32_bf16 v[60:63], v[148:151], v[182:185], 0
	v_mfma_f32_16x16x32_bf16 v[60:63], v[152:155], v[186:189], v[60:63]
	v_mfma_f32_16x16x32_bf16 v[52:55], v[156:159], v[182:185], 0
	v_mfma_f32_16x16x32_bf16 v[52:55], v[160:163], v[186:189], v[52:55]
	s_barrier
	s_setprio 1
	s_waitcnt lgkmcnt(0)
	v_mfma_f32_16x16x32_bf16 v[44:47], v[148:151], v[190:193], 0
	v_mfma_f32_16x16x32_bf16 v[44:47], v[152:155], v[194:197], v[44:47]
	v_mfma_f32_16x16x32_bf16 v[36:39], v[156:159], v[190:193], 0
	v_mfma_f32_16x16x32_bf16 v[36:39], v[160:163], v[194:197], v[36:39]
	v_mfma_f32_16x16x32_bf16 v[28:31], v[148:151], v[198:201], 0
	v_mfma_f32_16x16x32_bf16 v[28:31], v[152:155], v[202:205], v[28:31]
	v_mfma_f32_16x16x32_bf16 v[20:23], v[156:159], v[198:201], 0
	v_mfma_f32_16x16x32_bf16 v[20:23], v[160:163], v[202:205], v[20:23]
	v_mfma_f32_16x16x32_bf16 v[12:15], v[148:151], v[206:209], 0
	v_mfma_f32_16x16x32_bf16 v[12:15], v[152:155], v[210:213], v[12:15]
	v_mfma_f32_16x16x32_bf16 v[4:7], v[156:159], v[206:209], 0
	v_mfma_f32_16x16x32_bf16 v[4:7], v[160:163], v[210:213], v[4:7]
	s_setprio 0
	s_setprio 1
	v_mfma_f32_16x16x32_bf16 v[56:59], v[164:167], v[182:185], 0
	v_mfma_f32_16x16x32_bf16 v[56:59], v[170:173], v[186:189], v[56:59]
	v_mfma_f32_16x16x32_bf16 v[48:51], v[174:177], v[182:185], 0
	v_mfma_f32_16x16x32_bf16 v[48:51], v[178:181], v[186:189], v[48:51]
	v_mfma_f32_16x16x32_bf16 v[40:43], v[164:167], v[190:193], 0
	v_mfma_f32_16x16x32_bf16 v[40:43], v[170:173], v[194:197], v[40:43]
	v_mfma_f32_16x16x32_bf16 v[32:35], v[174:177], v[190:193], 0
	v_mfma_f32_16x16x32_bf16 v[32:35], v[178:181], v[194:197], v[32:35]
	v_mfma_f32_16x16x32_bf16 v[24:27], v[164:167], v[198:201], 0
	v_mfma_f32_16x16x32_bf16 v[24:27], v[170:173], v[202:205], v[24:27]
	v_mfma_f32_16x16x32_bf16 v[16:19], v[174:177], v[198:201], 0
	v_mfma_f32_16x16x32_bf16 v[16:19], v[178:181], v[202:205], v[16:19]
	v_mfma_f32_16x16x32_bf16 v[8:11], v[164:167], v[206:209], 0
	v_mfma_f32_16x16x32_bf16 v[8:11], v[170:173], v[210:213], v[8:11]
	v_mfma_f32_16x16x32_bf16 v[0:3], v[174:177], v[206:209], 0
	v_mfma_f32_16x16x32_bf16 v[0:3], v[178:181], v[210:213], v[0:3]
	s_setprio 0
	s_barrier
	s_add_i32 s56, 0, 0x18000
	s_add_i32 s57, 0, 0x1c000
	v_add_u32_e32 v160, s56, v133
	v_add_u32_e32 v168, s57, v133
	ds_read_b128 v[148:151], v160
	ds_read_b128 v[152:155], v160 offset:1024
	ds_read_b128 v[156:159], v160 offset:2048
	ds_read_b128 v[160:163], v160 offset:3072
	ds_read_b128 v[164:167], v168
	ds_read_b128 v[170:173], v168 offset:1024
	ds_read_b128 v[174:177], v168 offset:2048
	ds_read_b128 v[178:181], v168 offset:3072
	s_add_u32 s34, s34, 0x2b0000
	s_addc_u32 s35, s35, 0
	s_mov_b32 m0, s39
	ds_read_b128 v[182:185], v147 offset:32768
	ds_read_b128 v[186:189], v147 offset:33792
	ds_read_b128 v[190:193], v147 offset:34816
	ds_read_b128 v[194:197], v147 offset:35840
	ds_read_b128 v[198:201], v147 offset:36864
	ds_read_b128 v[202:205], v147 offset:37888
	ds_read_b128 v[206:209], v147 offset:38912
	ds_read_b128 v[210:213], v147 offset:39936
	global_load_lds_dwordx4 v128, s[34:35]
	s_mov_b32 m0, s40
	s_nop 0
	global_load_lds_dwordx4 v136, s[34:35]
	s_waitcnt vmcnt(8)
	s_waitcnt lgkmcnt(0)
	v_mfma_f32_16x16x32_bf16 v[124:127], v[148:151], v[182:185], v[124:127]
	v_mfma_f32_16x16x32_bf16 v[124:127], v[152:155], v[186:189], v[124:127]
	v_mfma_f32_16x16x32_bf16 v[120:123], v[156:159], v[182:185], v[120:123]
	v_mfma_f32_16x16x32_bf16 v[120:123], v[160:163], v[186:189], v[120:123]
	s_barrier
	s_setprio 1
	s_waitcnt lgkmcnt(0)
	v_mfma_f32_16x16x32_bf16 v[108:111], v[148:151], v[190:193], v[108:111]
	v_mfma_f32_16x16x32_bf16 v[108:111], v[152:155], v[194:197], v[108:111]
	v_mfma_f32_16x16x32_bf16 v[100:103], v[156:159], v[190:193], v[100:103]
	v_mfma_f32_16x16x32_bf16 v[100:103], v[160:163], v[194:197], v[100:103]
	v_mfma_f32_16x16x32_bf16 v[92:95], v[148:151], v[198:201], v[92:95]
	v_mfma_f32_16x16x32_bf16 v[92:95], v[152:155], v[202:205], v[92:95]
	v_mfma_f32_16x16x32_bf16 v[84:87], v[156:159], v[198:201], v[84:87]
	v_mfma_f32_16x16x32_bf16 v[84:87], v[160:163], v[202:205], v[84:87]
	v_mfma_f32_16x16x32_bf16 v[76:79], v[148:151], v[206:209], v[76:79]
	v_mfma_f32_16x16x32_bf16 v[76:79], v[152:155], v[210:213], v[76:79]
	v_mfma_f32_16x16x32_bf16 v[68:71], v[156:159], v[206:209], v[68:71]
	v_mfma_f32_16x16x32_bf16 v[68:71], v[160:163], v[210:213], v[68:71]
	s_setprio 0
	s_setprio 1
	v_mfma_f32_16x16x32_bf16 v[116:119], v[164:167], v[182:185], v[116:119]
	v_mfma_f32_16x16x32_bf16 v[116:119], v[170:173], v[186:189], v[116:119]
	v_mfma_f32_16x16x32_bf16 v[112:115], v[174:177], v[182:185], v[112:115]
	v_mfma_f32_16x16x32_bf16 v[112:115], v[178:181], v[186:189], v[112:115]
	v_mfma_f32_16x16x32_bf16 v[104:107], v[164:167], v[190:193], v[104:107]
	v_mfma_f32_16x16x32_bf16 v[104:107], v[170:173], v[194:197], v[104:107]
	v_mfma_f32_16x16x32_bf16 v[96:99], v[174:177], v[190:193], v[96:99]
	v_mfma_f32_16x16x32_bf16 v[96:99], v[178:181], v[194:197], v[96:99]
	v_mfma_f32_16x16x32_bf16 v[88:91], v[164:167], v[198:201], v[88:91]
	v_mfma_f32_16x16x32_bf16 v[88:91], v[170:173], v[202:205], v[88:91]
	v_mfma_f32_16x16x32_bf16 v[80:83], v[174:177], v[198:201], v[80:83]
	v_mfma_f32_16x16x32_bf16 v[80:83], v[178:181], v[202:205], v[80:83]
	v_mfma_f32_16x16x32_bf16 v[72:75], v[164:167], v[206:209], v[72:75]
	v_mfma_f32_16x16x32_bf16 v[72:75], v[170:173], v[210:213], v[72:75]
	v_mfma_f32_16x16x32_bf16 v[64:67], v[174:177], v[206:209], v[64:67]
	v_mfma_f32_16x16x32_bf16 v[64:67], v[178:181], v[210:213], v[64:67]
	s_setprio 0
	s_barrier
	s_add_i32 s34, s56, s33
	s_add_u32 s98, s2, s6
	s_addc_u32 s99, s3, s7
	s_mov_b32 m0, s34
	ds_read_b128 v[182:185], v147 offset:49152
	ds_read_b128 v[186:189], v147 offset:50176
	ds_read_b128 v[190:193], v147 offset:51200
	ds_read_b128 v[194:197], v147 offset:52224
	ds_read_b128 v[198:201], v147 offset:53248
	ds_read_b128 v[202:205], v147 offset:54272
	ds_read_b128 v[206:209], v147 offset:55296
	ds_read_b128 v[210:213], v147 offset:56320
	global_load_lds_dwordx4 v134, s[98:99]
	s_add_i32 m0, s34, 0x2000
	s_add_u32 s2, s2, 0x2b0080
	s_addc_u32 s3, s3, 0
	s_add_i32 s34, s57, s33
	global_load_lds_dwordx4 v138, s[98:99]
	s_mov_b32 m0, s34
	s_nop 0
	global_load_lds_dwordx4 v134, s[2:3]
	s_add_i32 m0, s34, 0x2000
	s_nop 0
	global_load_lds_dwordx4 v138, s[2:3]
	v_lshl_add_u64 v[214:215], v[218:219], 0, s[6:7]
	s_mov_b32 m0, s42
	s_nop 0
	global_load_lds_dwordx4 v[214:215], off
	v_lshl_add_u64 v[214:215], v[220:221], 0, s[6:7]
	s_mov_b32 m0, s43
	s_nop 0
	global_load_lds_dwordx4 v[214:215], off
	s_waitcnt vmcnt(8)
	s_waitcnt lgkmcnt(0)
	v_mfma_f32_16x16x32_bf16 v[60:63], v[148:151], v[182:185], v[60:63]
	v_mfma_f32_16x16x32_bf16 v[60:63], v[152:155], v[186:189], v[60:63]
	v_mfma_f32_16x16x32_bf16 v[52:55], v[156:159], v[182:185], v[52:55]
	v_mfma_f32_16x16x32_bf16 v[52:55], v[160:163], v[186:189], v[52:55]
	s_barrier
	s_setprio 1
	s_waitcnt lgkmcnt(0)
	v_mfma_f32_16x16x32_bf16 v[44:47], v[148:151], v[190:193], v[44:47]
	v_mfma_f32_16x16x32_bf16 v[44:47], v[152:155], v[194:197], v[44:47]
	v_mfma_f32_16x16x32_bf16 v[36:39], v[156:159], v[190:193], v[36:39]
	v_mfma_f32_16x16x32_bf16 v[36:39], v[160:163], v[194:197], v[36:39]
	v_mfma_f32_16x16x32_bf16 v[28:31], v[148:151], v[198:201], v[28:31]
	v_mfma_f32_16x16x32_bf16 v[28:31], v[152:155], v[202:205], v[28:31]
	v_mfma_f32_16x16x32_bf16 v[20:23], v[156:159], v[198:201], v[20:23]
	v_mfma_f32_16x16x32_bf16 v[20:23], v[160:163], v[202:205], v[20:23]
	v_mfma_f32_16x16x32_bf16 v[12:15], v[148:151], v[206:209], v[12:15]
	v_mfma_f32_16x16x32_bf16 v[12:15], v[152:155], v[210:213], v[12:15]
	v_mfma_f32_16x16x32_bf16 v[4:7], v[156:159], v[206:209], v[4:7]
	v_mfma_f32_16x16x32_bf16 v[4:7], v[160:163], v[210:213], v[4:7]
	s_setprio 0
	s_setprio 1
	v_mfma_f32_16x16x32_bf16 v[56:59], v[164:167], v[182:185], v[56:59]
	v_mfma_f32_16x16x32_bf16 v[56:59], v[170:173], v[186:189], v[56:59]
	v_mfma_f32_16x16x32_bf16 v[48:51], v[174:177], v[182:185], v[48:51]
	v_mfma_f32_16x16x32_bf16 v[48:51], v[178:181], v[186:189], v[48:51]
	v_mfma_f32_16x16x32_bf16 v[40:43], v[164:167], v[190:193], v[40:43]
	v_mfma_f32_16x16x32_bf16 v[40:43], v[170:173], v[194:197], v[40:43]
	v_mfma_f32_16x16x32_bf16 v[32:35], v[174:177], v[190:193], v[32:35]
	v_mfma_f32_16x16x32_bf16 v[32:35], v[178:181], v[194:197], v[32:35]
	v_mfma_f32_16x16x32_bf16 v[24:27], v[164:167], v[198:201], v[24:27]
	v_mfma_f32_16x16x32_bf16 v[24:27], v[170:173], v[202:205], v[24:27]
	v_mfma_f32_16x16x32_bf16 v[16:19], v[174:177], v[198:201], v[16:19]
	v_mfma_f32_16x16x32_bf16 v[16:19], v[178:181], v[202:205], v[16:19]
	v_mfma_f32_16x16x32_bf16 v[8:11], v[164:167], v[206:209], v[8:11]
	v_mfma_f32_16x16x32_bf16 v[8:11], v[170:173], v[210:213], v[8:11]
	v_mfma_f32_16x16x32_bf16 v[0:3], v[174:177], v[206:209], v[0:3]
	v_mfma_f32_16x16x32_bf16 v[0:3], v[178:181], v[210:213], v[0:3]
	s_setprio 0
	s_barrier
	s_add_u32 s30, s30, 0x100
	s_addc_u32 s31, s31, 0
	s_add_u32 s28, s28, 0x100
	s_addc_u32 s52, s52, 0
	s_cmp_ge_i32 s53, s29
	s_mov_b32 s2, s53
	s_cbranch_scc1 .Lkpeel_exit_6
.LBB0_1128:
	ds_read_b128 v[148:151], v145
	ds_read_b128 v[152:155], v145 offset:1024
	ds_read_b128 v[156:159], v145 offset:2048
	ds_read_b128 v[160:163], v145 offset:3072
	ds_read_b128 v[164:167], v146
	ds_read_b128 v[170:173], v146 offset:1024
	ds_read_b128 v[174:177], v146 offset:2048
	ds_read_b128 v[178:181], v146 offset:3072
	s_add_i32 s53, s2, 2
	s_add_u32 s3, s30, 0xffd50080
	s_addc_u32 s34, s31, -1
	s_cmp_eq_u32 s18, s2
	s_cselect_b32 s2, s26, s28
	s_cselect_b32 s35, s25, s34
	s_cselect_b32 s34, s24, s3
	s_cselect_b32 s3, s27, s52
	s_add_i32 m0, s37, 0xc000
	ds_read_b128 v[182:185], v147
	ds_read_b128 v[186:189], v147 offset:1024
	ds_read_b128 v[190:193], v147 offset:2048
	ds_read_b128 v[194:197], v147 offset:3072
	ds_read_b128 v[198:201], v147 offset:4096
	ds_read_b128 v[202:205], v147 offset:5120
	ds_read_b128 v[206:209], v147 offset:6144
	ds_read_b128 v[210:213], v147 offset:7168
	global_load_lds_dwordx4 v140, s[30:31]
	s_add_i32 m0, s37, 0xe000
	s_nop 0
	global_load_lds_dwordx4 v142, s[30:31]
	s_waitcnt vmcnt(8)
	s_waitcnt lgkmcnt(0)
	v_mfma_f32_16x16x32_bf16 v[124:127], v[148:151], v[182:185], v[124:127]
	v_mfma_f32_16x16x32_bf16 v[124:127], v[152:155], v[186:189], v[124:127]
	v_mfma_f32_16x16x32_bf16 v[120:123], v[156:159], v[182:185], v[120:123]
	v_mfma_f32_16x16x32_bf16 v[120:123], v[160:163], v[186:189], v[120:123]
	s_barrier
	s_setprio 1
	s_waitcnt lgkmcnt(0)
	v_mfma_f32_16x16x32_bf16 v[108:111], v[148:151], v[190:193], v[108:111]
	v_mfma_f32_16x16x32_bf16 v[108:111], v[152:155], v[194:197], v[108:111]
	v_mfma_f32_16x16x32_bf16 v[100:103], v[156:159], v[190:193], v[100:103]
	v_mfma_f32_16x16x32_bf16 v[100:103], v[160:163], v[194:197], v[100:103]
	v_mfma_f32_16x16x32_bf16 v[92:95], v[148:151], v[198:201], v[92:95]
	v_mfma_f32_16x16x32_bf16 v[92:95], v[152:155], v[202:205], v[92:95]
	v_mfma_f32_16x16x32_bf16 v[84:87], v[156:159], v[198:201], v[84:87]
	v_mfma_f32_16x16x32_bf16 v[84:87], v[160:163], v[202:205], v[84:87]
	v_mfma_f32_16x16x32_bf16 v[76:79], v[148:151], v[206:209], v[76:79]
	v_mfma_f32_16x16x32_bf16 v[76:79], v[152:155], v[210:213], v[76:79]
	v_mfma_f32_16x16x32_bf16 v[68:71], v[156:159], v[206:209], v[68:71]
	v_mfma_f32_16x16x32_bf16 v[68:71], v[160:163], v[210:213], v[68:71]
	s_setprio 0
	s_setprio 1
	v_mfma_f32_16x16x32_bf16 v[116:119], v[164:167], v[182:185], v[116:119]
	v_mfma_f32_16x16x32_bf16 v[116:119], v[170:173], v[186:189], v[116:119]
	v_mfma_f32_16x16x32_bf16 v[112:115], v[174:177], v[182:185], v[112:115]
	v_mfma_f32_16x16x32_bf16 v[112:115], v[178:181], v[186:189], v[112:115]
	v_mfma_f32_16x16x32_bf16 v[104:107], v[164:167], v[190:193], v[104:107]
	v_mfma_f32_16x16x32_bf16 v[104:107], v[170:173], v[194:197], v[104:107]
	v_mfma_f32_16x16x32_bf16 v[96:99], v[174:177], v[190:193], v[96:99]
	v_mfma_f32_16x16x32_bf16 v[96:99], v[178:181], v[194:197], v[96:99]
	v_mfma_f32_16x16x32_bf16 v[88:91], v[164:167], v[198:201], v[88:91]
	v_mfma_f32_16x16x32_bf16 v[88:91], v[170:173], v[202:205], v[88:91]
	v_mfma_f32_16x16x32_bf16 v[80:83], v[174:177], v[198:201], v[80:83]
	v_mfma_f32_16x16x32_bf16 v[80:83], v[178:181], v[202:205], v[80:83]
	v_mfma_f32_16x16x32_bf16 v[72:75], v[164:167], v[206:209], v[72:75]
	v_mfma_f32_16x16x32_bf16 v[72:75], v[170:173], v[210:213], v[72:75]
	v_mfma_f32_16x16x32_bf16 v[64:67], v[174:177], v[206:209], v[64:67]
	v_mfma_f32_16x16x32_bf16 v[64:67], v[178:181], v[210:213], v[64:67]
	s_setprio 0
	s_barrier
	s_add_i32 s56, s46, s33
	s_mov_b32 m0, s56
	ds_read_b128 v[182:185], v147 offset:16384
	ds_read_b128 v[186:189], v147 offset:17408
	ds_read_b128 v[190:193], v147 offset:18432
	ds_read_b128 v[194:197], v147 offset:19456
	ds_read_b128 v[198:201], v147 offset:20480
	ds_read_b128 v[202:205], v147 offset:21504
	ds_read_b128 v[206:209], v147 offset:22528
	ds_read_b128 v[210:213], v147 offset:23552
	global_load_lds_dwordx4 v134, s[2:3]
	s_add_i32 m0, s56, 0x2000
	s_add_u32 s56, s2, 0x2b0000
	s_addc_u32 s57, s3, 0
	s_add_i32 s58, s47, s33
	global_load_lds_dwordx4 v138, s[2:3]
	s_mov_b32 m0, s58
	v_lshl_add_u64 v[220:221], s[34:35], 0, v[136:137]
	global_load_lds_dwordx4 v134, s[56:57]
	s_add_i32 m0, s58, 0x2000
	s_nop 0
	global_load_lds_dwordx4 v138, s[56:57]
	v_lshl_add_u64 v[218:219], s[34:35], 0, v[128:129]
	s_mov_b32 m0, s37
	s_nop 0
	global_load_lds_dwordx4 v128, s[34:35]
	s_mov_b32 m0, s38
	s_nop 0
	global_load_lds_dwordx4 v136, s[34:35]
	s_waitcnt vmcnt(8)
	s_waitcnt lgkmcnt(0)
	v_mfma_f32_16x16x32_bf16 v[60:63], v[148:151], v[182:185], v[60:63]
	v_mfma_f32_16x16x32_bf16 v[60:63], v[152:155], v[186:189], v[60:63]
	v_mfma_f32_16x16x32_bf16 v[52:55], v[156:159], v[182:185], v[52:55]
	v_mfma_f32_16x16x32_bf16 v[52:55], v[160:163], v[186:189], v[52:55]
	s_barrier
	s_setprio 1
	s_waitcnt lgkmcnt(0)
	v_mfma_f32_16x16x32_bf16 v[44:47], v[148:151], v[190:193], v[44:47]
	v_mfma_f32_16x16x32_bf16 v[44:47], v[152:155], v[194:197], v[44:47]
	v_mfma_f32_16x16x32_bf16 v[36:39], v[156:159], v[190:193], v[36:39]
	v_mfma_f32_16x16x32_bf16 v[36:39], v[160:163], v[194:197], v[36:39]
	v_mfma_f32_16x16x32_bf16 v[28:31], v[148:151], v[198:201], v[28:31]
	v_mfma_f32_16x16x32_bf16 v[28:31], v[152:155], v[202:205], v[28:31]
	v_mfma_f32_16x16x32_bf16 v[20:23], v[156:159], v[198:201], v[20:23]
	v_mfma_f32_16x16x32_bf16 v[20:23], v[160:163], v[202:205], v[20:23]
	v_mfma_f32_16x16x32_bf16 v[12:15], v[148:151], v[206:209], v[12:15]
	v_mfma_f32_16x16x32_bf16 v[12:15], v[152:155], v[210:213], v[12:15]
	v_mfma_f32_16x16x32_bf16 v[4:7], v[156:159], v[206:209], v[4:7]
	v_mfma_f32_16x16x32_bf16 v[4:7], v[160:163], v[210:213], v[4:7]
	s_setprio 0
	s_setprio 1
	v_mfma_f32_16x16x32_bf16 v[56:59], v[164:167], v[182:185], v[56:59]
	v_mfma_f32_16x16x32_bf16 v[56:59], v[170:173], v[186:189], v[56:59]
	v_mfma_f32_16x16x32_bf16 v[48:51], v[174:177], v[182:185], v[48:51]
	v_mfma_f32_16x16x32_bf16 v[48:51], v[178:181], v[186:189], v[48:51]
	v_mfma_f32_16x16x32_bf16 v[40:43], v[164:167], v[190:193], v[40:43]
	v_mfma_f32_16x16x32_bf16 v[40:43], v[170:173], v[194:197], v[40:43]
	v_mfma_f32_16x16x32_bf16 v[32:35], v[174:177], v[190:193], v[32:35]
	v_mfma_f32_16x16x32_bf16 v[32:35], v[178:181], v[194:197], v[32:35]
	v_mfma_f32_16x16x32_bf16 v[24:27], v[164:167], v[198:201], v[24:27]
	v_mfma_f32_16x16x32_bf16 v[24:27], v[170:173], v[202:205], v[24:27]
	v_mfma_f32_16x16x32_bf16 v[16:19], v[174:177], v[198:201], v[16:19]
	v_mfma_f32_16x16x32_bf16 v[16:19], v[178:181], v[202:205], v[16:19]
	v_mfma_f32_16x16x32_bf16 v[8:11], v[164:167], v[206:209], v[8:11]
	v_mfma_f32_16x16x32_bf16 v[8:11], v[170:173], v[210:213], v[8:11]
	v_mfma_f32_16x16x32_bf16 v[0:3], v[174:177], v[206:209], v[0:3]
	v_mfma_f32_16x16x32_bf16 v[0:3], v[178:181], v[210:213], v[0:3]
	s_setprio 0
	s_barrier
	s_add_i32 s56, 0, 0x18000
	s_add_i32 s57, 0, 0x1c000
	v_add_u32_e32 v160, s56, v133
	v_add_u32_e32 v168, s57, v133
	ds_read_b128 v[148:151], v160
	ds_read_b128 v[152:155], v160 offset:1024
	ds_read_b128 v[156:159], v160 offset:2048
	ds_read_b128 v[160:163], v160 offset:3072
	ds_read_b128 v[164:167], v168
	ds_read_b128 v[170:173], v168 offset:1024
	ds_read_b128 v[174:177], v168 offset:2048
	ds_read_b128 v[178:181], v168 offset:3072
	s_add_u32 s34, s34, 0x2b0000
	s_addc_u32 s35, s35, 0
	s_mov_b32 m0, s39
	ds_read_b128 v[182:185], v147 offset:32768
	ds_read_b128 v[186:189], v147 offset:33792
	ds_read_b128 v[190:193], v147 offset:34816
	ds_read_b128 v[194:197], v147 offset:35840
	ds_read_b128 v[198:201], v147 offset:36864
	ds_read_b128 v[202:205], v147 offset:37888
	ds_read_b128 v[206:209], v147 offset:38912
	ds_read_b128 v[210:213], v147 offset:39936
	global_load_lds_dwordx4 v128, s[34:35]
	s_mov_b32 m0, s40
	s_nop 0
	global_load_lds_dwordx4 v136, s[34:35]
	s_waitcnt vmcnt(8)
	s_waitcnt lgkmcnt(0)
	v_mfma_f32_16x16x32_bf16 v[124:127], v[148:151], v[182:185], v[124:127]
	v_mfma_f32_16x16x32_bf16 v[124:127], v[152:155], v[186:189], v[124:127]
	v_mfma_f32_16x16x32_bf16 v[120:123], v[156:159], v[182:185], v[120:123]
	v_mfma_f32_16x16x32_bf16 v[120:123], v[160:163], v[186:189], v[120:123]
	s_barrier
	s_setprio 1
	s_waitcnt lgkmcnt(0)
	v_mfma_f32_16x16x32_bf16 v[108:111], v[148:151], v[190:193], v[108:111]
	v_mfma_f32_16x16x32_bf16 v[108:111], v[152:155], v[194:197], v[108:111]
	v_mfma_f32_16x16x32_bf16 v[100:103], v[156:159], v[190:193], v[100:103]
	v_mfma_f32_16x16x32_bf16 v[100:103], v[160:163], v[194:197], v[100:103]
	v_mfma_f32_16x16x32_bf16 v[92:95], v[148:151], v[198:201], v[92:95]
	v_mfma_f32_16x16x32_bf16 v[92:95], v[152:155], v[202:205], v[92:95]
	v_mfma_f32_16x16x32_bf16 v[84:87], v[156:159], v[198:201], v[84:87]
	v_mfma_f32_16x16x32_bf16 v[84:87], v[160:163], v[202:205], v[84:87]
	v_mfma_f32_16x16x32_bf16 v[76:79], v[148:151], v[206:209], v[76:79]
	v_mfma_f32_16x16x32_bf16 v[76:79], v[152:155], v[210:213], v[76:79]
	v_mfma_f32_16x16x32_bf16 v[68:71], v[156:159], v[206:209], v[68:71]
	v_mfma_f32_16x16x32_bf16 v[68:71], v[160:163], v[210:213], v[68:71]
	s_setprio 0
	s_setprio 1
	v_mfma_f32_16x16x32_bf16 v[116:119], v[164:167], v[182:185], v[116:119]
	v_mfma_f32_16x16x32_bf16 v[116:119], v[170:173], v[186:189], v[116:119]
	v_mfma_f32_16x16x32_bf16 v[112:115], v[174:177], v[182:185], v[112:115]
	v_mfma_f32_16x16x32_bf16 v[112:115], v[178:181], v[186:189], v[112:115]
	v_mfma_f32_16x16x32_bf16 v[104:107], v[164:167], v[190:193], v[104:107]
	v_mfma_f32_16x16x32_bf16 v[104:107], v[170:173], v[194:197], v[104:107]
	v_mfma_f32_16x16x32_bf16 v[96:99], v[174:177], v[190:193], v[96:99]
	v_mfma_f32_16x16x32_bf16 v[96:99], v[178:181], v[194:197], v[96:99]
	v_mfma_f32_16x16x32_bf16 v[88:91], v[164:167], v[198:201], v[88:91]
	v_mfma_f32_16x16x32_bf16 v[88:91], v[170:173], v[202:205], v[88:91]
	v_mfma_f32_16x16x32_bf16 v[80:83], v[174:177], v[198:201], v[80:83]
	v_mfma_f32_16x16x32_bf16 v[80:83], v[178:181], v[202:205], v[80:83]
	v_mfma_f32_16x16x32_bf16 v[72:75], v[164:167], v[206:209], v[72:75]
	v_mfma_f32_16x16x32_bf16 v[72:75], v[170:173], v[210:213], v[72:75]
	v_mfma_f32_16x16x32_bf16 v[64:67], v[174:177], v[206:209], v[64:67]
	v_mfma_f32_16x16x32_bf16 v[64:67], v[178:181], v[210:213], v[64:67]
	s_setprio 0
	s_barrier
	s_add_i32 s34, s56, s33
	s_add_u32 s98, s2, s6
	s_addc_u32 s99, s3, s7
	s_mov_b32 m0, s34
	ds_read_b128 v[182:185], v147 offset:49152
	ds_read_b128 v[186:189], v147 offset:50176
	ds_read_b128 v[190:193], v147 offset:51200
	ds_read_b128 v[194:197], v147 offset:52224
	ds_read_b128 v[198:201], v147 offset:53248
	ds_read_b128 v[202:205], v147 offset:54272
	ds_read_b128 v[206:209], v147 offset:55296
	ds_read_b128 v[210:213], v147 offset:56320
	global_load_lds_dwordx4 v134, s[98:99]
	s_add_i32 m0, s34, 0x2000
	s_add_u32 s2, s2, 0x2b0080
	s_addc_u32 s3, s3, 0
	s_add_i32 s34, s57, s33
	global_load_lds_dwordx4 v138, s[98:99]
	s_mov_b32 m0, s34
	s_nop 0
	global_load_lds_dwordx4 v134, s[2:3]
	s_add_i32 m0, s34, 0x2000
	s_nop 0
	global_load_lds_dwordx4 v138, s[2:3]
	v_lshl_add_u64 v[214:215], v[218:219], 0, s[6:7]
	s_mov_b32 m0, s42
	s_nop 0
	global_load_lds_dwordx4 v[214:215], off
	v_lshl_add_u64 v[214:215], v[220:221], 0, s[6:7]
	s_mov_b32 m0, s43
	s_nop 0
	global_load_lds_dwordx4 v[214:215], off
	s_waitcnt vmcnt(8)
	s_waitcnt lgkmcnt(0)
	v_mfma_f32_16x16x32_bf16 v[60:63], v[148:151], v[182:185], v[60:63]
	v_mfma_f32_16x16x32_bf16 v[60:63], v[152:155], v[186:189], v[60:63]
	v_mfma_f32_16x16x32_bf16 v[52:55], v[156:159], v[182:185], v[52:55]
	v_mfma_f32_16x16x32_bf16 v[52:55], v[160:163], v[186:189], v[52:55]
	s_barrier
	s_setprio 1
	s_waitcnt lgkmcnt(0)
	v_mfma_f32_16x16x32_bf16 v[44:47], v[148:151], v[190:193], v[44:47]
	v_mfma_f32_16x16x32_bf16 v[44:47], v[152:155], v[194:197], v[44:47]
	v_mfma_f32_16x16x32_bf16 v[36:39], v[156:159], v[190:193], v[36:39]
	v_mfma_f32_16x16x32_bf16 v[36:39], v[160:163], v[194:197], v[36:39]
	v_mfma_f32_16x16x32_bf16 v[28:31], v[148:151], v[198:201], v[28:31]
	v_mfma_f32_16x16x32_bf16 v[28:31], v[152:155], v[202:205], v[28:31]
	v_mfma_f32_16x16x32_bf16 v[20:23], v[156:159], v[198:201], v[20:23]
	v_mfma_f32_16x16x32_bf16 v[20:23], v[160:163], v[202:205], v[20:23]
	v_mfma_f32_16x16x32_bf16 v[12:15], v[148:151], v[206:209], v[12:15]
	v_mfma_f32_16x16x32_bf16 v[12:15], v[152:155], v[210:213], v[12:15]
	v_mfma_f32_16x16x32_bf16 v[4:7], v[156:159], v[206:209], v[4:7]
	v_mfma_f32_16x16x32_bf16 v[4:7], v[160:163], v[210:213], v[4:7]
	s_setprio 0
	s_setprio 1
	v_mfma_f32_16x16x32_bf16 v[56:59], v[164:167], v[182:185], v[56:59]
	v_mfma_f32_16x16x32_bf16 v[56:59], v[170:173], v[186:189], v[56:59]
	v_mfma_f32_16x16x32_bf16 v[48:51], v[174:177], v[182:185], v[48:51]
	v_mfma_f32_16x16x32_bf16 v[48:51], v[178:181], v[186:189], v[48:51]
	v_mfma_f32_16x16x32_bf16 v[40:43], v[164:167], v[190:193], v[40:43]
	v_mfma_f32_16x16x32_bf16 v[40:43], v[170:173], v[194:197], v[40:43]
	v_mfma_f32_16x16x32_bf16 v[32:35], v[174:177], v[190:193], v[32:35]
	v_mfma_f32_16x16x32_bf16 v[32:35], v[178:181], v[194:197], v[32:35]
	v_mfma_f32_16x16x32_bf16 v[24:27], v[164:167], v[198:201], v[24:27]
	v_mfma_f32_16x16x32_bf16 v[24:27], v[170:173], v[202:205], v[24:27]
	v_mfma_f32_16x16x32_bf16 v[16:19], v[174:177], v[198:201], v[16:19]
	v_mfma_f32_16x16x32_bf16 v[16:19], v[178:181], v[202:205], v[16:19]
	v_mfma_f32_16x16x32_bf16 v[8:11], v[164:167], v[206:209], v[8:11]
	v_mfma_f32_16x16x32_bf16 v[8:11], v[170:173], v[210:213], v[8:11]
	v_mfma_f32_16x16x32_bf16 v[0:3], v[174:177], v[206:209], v[0:3]
	v_mfma_f32_16x16x32_bf16 v[0:3], v[178:181], v[210:213], v[0:3]
	s_setprio 0
	s_barrier
	s_add_u32 s30, s30, 0x100
	s_addc_u32 s31, s31, 0
	s_add_u32 s28, s28, 0x100
	s_addc_u32 s52, s52, 0
	s_cmp_ge_i32 s53, s29
	s_mov_b32 s2, s53
	s_cbranch_scc0 .LBB0_1128
